# scan inner loop: next-step LDS reads issued at the top of each step (full-step latency cover), rest as v26
# speedup vs baseline: 1.0076x; 1.0076x over previous
.LBB0_985:
	s_and_saveexec_b64 s[24:25], s[16:17]
	s_cbranch_execz .LBB0_988
	ds_read_b128 v[30:33], v161 offset:8192
	ds_read_b128 v[34:37], v161 offset:16384
	ds_read_b128 v[46:49], v161 offset:24576
	ds_read_b64 v[80:81], v82 offset:40960
	ds_read_b128 v[38:41], v161
	ds_read_b128 v[42:45], v161 offset:32768
	s_waitcnt lgkmcnt(0)
	ds_read_b128 v[84:87], v161 offset:8448
	ds_read_b128 v[88:91], v161 offset:16640
	ds_read_b128 v[100:103], v161 offset:24832
	ds_read_b64 v[104:105], v82 offset:41216
	ds_read_b128 v[92:95], v161 offset:256
	ds_read_b128 v[96:99], v161 offset:33024
	v_pk_mul_f32 v[106:107], v[72:73], v[30:31]
	v_pk_mul_f32 v[108:109], v[76:77], v[30:31]
	v_pk_fma_f32 v[106:107], v[74:75], v[32:33], v[106:107]
	v_pk_fma_f32 v[108:109], v[78:79], v[32:33], v[108:109]
	v_add_f32_e32 v110, v106, v107
	v_add_f32_e32 v112, v108, v109
	s_nop 0
	v_add_f32_dpp v110, v110, v110 quad_perm:[1,0,3,2] row_mask:0xf bank_mask:0xf bound_ctrl:1
	v_add_f32_dpp v112, v112, v112 quad_perm:[1,0,3,2] row_mask:0xf bank_mask:0xf bound_ctrl:1
	s_nop 0
	v_add_f32_dpp v110, v110, v110 quad_perm:[2,3,0,1] row_mask:0xf bank_mask:0xf bound_ctrl:1
	v_add_f32_dpp v112, v112, v112 quad_perm:[2,3,0,1] row_mask:0xf bank_mask:0xf bound_ctrl:1
	s_nop 0
	v_add_f32_dpp v110, v110, v110 row_half_mirror row_mask:0xf bank_mask:0xf bound_ctrl:1
	v_add_f32_dpp v112, v112, v112 row_half_mirror row_mask:0xf bank_mask:0xf bound_ctrl:1
	s_nop 0
	v_add_f32_dpp v110, v110, v110 row_ror:8 row_mask:0xf bank_mask:0xf bound_ctrl:1
	v_add_f32_dpp v112, v112, v112 row_ror:8 row_mask:0xf bank_mask:0xf bound_ctrl:1
	v_pk_mul_f32 v[114:115], v[34:35], v[110:111] op_sel_hi:[1,0]
	v_pk_mul_f32 v[116:117], v[34:35], v[112:113] op_sel_hi:[1,0]
	v_pk_mul_f32 v[118:119], v[36:37], v[110:111] op_sel_hi:[1,0]
	v_pk_mul_f32 v[120:121], v[36:37], v[112:113] op_sel_hi:[1,0]
	v_pk_fma_f32 v[114:115], v[46:47], v[80:81], v[114:115] op_sel_hi:[1,0,1]
	v_pk_fma_f32 v[116:117], v[46:47], v[80:81], v[116:117] op_sel:[0,1,0]
	v_pk_fma_f32 v[118:119], v[48:49], v[80:81], v[118:119] op_sel_hi:[1,0,1]
	v_pk_fma_f32 v[120:121], v[48:49], v[80:81], v[120:121] op_sel:[0,1,0]
	v_pk_fma_f32 v[72:73], v[72:73], v[38:39], v[114:115]
	v_pk_fma_f32 v[76:77], v[76:77], v[38:39], v[116:117]
	v_pk_fma_f32 v[74:75], v[74:75], v[40:41], v[118:119]
	v_pk_fma_f32 v[78:79], v[78:79], v[40:41], v[120:121]
	v_pk_mul_f32 v[122:123], v[72:73], v[42:43]
	v_pk_mul_f32 v[124:125], v[76:77], v[42:43]
	v_pk_fma_f32 v[122:123], v[74:75], v[44:45], v[122:123]
	v_pk_fma_f32 v[124:125], v[78:79], v[44:45], v[124:125]
	v_add_f32_e32 v126, v122, v123
	v_add_f32_e32 v127, v124, v125
	ds_write_b64 v187, v[126:127]
	s_waitcnt lgkmcnt(1)
	ds_read_b128 v[30:33], v161 offset:8704
	ds_read_b128 v[34:37], v161 offset:16896
	ds_read_b128 v[46:49], v161 offset:25088
	ds_read_b64 v[80:81], v82 offset:41472
	ds_read_b128 v[38:41], v161 offset:512
	ds_read_b128 v[42:45], v161 offset:33280
	v_pk_mul_f32 v[106:107], v[72:73], v[84:85]
	v_pk_mul_f32 v[108:109], v[76:77], v[84:85]
	v_pk_fma_f32 v[106:107], v[74:75], v[86:87], v[106:107]
	v_pk_fma_f32 v[108:109], v[78:79], v[86:87], v[108:109]
	v_add_f32_e32 v110, v106, v107
	v_add_f32_e32 v112, v108, v109
	s_nop 0
	v_add_f32_dpp v110, v110, v110 quad_perm:[1,0,3,2] row_mask:0xf bank_mask:0xf bound_ctrl:1
	v_add_f32_dpp v112, v112, v112 quad_perm:[1,0,3,2] row_mask:0xf bank_mask:0xf bound_ctrl:1
	s_nop 0
	v_add_f32_dpp v110, v110, v110 quad_perm:[2,3,0,1] row_mask:0xf bank_mask:0xf bound_ctrl:1
	v_add_f32_dpp v112, v112, v112 quad_perm:[2,3,0,1] row_mask:0xf bank_mask:0xf bound_ctrl:1
	s_nop 0
	v_add_f32_dpp v110, v110, v110 row_half_mirror row_mask:0xf bank_mask:0xf bound_ctrl:1
	v_add_f32_dpp v112, v112, v112 row_half_mirror row_mask:0xf bank_mask:0xf bound_ctrl:1
	s_nop 0
	v_add_f32_dpp v110, v110, v110 row_ror:8 row_mask:0xf bank_mask:0xf bound_ctrl:1
	v_add_f32_dpp v112, v112, v112 row_ror:8 row_mask:0xf bank_mask:0xf bound_ctrl:1
	v_pk_mul_f32 v[114:115], v[88:89], v[110:111] op_sel_hi:[1,0]
	v_pk_mul_f32 v[116:117], v[88:89], v[112:113] op_sel_hi:[1,0]
	v_pk_mul_f32 v[118:119], v[90:91], v[110:111] op_sel_hi:[1,0]
	v_pk_mul_f32 v[120:121], v[90:91], v[112:113] op_sel_hi:[1,0]
	v_pk_fma_f32 v[114:115], v[100:101], v[104:105], v[114:115] op_sel_hi:[1,0,1]
	v_pk_fma_f32 v[116:117], v[100:101], v[104:105], v[116:117] op_sel:[0,1,0]
	v_pk_fma_f32 v[118:119], v[102:103], v[104:105], v[118:119] op_sel_hi:[1,0,1]
	v_pk_fma_f32 v[120:121], v[102:103], v[104:105], v[120:121] op_sel:[0,1,0]
	v_pk_fma_f32 v[72:73], v[72:73], v[92:93], v[114:115]
	v_pk_fma_f32 v[76:77], v[76:77], v[92:93], v[116:117]
	v_pk_fma_f32 v[74:75], v[74:75], v[94:95], v[118:119]
	v_pk_fma_f32 v[78:79], v[78:79], v[94:95], v[120:121]
	v_pk_mul_f32 v[122:123], v[72:73], v[96:97]
	v_pk_mul_f32 v[124:125], v[76:77], v[96:97]
	v_pk_fma_f32 v[122:123], v[74:75], v[98:99], v[122:123]
	v_pk_fma_f32 v[124:125], v[78:79], v[98:99], v[124:125]
	v_add_f32_e32 v126, v122, v123
	v_add_f32_e32 v127, v124, v125
	ds_write_b64 v187, v[126:127] offset:2048
	s_waitcnt lgkmcnt(1)
	ds_read_b128 v[84:87], v161 offset:8960
	ds_read_b128 v[88:91], v161 offset:17152
	ds_read_b128 v[100:103], v161 offset:25344
	ds_read_b64 v[104:105], v82 offset:41728
	ds_read_b128 v[92:95], v161 offset:768
	ds_read_b128 v[96:99], v161 offset:33536
	v_pk_mul_f32 v[106:107], v[72:73], v[30:31]
	v_pk_mul_f32 v[108:109], v[76:77], v[30:31]
	v_pk_fma_f32 v[106:107], v[74:75], v[32:33], v[106:107]
	v_pk_fma_f32 v[108:109], v[78:79], v[32:33], v[108:109]
	v_add_f32_e32 v110, v106, v107
	v_add_f32_e32 v112, v108, v109
	s_nop 0
	v_add_f32_dpp v110, v110, v110 quad_perm:[1,0,3,2] row_mask:0xf bank_mask:0xf bound_ctrl:1
	v_add_f32_dpp v112, v112, v112 quad_perm:[1,0,3,2] row_mask:0xf bank_mask:0xf bound_ctrl:1
	s_nop 0
	v_add_f32_dpp v110, v110, v110 quad_perm:[2,3,0,1] row_mask:0xf bank_mask:0xf bound_ctrl:1
	v_add_f32_dpp v112, v112, v112 quad_perm:[2,3,0,1] row_mask:0xf bank_mask:0xf bound_ctrl:1
	s_nop 0
	v_add_f32_dpp v110, v110, v110 row_half_mirror row_mask:0xf bank_mask:0xf bound_ctrl:1
	v_add_f32_dpp v112, v112, v112 row_half_mirror row_mask:0xf bank_mask:0xf bound_ctrl:1
	s_nop 0
	v_add_f32_dpp v110, v110, v110 row_ror:8 row_mask:0xf bank_mask:0xf bound_ctrl:1
	v_add_f32_dpp v112, v112, v112 row_ror:8 row_mask:0xf bank_mask:0xf bound_ctrl:1
	v_pk_mul_f32 v[114:115], v[34:35], v[110:111] op_sel_hi:[1,0]
	v_pk_mul_f32 v[116:117], v[34:35], v[112:113] op_sel_hi:[1,0]
	v_pk_mul_f32 v[118:119], v[36:37], v[110:111] op_sel_hi:[1,0]
	v_pk_mul_f32 v[120:121], v[36:37], v[112:113] op_sel_hi:[1,0]
	v_pk_fma_f32 v[114:115], v[46:47], v[80:81], v[114:115] op_sel_hi:[1,0,1]
	v_pk_fma_f32 v[116:117], v[46:47], v[80:81], v[116:117] op_sel:[0,1,0]
	v_pk_fma_f32 v[118:119], v[48:49], v[80:81], v[118:119] op_sel_hi:[1,0,1]
	v_pk_fma_f32 v[120:121], v[48:49], v[80:81], v[120:121] op_sel:[0,1,0]
	v_pk_fma_f32 v[72:73], v[72:73], v[38:39], v[114:115]
	v_pk_fma_f32 v[76:77], v[76:77], v[38:39], v[116:117]
	v_pk_fma_f32 v[74:75], v[74:75], v[40:41], v[118:119]
	v_pk_fma_f32 v[78:79], v[78:79], v[40:41], v[120:121]
	v_pk_mul_f32 v[122:123], v[72:73], v[42:43]
	v_pk_mul_f32 v[124:125], v[76:77], v[42:43]
	v_pk_fma_f32 v[122:123], v[74:75], v[44:45], v[122:123]
	v_pk_fma_f32 v[124:125], v[78:79], v[44:45], v[124:125]
	v_add_f32_e32 v126, v122, v123
	v_add_f32_e32 v127, v124, v125
	ds_write_b64 v187, v[126:127] offset:4096
	s_waitcnt lgkmcnt(1)
	ds_read_b128 v[30:33], v161 offset:9216
	ds_read_b128 v[34:37], v161 offset:17408
	ds_read_b128 v[46:49], v161 offset:25600
	ds_read_b64 v[80:81], v82 offset:41984
	ds_read_b128 v[38:41], v161 offset:1024
	ds_read_b128 v[42:45], v161 offset:33792
	v_pk_mul_f32 v[106:107], v[72:73], v[84:85]
	v_pk_mul_f32 v[108:109], v[76:77], v[84:85]
	v_pk_fma_f32 v[106:107], v[74:75], v[86:87], v[106:107]
	v_pk_fma_f32 v[108:109], v[78:79], v[86:87], v[108:109]
	v_add_f32_e32 v110, v106, v107
	v_add_f32_e32 v112, v108, v109
	s_nop 0
	v_add_f32_dpp v110, v110, v110 quad_perm:[1,0,3,2] row_mask:0xf bank_mask:0xf bound_ctrl:1
	v_add_f32_dpp v112, v112, v112 quad_perm:[1,0,3,2] row_mask:0xf bank_mask:0xf bound_ctrl:1
	s_nop 0
	v_add_f32_dpp v110, v110, v110 quad_perm:[2,3,0,1] row_mask:0xf bank_mask:0xf bound_ctrl:1
	v_add_f32_dpp v112, v112, v112 quad_perm:[2,3,0,1] row_mask:0xf bank_mask:0xf bound_ctrl:1
	s_nop 0
	v_add_f32_dpp v110, v110, v110 row_half_mirror row_mask:0xf bank_mask:0xf bound_ctrl:1
	v_add_f32_dpp v112, v112, v112 row_half_mirror row_mask:0xf bank_mask:0xf bound_ctrl:1
	s_nop 0
	v_add_f32_dpp v110, v110, v110 row_ror:8 row_mask:0xf bank_mask:0xf bound_ctrl:1
	v_add_f32_dpp v112, v112, v112 row_ror:8 row_mask:0xf bank_mask:0xf bound_ctrl:1
	v_pk_mul_f32 v[114:115], v[88:89], v[110:111] op_sel_hi:[1,0]
	v_pk_mul_f32 v[116:117], v[88:89], v[112:113] op_sel_hi:[1,0]
	v_pk_mul_f32 v[118:119], v[90:91], v[110:111] op_sel_hi:[1,0]
	v_pk_mul_f32 v[120:121], v[90:91], v[112:113] op_sel_hi:[1,0]
	v_pk_fma_f32 v[114:115], v[100:101], v[104:105], v[114:115] op_sel_hi:[1,0,1]
	v_pk_fma_f32 v[116:117], v[100:101], v[104:105], v[116:117] op_sel:[0,1,0]
	v_pk_fma_f32 v[118:119], v[102:103], v[104:105], v[118:119] op_sel_hi:[1,0,1]
	v_pk_fma_f32 v[120:121], v[102:103], v[104:105], v[120:121] op_sel:[0,1,0]
	v_pk_fma_f32 v[72:73], v[72:73], v[92:93], v[114:115]
	v_pk_fma_f32 v[76:77], v[76:77], v[92:93], v[116:117]
	v_pk_fma_f32 v[74:75], v[74:75], v[94:95], v[118:119]
	v_pk_fma_f32 v[78:79], v[78:79], v[94:95], v[120:121]
	v_pk_mul_f32 v[122:123], v[72:73], v[96:97]
	v_pk_mul_f32 v[124:125], v[76:77], v[96:97]
	v_pk_fma_f32 v[122:123], v[74:75], v[98:99], v[122:123]
	v_pk_fma_f32 v[124:125], v[78:79], v[98:99], v[124:125]
	v_add_f32_e32 v126, v122, v123
	v_add_f32_e32 v127, v124, v125
	ds_write_b64 v187, v[126:127] offset:6144
	s_waitcnt lgkmcnt(1)
	ds_read_b128 v[84:87], v161 offset:9472
	ds_read_b128 v[88:91], v161 offset:17664
	ds_read_b128 v[100:103], v161 offset:25856
	ds_read_b64 v[104:105], v82 offset:42240
	ds_read_b128 v[92:95], v161 offset:1280
	ds_read_b128 v[96:99], v161 offset:34048
	v_pk_mul_f32 v[106:107], v[72:73], v[30:31]
	v_pk_mul_f32 v[108:109], v[76:77], v[30:31]
	v_pk_fma_f32 v[106:107], v[74:75], v[32:33], v[106:107]
	v_pk_fma_f32 v[108:109], v[78:79], v[32:33], v[108:109]
	v_add_f32_e32 v110, v106, v107
	v_add_f32_e32 v112, v108, v109
	s_nop 0
	v_add_f32_dpp v110, v110, v110 quad_perm:[1,0,3,2] row_mask:0xf bank_mask:0xf bound_ctrl:1
	v_add_f32_dpp v112, v112, v112 quad_perm:[1,0,3,2] row_mask:0xf bank_mask:0xf bound_ctrl:1
	s_nop 0
	v_add_f32_dpp v110, v110, v110 quad_perm:[2,3,0,1] row_mask:0xf bank_mask:0xf bound_ctrl:1
	v_add_f32_dpp v112, v112, v112 quad_perm:[2,3,0,1] row_mask:0xf bank_mask:0xf bound_ctrl:1
	s_nop 0
	v_add_f32_dpp v110, v110, v110 row_half_mirror row_mask:0xf bank_mask:0xf bound_ctrl:1
	v_add_f32_dpp v112, v112, v112 row_half_mirror row_mask:0xf bank_mask:0xf bound_ctrl:1
	s_nop 0
	v_add_f32_dpp v110, v110, v110 row_ror:8 row_mask:0xf bank_mask:0xf bound_ctrl:1
	v_add_f32_dpp v112, v112, v112 row_ror:8 row_mask:0xf bank_mask:0xf bound_ctrl:1
	v_pk_mul_f32 v[114:115], v[34:35], v[110:111] op_sel_hi:[1,0]
	v_pk_mul_f32 v[116:117], v[34:35], v[112:113] op_sel_hi:[1,0]
	v_pk_mul_f32 v[118:119], v[36:37], v[110:111] op_sel_hi:[1,0]
	v_pk_mul_f32 v[120:121], v[36:37], v[112:113] op_sel_hi:[1,0]
	v_pk_fma_f32 v[114:115], v[46:47], v[80:81], v[114:115] op_sel_hi:[1,0,1]
	v_pk_fma_f32 v[116:117], v[46:47], v[80:81], v[116:117] op_sel:[0,1,0]
	v_pk_fma_f32 v[118:119], v[48:49], v[80:81], v[118:119] op_sel_hi:[1,0,1]
	v_pk_fma_f32 v[120:121], v[48:49], v[80:81], v[120:121] op_sel:[0,1,0]
	v_pk_fma_f32 v[72:73], v[72:73], v[38:39], v[114:115]
	v_pk_fma_f32 v[76:77], v[76:77], v[38:39], v[116:117]
	v_pk_fma_f32 v[74:75], v[74:75], v[40:41], v[118:119]
	v_pk_fma_f32 v[78:79], v[78:79], v[40:41], v[120:121]
	v_pk_mul_f32 v[122:123], v[72:73], v[42:43]
	v_pk_mul_f32 v[124:125], v[76:77], v[42:43]
	v_pk_fma_f32 v[122:123], v[74:75], v[44:45], v[122:123]
	v_pk_fma_f32 v[124:125], v[78:79], v[44:45], v[124:125]
	v_add_f32_e32 v126, v122, v123
	v_add_f32_e32 v127, v124, v125
	ds_write_b64 v187, v[126:127] offset:8192
	s_waitcnt lgkmcnt(1)
	ds_read_b128 v[30:33], v161 offset:9728
	ds_read_b128 v[34:37], v161 offset:17920
	ds_read_b128 v[46:49], v161 offset:26112
	ds_read_b64 v[80:81], v82 offset:42496
	ds_read_b128 v[38:41], v161 offset:1536
	ds_read_b128 v[42:45], v161 offset:34304
	v_pk_mul_f32 v[106:107], v[72:73], v[84:85]
	v_pk_mul_f32 v[108:109], v[76:77], v[84:85]
	v_pk_fma_f32 v[106:107], v[74:75], v[86:87], v[106:107]
	v_pk_fma_f32 v[108:109], v[78:79], v[86:87], v[108:109]
	v_add_f32_e32 v110, v106, v107
	v_add_f32_e32 v112, v108, v109
	s_nop 0
	v_add_f32_dpp v110, v110, v110 quad_perm:[1,0,3,2] row_mask:0xf bank_mask:0xf bound_ctrl:1
	v_add_f32_dpp v112, v112, v112 quad_perm:[1,0,3,2] row_mask:0xf bank_mask:0xf bound_ctrl:1
	s_nop 0
	v_add_f32_dpp v110, v110, v110 quad_perm:[2,3,0,1] row_mask:0xf bank_mask:0xf bound_ctrl:1
	v_add_f32_dpp v112, v112, v112 quad_perm:[2,3,0,1] row_mask:0xf bank_mask:0xf bound_ctrl:1
	s_nop 0
	v_add_f32_dpp v110, v110, v110 row_half_mirror row_mask:0xf bank_mask:0xf bound_ctrl:1
	v_add_f32_dpp v112, v112, v112 row_half_mirror row_mask:0xf bank_mask:0xf bound_ctrl:1
	s_nop 0
	v_add_f32_dpp v110, v110, v110 row_ror:8 row_mask:0xf bank_mask:0xf bound_ctrl:1
	v_add_f32_dpp v112, v112, v112 row_ror:8 row_mask:0xf bank_mask:0xf bound_ctrl:1
	v_pk_mul_f32 v[114:115], v[88:89], v[110:111] op_sel_hi:[1,0]
	v_pk_mul_f32 v[116:117], v[88:89], v[112:113] op_sel_hi:[1,0]
	v_pk_mul_f32 v[118:119], v[90:91], v[110:111] op_sel_hi:[1,0]
	v_pk_mul_f32 v[120:121], v[90:91], v[112:113] op_sel_hi:[1,0]
	v_pk_fma_f32 v[114:115], v[100:101], v[104:105], v[114:115] op_sel_hi:[1,0,1]
	v_pk_fma_f32 v[116:117], v[100:101], v[104:105], v[116:117] op_sel:[0,1,0]
	v_pk_fma_f32 v[118:119], v[102:103], v[104:105], v[118:119] op_sel_hi:[1,0,1]
	v_pk_fma_f32 v[120:121], v[102:103], v[104:105], v[120:121] op_sel:[0,1,0]
	v_pk_fma_f32 v[72:73], v[72:73], v[92:93], v[114:115]
	v_pk_fma_f32 v[76:77], v[76:77], v[92:93], v[116:117]
	v_pk_fma_f32 v[74:75], v[74:75], v[94:95], v[118:119]
	v_pk_fma_f32 v[78:79], v[78:79], v[94:95], v[120:121]
	v_pk_mul_f32 v[122:123], v[72:73], v[96:97]
	v_pk_mul_f32 v[124:125], v[76:77], v[96:97]
	v_pk_fma_f32 v[122:123], v[74:75], v[98:99], v[122:123]
	v_pk_fma_f32 v[124:125], v[78:79], v[98:99], v[124:125]
	v_add_f32_e32 v126, v122, v123
	v_add_f32_e32 v127, v124, v125
	ds_write_b64 v187, v[126:127] offset:10240
	s_waitcnt lgkmcnt(1)
	ds_read_b128 v[84:87], v161 offset:9984
	ds_read_b128 v[88:91], v161 offset:18176
	ds_read_b128 v[100:103], v161 offset:26368
	ds_read_b64 v[104:105], v82 offset:42752
	ds_read_b128 v[92:95], v161 offset:1792
	ds_read_b128 v[96:99], v161 offset:34560
	v_pk_mul_f32 v[106:107], v[72:73], v[30:31]
	v_pk_mul_f32 v[108:109], v[76:77], v[30:31]
	v_pk_fma_f32 v[106:107], v[74:75], v[32:33], v[106:107]
	v_pk_fma_f32 v[108:109], v[78:79], v[32:33], v[108:109]
	v_add_f32_e32 v110, v106, v107
	v_add_f32_e32 v112, v108, v109
	s_nop 0
	v_add_f32_dpp v110, v110, v110 quad_perm:[1,0,3,2] row_mask:0xf bank_mask:0xf bound_ctrl:1
	v_add_f32_dpp v112, v112, v112 quad_perm:[1,0,3,2] row_mask:0xf bank_mask:0xf bound_ctrl:1
	s_nop 0
	v_add_f32_dpp v110, v110, v110 quad_perm:[2,3,0,1] row_mask:0xf bank_mask:0xf bound_ctrl:1
	v_add_f32_dpp v112, v112, v112 quad_perm:[2,3,0,1] row_mask:0xf bank_mask:0xf bound_ctrl:1
	s_nop 0
	v_add_f32_dpp v110, v110, v110 row_half_mirror row_mask:0xf bank_mask:0xf bound_ctrl:1
	v_add_f32_dpp v112, v112, v112 row_half_mirror row_mask:0xf bank_mask:0xf bound_ctrl:1
	s_nop 0
	v_add_f32_dpp v110, v110, v110 row_ror:8 row_mask:0xf bank_mask:0xf bound_ctrl:1
	v_add_f32_dpp v112, v112, v112 row_ror:8 row_mask:0xf bank_mask:0xf bound_ctrl:1
	v_pk_mul_f32 v[114:115], v[34:35], v[110:111] op_sel_hi:[1,0]
	v_pk_mul_f32 v[116:117], v[34:35], v[112:113] op_sel_hi:[1,0]
	v_pk_mul_f32 v[118:119], v[36:37], v[110:111] op_sel_hi:[1,0]
	v_pk_mul_f32 v[120:121], v[36:37], v[112:113] op_sel_hi:[1,0]
	v_pk_fma_f32 v[114:115], v[46:47], v[80:81], v[114:115] op_sel_hi:[1,0,1]
	v_pk_fma_f32 v[116:117], v[46:47], v[80:81], v[116:117] op_sel:[0,1,0]
	v_pk_fma_f32 v[118:119], v[48:49], v[80:81], v[118:119] op_sel_hi:[1,0,1]
	v_pk_fma_f32 v[120:121], v[48:49], v[80:81], v[120:121] op_sel:[0,1,0]
	v_pk_fma_f32 v[72:73], v[72:73], v[38:39], v[114:115]
	v_pk_fma_f32 v[76:77], v[76:77], v[38:39], v[116:117]
	v_pk_fma_f32 v[74:75], v[74:75], v[40:41], v[118:119]
	v_pk_fma_f32 v[78:79], v[78:79], v[40:41], v[120:121]
	v_pk_mul_f32 v[122:123], v[72:73], v[42:43]
	v_pk_mul_f32 v[124:125], v[76:77], v[42:43]
	v_pk_fma_f32 v[122:123], v[74:75], v[44:45], v[122:123]
	v_pk_fma_f32 v[124:125], v[78:79], v[44:45], v[124:125]
	v_add_f32_e32 v126, v122, v123
	v_add_f32_e32 v127, v124, v125
	ds_write_b64 v187, v[126:127] offset:12288
	s_waitcnt lgkmcnt(1)
	ds_read_b128 v[30:33], v161 offset:10240
	ds_read_b128 v[34:37], v161 offset:18432
	ds_read_b128 v[46:49], v161 offset:26624
	ds_read_b64 v[80:81], v82 offset:43008
	ds_read_b128 v[38:41], v161 offset:2048
	ds_read_b128 v[42:45], v161 offset:34816
	v_pk_mul_f32 v[106:107], v[72:73], v[84:85]
	v_pk_mul_f32 v[108:109], v[76:77], v[84:85]
	v_pk_fma_f32 v[106:107], v[74:75], v[86:87], v[106:107]
	v_pk_fma_f32 v[108:109], v[78:79], v[86:87], v[108:109]
	v_add_f32_e32 v110, v106, v107
	v_add_f32_e32 v112, v108, v109
	s_nop 0
	v_add_f32_dpp v110, v110, v110 quad_perm:[1,0,3,2] row_mask:0xf bank_mask:0xf bound_ctrl:1
	v_add_f32_dpp v112, v112, v112 quad_perm:[1,0,3,2] row_mask:0xf bank_mask:0xf bound_ctrl:1
	s_nop 0
	v_add_f32_dpp v110, v110, v110 quad_perm:[2,3,0,1] row_mask:0xf bank_mask:0xf bound_ctrl:1
	v_add_f32_dpp v112, v112, v112 quad_perm:[2,3,0,1] row_mask:0xf bank_mask:0xf bound_ctrl:1
	s_nop 0
	v_add_f32_dpp v110, v110, v110 row_half_mirror row_mask:0xf bank_mask:0xf bound_ctrl:1
	v_add_f32_dpp v112, v112, v112 row_half_mirror row_mask:0xf bank_mask:0xf bound_ctrl:1
	s_nop 0
	v_add_f32_dpp v110, v110, v110 row_ror:8 row_mask:0xf bank_mask:0xf bound_ctrl:1
	v_add_f32_dpp v112, v112, v112 row_ror:8 row_mask:0xf bank_mask:0xf bound_ctrl:1
	v_pk_mul_f32 v[114:115], v[88:89], v[110:111] op_sel_hi:[1,0]
	v_pk_mul_f32 v[116:117], v[88:89], v[112:113] op_sel_hi:[1,0]
	v_pk_mul_f32 v[118:119], v[90:91], v[110:111] op_sel_hi:[1,0]
	v_pk_mul_f32 v[120:121], v[90:91], v[112:113] op_sel_hi:[1,0]
	v_pk_fma_f32 v[114:115], v[100:101], v[104:105], v[114:115] op_sel_hi:[1,0,1]
	v_pk_fma_f32 v[116:117], v[100:101], v[104:105], v[116:117] op_sel:[0,1,0]
	v_pk_fma_f32 v[118:119], v[102:103], v[104:105], v[118:119] op_sel_hi:[1,0,1]
	v_pk_fma_f32 v[120:121], v[102:103], v[104:105], v[120:121] op_sel:[0,1,0]
	v_pk_fma_f32 v[72:73], v[72:73], v[92:93], v[114:115]
	v_pk_fma_f32 v[76:77], v[76:77], v[92:93], v[116:117]
	v_pk_fma_f32 v[74:75], v[74:75], v[94:95], v[118:119]
	v_pk_fma_f32 v[78:79], v[78:79], v[94:95], v[120:121]
	v_pk_mul_f32 v[122:123], v[72:73], v[96:97]
	v_pk_mul_f32 v[124:125], v[76:77], v[96:97]
	v_pk_fma_f32 v[122:123], v[74:75], v[98:99], v[122:123]
	v_pk_fma_f32 v[124:125], v[78:79], v[98:99], v[124:125]
	v_add_f32_e32 v126, v122, v123
	v_add_f32_e32 v127, v124, v125
	ds_write_b64 v187, v[126:127] offset:14336
	s_waitcnt lgkmcnt(1)
	ds_read_b128 v[84:87], v161 offset:10496
	ds_read_b128 v[88:91], v161 offset:18688
	ds_read_b128 v[100:103], v161 offset:26880
	ds_read_b64 v[104:105], v82 offset:43264
	ds_read_b128 v[92:95], v161 offset:2304
	ds_read_b128 v[96:99], v161 offset:35072
	v_pk_mul_f32 v[106:107], v[72:73], v[30:31]
	v_pk_mul_f32 v[108:109], v[76:77], v[30:31]
	v_pk_fma_f32 v[106:107], v[74:75], v[32:33], v[106:107]
	v_pk_fma_f32 v[108:109], v[78:79], v[32:33], v[108:109]
	v_add_f32_e32 v110, v106, v107
	v_add_f32_e32 v112, v108, v109
	s_nop 0
	v_add_f32_dpp v110, v110, v110 quad_perm:[1,0,3,2] row_mask:0xf bank_mask:0xf bound_ctrl:1
	v_add_f32_dpp v112, v112, v112 quad_perm:[1,0,3,2] row_mask:0xf bank_mask:0xf bound_ctrl:1
	s_nop 0
	v_add_f32_dpp v110, v110, v110 quad_perm:[2,3,0,1] row_mask:0xf bank_mask:0xf bound_ctrl:1
	v_add_f32_dpp v112, v112, v112 quad_perm:[2,3,0,1] row_mask:0xf bank_mask:0xf bound_ctrl:1
	s_nop 0
	v_add_f32_dpp v110, v110, v110 row_half_mirror row_mask:0xf bank_mask:0xf bound_ctrl:1
	v_add_f32_dpp v112, v112, v112 row_half_mirror row_mask:0xf bank_mask:0xf bound_ctrl:1
	s_nop 0
	v_add_f32_dpp v110, v110, v110 row_ror:8 row_mask:0xf bank_mask:0xf bound_ctrl:1
	v_add_f32_dpp v112, v112, v112 row_ror:8 row_mask:0xf bank_mask:0xf bound_ctrl:1
	v_pk_mul_f32 v[114:115], v[34:35], v[110:111] op_sel_hi:[1,0]
	v_pk_mul_f32 v[116:117], v[34:35], v[112:113] op_sel_hi:[1,0]
	v_pk_mul_f32 v[118:119], v[36:37], v[110:111] op_sel_hi:[1,0]
	v_pk_mul_f32 v[120:121], v[36:37], v[112:113] op_sel_hi:[1,0]
	v_pk_fma_f32 v[114:115], v[46:47], v[80:81], v[114:115] op_sel_hi:[1,0,1]
	v_pk_fma_f32 v[116:117], v[46:47], v[80:81], v[116:117] op_sel:[0,1,0]
	v_pk_fma_f32 v[118:119], v[48:49], v[80:81], v[118:119] op_sel_hi:[1,0,1]
	v_pk_fma_f32 v[120:121], v[48:49], v[80:81], v[120:121] op_sel:[0,1,0]
	v_pk_fma_f32 v[72:73], v[72:73], v[38:39], v[114:115]
	v_pk_fma_f32 v[76:77], v[76:77], v[38:39], v[116:117]
	v_pk_fma_f32 v[74:75], v[74:75], v[40:41], v[118:119]
	v_pk_fma_f32 v[78:79], v[78:79], v[40:41], v[120:121]
	v_pk_mul_f32 v[122:123], v[72:73], v[42:43]
	v_pk_mul_f32 v[124:125], v[76:77], v[42:43]
	v_pk_fma_f32 v[122:123], v[74:75], v[44:45], v[122:123]
	v_pk_fma_f32 v[124:125], v[78:79], v[44:45], v[124:125]
	v_add_f32_e32 v126, v122, v123
	v_add_f32_e32 v127, v124, v125
	ds_write_b64 v187, v[126:127] offset:16384
	s_waitcnt lgkmcnt(1)
	ds_read_b128 v[30:33], v161 offset:10752
	ds_read_b128 v[34:37], v161 offset:18944
	ds_read_b128 v[46:49], v161 offset:27136
	ds_read_b64 v[80:81], v82 offset:43520
	ds_read_b128 v[38:41], v161 offset:2560
	ds_read_b128 v[42:45], v161 offset:35328
	v_pk_mul_f32 v[106:107], v[72:73], v[84:85]
	v_pk_mul_f32 v[108:109], v[76:77], v[84:85]
	v_pk_fma_f32 v[106:107], v[74:75], v[86:87], v[106:107]
	v_pk_fma_f32 v[108:109], v[78:79], v[86:87], v[108:109]
	v_add_f32_e32 v110, v106, v107
	v_add_f32_e32 v112, v108, v109
	s_nop 0
	v_add_f32_dpp v110, v110, v110 quad_perm:[1,0,3,2] row_mask:0xf bank_mask:0xf bound_ctrl:1
	v_add_f32_dpp v112, v112, v112 quad_perm:[1,0,3,2] row_mask:0xf bank_mask:0xf bound_ctrl:1
	s_nop 0
	v_add_f32_dpp v110, v110, v110 quad_perm:[2,3,0,1] row_mask:0xf bank_mask:0xf bound_ctrl:1
	v_add_f32_dpp v112, v112, v112 quad_perm:[2,3,0,1] row_mask:0xf bank_mask:0xf bound_ctrl:1
	s_nop 0
	v_add_f32_dpp v110, v110, v110 row_half_mirror row_mask:0xf bank_mask:0xf bound_ctrl:1
	v_add_f32_dpp v112, v112, v112 row_half_mirror row_mask:0xf bank_mask:0xf bound_ctrl:1
	s_nop 0
	v_add_f32_dpp v110, v110, v110 row_ror:8 row_mask:0xf bank_mask:0xf bound_ctrl:1
	v_add_f32_dpp v112, v112, v112 row_ror:8 row_mask:0xf bank_mask:0xf bound_ctrl:1
	v_pk_mul_f32 v[114:115], v[88:89], v[110:111] op_sel_hi:[1,0]
	v_pk_mul_f32 v[116:117], v[88:89], v[112:113] op_sel_hi:[1,0]
	v_pk_mul_f32 v[118:119], v[90:91], v[110:111] op_sel_hi:[1,0]
	v_pk_mul_f32 v[120:121], v[90:91], v[112:113] op_sel_hi:[1,0]
	v_pk_fma_f32 v[114:115], v[100:101], v[104:105], v[114:115] op_sel_hi:[1,0,1]
	v_pk_fma_f32 v[116:117], v[100:101], v[104:105], v[116:117] op_sel:[0,1,0]
	v_pk_fma_f32 v[118:119], v[102:103], v[104:105], v[118:119] op_sel_hi:[1,0,1]
	v_pk_fma_f32 v[120:121], v[102:103], v[104:105], v[120:121] op_sel:[0,1,0]
	v_pk_fma_f32 v[72:73], v[72:73], v[92:93], v[114:115]
	v_pk_fma_f32 v[76:77], v[76:77], v[92:93], v[116:117]
	v_pk_fma_f32 v[74:75], v[74:75], v[94:95], v[118:119]
	v_pk_fma_f32 v[78:79], v[78:79], v[94:95], v[120:121]
	v_pk_mul_f32 v[122:123], v[72:73], v[96:97]
	v_pk_mul_f32 v[124:125], v[76:77], v[96:97]
	v_pk_fma_f32 v[122:123], v[74:75], v[98:99], v[122:123]
	v_pk_fma_f32 v[124:125], v[78:79], v[98:99], v[124:125]
	v_add_f32_e32 v126, v122, v123
	v_add_f32_e32 v127, v124, v125
	ds_write_b64 v187, v[126:127] offset:18432
	s_waitcnt lgkmcnt(1)
	ds_read_b128 v[84:87], v161 offset:11008
	ds_read_b128 v[88:91], v161 offset:19200
	ds_read_b128 v[100:103], v161 offset:27392
	ds_read_b64 v[104:105], v82 offset:43776
	ds_read_b128 v[92:95], v161 offset:2816
	ds_read_b128 v[96:99], v161 offset:35584
	v_pk_mul_f32 v[106:107], v[72:73], v[30:31]
	v_pk_mul_f32 v[108:109], v[76:77], v[30:31]
	v_pk_fma_f32 v[106:107], v[74:75], v[32:33], v[106:107]
	v_pk_fma_f32 v[108:109], v[78:79], v[32:33], v[108:109]
	v_add_f32_e32 v110, v106, v107
	v_add_f32_e32 v112, v108, v109
	s_nop 0
	v_add_f32_dpp v110, v110, v110 quad_perm:[1,0,3,2] row_mask:0xf bank_mask:0xf bound_ctrl:1
	v_add_f32_dpp v112, v112, v112 quad_perm:[1,0,3,2] row_mask:0xf bank_mask:0xf bound_ctrl:1
	s_nop 0
	v_add_f32_dpp v110, v110, v110 quad_perm:[2,3,0,1] row_mask:0xf bank_mask:0xf bound_ctrl:1
	v_add_f32_dpp v112, v112, v112 quad_perm:[2,3,0,1] row_mask:0xf bank_mask:0xf bound_ctrl:1
	s_nop 0
	v_add_f32_dpp v110, v110, v110 row_half_mirror row_mask:0xf bank_mask:0xf bound_ctrl:1
	v_add_f32_dpp v112, v112, v112 row_half_mirror row_mask:0xf bank_mask:0xf bound_ctrl:1
	s_nop 0
	v_add_f32_dpp v110, v110, v110 row_ror:8 row_mask:0xf bank_mask:0xf bound_ctrl:1
	v_add_f32_dpp v112, v112, v112 row_ror:8 row_mask:0xf bank_mask:0xf bound_ctrl:1
	v_pk_mul_f32 v[114:115], v[34:35], v[110:111] op_sel_hi:[1,0]
	v_pk_mul_f32 v[116:117], v[34:35], v[112:113] op_sel_hi:[1,0]
	v_pk_mul_f32 v[118:119], v[36:37], v[110:111] op_sel_hi:[1,0]
	v_pk_mul_f32 v[120:121], v[36:37], v[112:113] op_sel_hi:[1,0]
	v_pk_fma_f32 v[114:115], v[46:47], v[80:81], v[114:115] op_sel_hi:[1,0,1]
	v_pk_fma_f32 v[116:117], v[46:47], v[80:81], v[116:117] op_sel:[0,1,0]
	v_pk_fma_f32 v[118:119], v[48:49], v[80:81], v[118:119] op_sel_hi:[1,0,1]
	v_pk_fma_f32 v[120:121], v[48:49], v[80:81], v[120:121] op_sel:[0,1,0]
	v_pk_fma_f32 v[72:73], v[72:73], v[38:39], v[114:115]
	v_pk_fma_f32 v[76:77], v[76:77], v[38:39], v[116:117]
	v_pk_fma_f32 v[74:75], v[74:75], v[40:41], v[118:119]
	v_pk_fma_f32 v[78:79], v[78:79], v[40:41], v[120:121]
	v_pk_mul_f32 v[122:123], v[72:73], v[42:43]
	v_pk_mul_f32 v[124:125], v[76:77], v[42:43]
	v_pk_fma_f32 v[122:123], v[74:75], v[44:45], v[122:123]
	v_pk_fma_f32 v[124:125], v[78:79], v[44:45], v[124:125]
	v_add_f32_e32 v126, v122, v123
	v_add_f32_e32 v127, v124, v125
	ds_write_b64 v187, v[126:127] offset:20480
	s_waitcnt lgkmcnt(1)
	ds_read_b128 v[30:33], v161 offset:11264
	ds_read_b128 v[34:37], v161 offset:19456
	ds_read_b128 v[46:49], v161 offset:27648
	ds_read_b64 v[80:81], v82 offset:44032
	ds_read_b128 v[38:41], v161 offset:3072
	ds_read_b128 v[42:45], v161 offset:35840
	v_pk_mul_f32 v[106:107], v[72:73], v[84:85]
	v_pk_mul_f32 v[108:109], v[76:77], v[84:85]
	v_pk_fma_f32 v[106:107], v[74:75], v[86:87], v[106:107]
	v_pk_fma_f32 v[108:109], v[78:79], v[86:87], v[108:109]
	v_add_f32_e32 v110, v106, v107
	v_add_f32_e32 v112, v108, v109
	s_nop 0
	v_add_f32_dpp v110, v110, v110 quad_perm:[1,0,3,2] row_mask:0xf bank_mask:0xf bound_ctrl:1
	v_add_f32_dpp v112, v112, v112 quad_perm:[1,0,3,2] row_mask:0xf bank_mask:0xf bound_ctrl:1
	s_nop 0
	v_add_f32_dpp v110, v110, v110 quad_perm:[2,3,0,1] row_mask:0xf bank_mask:0xf bound_ctrl:1
	v_add_f32_dpp v112, v112, v112 quad_perm:[2,3,0,1] row_mask:0xf bank_mask:0xf bound_ctrl:1
	s_nop 0
	v_add_f32_dpp v110, v110, v110 row_half_mirror row_mask:0xf bank_mask:0xf bound_ctrl:1
	v_add_f32_dpp v112, v112, v112 row_half_mirror row_mask:0xf bank_mask:0xf bound_ctrl:1
	s_nop 0
	v_add_f32_dpp v110, v110, v110 row_ror:8 row_mask:0xf bank_mask:0xf bound_ctrl:1
	v_add_f32_dpp v112, v112, v112 row_ror:8 row_mask:0xf bank_mask:0xf bound_ctrl:1
	v_pk_mul_f32 v[114:115], v[88:89], v[110:111] op_sel_hi:[1,0]
	v_pk_mul_f32 v[116:117], v[88:89], v[112:113] op_sel_hi:[1,0]
	v_pk_mul_f32 v[118:119], v[90:91], v[110:111] op_sel_hi:[1,0]
	v_pk_mul_f32 v[120:121], v[90:91], v[112:113] op_sel_hi:[1,0]
	v_pk_fma_f32 v[114:115], v[100:101], v[104:105], v[114:115] op_sel_hi:[1,0,1]
	v_pk_fma_f32 v[116:117], v[100:101], v[104:105], v[116:117] op_sel:[0,1,0]
	v_pk_fma_f32 v[118:119], v[102:103], v[104:105], v[118:119] op_sel_hi:[1,0,1]
	v_pk_fma_f32 v[120:121], v[102:103], v[104:105], v[120:121] op_sel:[0,1,0]
	v_pk_fma_f32 v[72:73], v[72:73], v[92:93], v[114:115]
	v_pk_fma_f32 v[76:77], v[76:77], v[92:93], v[116:117]
	v_pk_fma_f32 v[74:75], v[74:75], v[94:95], v[118:119]
	v_pk_fma_f32 v[78:79], v[78:79], v[94:95], v[120:121]
	v_pk_mul_f32 v[122:123], v[72:73], v[96:97]
	v_pk_mul_f32 v[124:125], v[76:77], v[96:97]
	v_pk_fma_f32 v[122:123], v[74:75], v[98:99], v[122:123]
	v_pk_fma_f32 v[124:125], v[78:79], v[98:99], v[124:125]
	v_add_f32_e32 v126, v122, v123
	v_add_f32_e32 v127, v124, v125
	ds_write_b64 v187, v[126:127] offset:22528
	s_waitcnt lgkmcnt(1)
	ds_read_b128 v[84:87], v161 offset:11520
	ds_read_b128 v[88:91], v161 offset:19712
	ds_read_b128 v[100:103], v161 offset:27904
	ds_read_b64 v[104:105], v82 offset:44288
	ds_read_b128 v[92:95], v161 offset:3328
	ds_read_b128 v[96:99], v161 offset:36096
	v_pk_mul_f32 v[106:107], v[72:73], v[30:31]
	v_pk_mul_f32 v[108:109], v[76:77], v[30:31]
	v_pk_fma_f32 v[106:107], v[74:75], v[32:33], v[106:107]
	v_pk_fma_f32 v[108:109], v[78:79], v[32:33], v[108:109]
	v_add_f32_e32 v110, v106, v107
	v_add_f32_e32 v112, v108, v109
	s_nop 0
	v_add_f32_dpp v110, v110, v110 quad_perm:[1,0,3,2] row_mask:0xf bank_mask:0xf bound_ctrl:1
	v_add_f32_dpp v112, v112, v112 quad_perm:[1,0,3,2] row_mask:0xf bank_mask:0xf bound_ctrl:1
	s_nop 0
	v_add_f32_dpp v110, v110, v110 quad_perm:[2,3,0,1] row_mask:0xf bank_mask:0xf bound_ctrl:1
	v_add_f32_dpp v112, v112, v112 quad_perm:[2,3,0,1] row_mask:0xf bank_mask:0xf bound_ctrl:1
	s_nop 0
	v_add_f32_dpp v110, v110, v110 row_half_mirror row_mask:0xf bank_mask:0xf bound_ctrl:1
	v_add_f32_dpp v112, v112, v112 row_half_mirror row_mask:0xf bank_mask:0xf bound_ctrl:1
	s_nop 0
	v_add_f32_dpp v110, v110, v110 row_ror:8 row_mask:0xf bank_mask:0xf bound_ctrl:1
	v_add_f32_dpp v112, v112, v112 row_ror:8 row_mask:0xf bank_mask:0xf bound_ctrl:1
	v_pk_mul_f32 v[114:115], v[34:35], v[110:111] op_sel_hi:[1,0]
	v_pk_mul_f32 v[116:117], v[34:35], v[112:113] op_sel_hi:[1,0]
	v_pk_mul_f32 v[118:119], v[36:37], v[110:111] op_sel_hi:[1,0]
	v_pk_mul_f32 v[120:121], v[36:37], v[112:113] op_sel_hi:[1,0]
	v_pk_fma_f32 v[114:115], v[46:47], v[80:81], v[114:115] op_sel_hi:[1,0,1]
	v_pk_fma_f32 v[116:117], v[46:47], v[80:81], v[116:117] op_sel:[0,1,0]
	v_pk_fma_f32 v[118:119], v[48:49], v[80:81], v[118:119] op_sel_hi:[1,0,1]
	v_pk_fma_f32 v[120:121], v[48:49], v[80:81], v[120:121] op_sel:[0,1,0]
	v_pk_fma_f32 v[72:73], v[72:73], v[38:39], v[114:115]
	v_pk_fma_f32 v[76:77], v[76:77], v[38:39], v[116:117]
	v_pk_fma_f32 v[74:75], v[74:75], v[40:41], v[118:119]
	v_pk_fma_f32 v[78:79], v[78:79], v[40:41], v[120:121]
	v_pk_mul_f32 v[122:123], v[72:73], v[42:43]
	v_pk_mul_f32 v[124:125], v[76:77], v[42:43]
	v_pk_fma_f32 v[122:123], v[74:75], v[44:45], v[122:123]
	v_pk_fma_f32 v[124:125], v[78:79], v[44:45], v[124:125]
	v_add_f32_e32 v126, v122, v123
	v_add_f32_e32 v127, v124, v125
	ds_write_b64 v187, v[126:127] offset:24576
	s_waitcnt lgkmcnt(1)
	ds_read_b128 v[30:33], v161 offset:11776
	ds_read_b128 v[34:37], v161 offset:19968
	ds_read_b128 v[46:49], v161 offset:28160
	ds_read_b64 v[80:81], v82 offset:44544
	ds_read_b128 v[38:41], v161 offset:3584
	ds_read_b128 v[42:45], v161 offset:36352
	v_pk_mul_f32 v[106:107], v[72:73], v[84:85]
	v_pk_mul_f32 v[108:109], v[76:77], v[84:85]
	v_pk_fma_f32 v[106:107], v[74:75], v[86:87], v[106:107]
	v_pk_fma_f32 v[108:109], v[78:79], v[86:87], v[108:109]
	v_add_f32_e32 v110, v106, v107
	v_add_f32_e32 v112, v108, v109
	s_nop 0
	v_add_f32_dpp v110, v110, v110 quad_perm:[1,0,3,2] row_mask:0xf bank_mask:0xf bound_ctrl:1
	v_add_f32_dpp v112, v112, v112 quad_perm:[1,0,3,2] row_mask:0xf bank_mask:0xf bound_ctrl:1
	s_nop 0
	v_add_f32_dpp v110, v110, v110 quad_perm:[2,3,0,1] row_mask:0xf bank_mask:0xf bound_ctrl:1
	v_add_f32_dpp v112, v112, v112 quad_perm:[2,3,0,1] row_mask:0xf bank_mask:0xf bound_ctrl:1
	s_nop 0
	v_add_f32_dpp v110, v110, v110 row_half_mirror row_mask:0xf bank_mask:0xf bound_ctrl:1
	v_add_f32_dpp v112, v112, v112 row_half_mirror row_mask:0xf bank_mask:0xf bound_ctrl:1
	s_nop 0
	v_add_f32_dpp v110, v110, v110 row_ror:8 row_mask:0xf bank_mask:0xf bound_ctrl:1
	v_add_f32_dpp v112, v112, v112 row_ror:8 row_mask:0xf bank_mask:0xf bound_ctrl:1
	v_pk_mul_f32 v[114:115], v[88:89], v[110:111] op_sel_hi:[1,0]
	v_pk_mul_f32 v[116:117], v[88:89], v[112:113] op_sel_hi:[1,0]
	v_pk_mul_f32 v[118:119], v[90:91], v[110:111] op_sel_hi:[1,0]
	v_pk_mul_f32 v[120:121], v[90:91], v[112:113] op_sel_hi:[1,0]
	v_pk_fma_f32 v[114:115], v[100:101], v[104:105], v[114:115] op_sel_hi:[1,0,1]
	v_pk_fma_f32 v[116:117], v[100:101], v[104:105], v[116:117] op_sel:[0,1,0]
	v_pk_fma_f32 v[118:119], v[102:103], v[104:105], v[118:119] op_sel_hi:[1,0,1]
	v_pk_fma_f32 v[120:121], v[102:103], v[104:105], v[120:121] op_sel:[0,1,0]
	v_pk_fma_f32 v[72:73], v[72:73], v[92:93], v[114:115]
	v_pk_fma_f32 v[76:77], v[76:77], v[92:93], v[116:117]
	v_pk_fma_f32 v[74:75], v[74:75], v[94:95], v[118:119]
	v_pk_fma_f32 v[78:79], v[78:79], v[94:95], v[120:121]
	v_pk_mul_f32 v[122:123], v[72:73], v[96:97]
	v_pk_mul_f32 v[124:125], v[76:77], v[96:97]
	v_pk_fma_f32 v[122:123], v[74:75], v[98:99], v[122:123]
	v_pk_fma_f32 v[124:125], v[78:79], v[98:99], v[124:125]
	v_add_f32_e32 v126, v122, v123
	v_add_f32_e32 v127, v124, v125
	ds_write_b64 v187, v[126:127] offset:26624
	s_waitcnt lgkmcnt(1)
	ds_read_b128 v[84:87], v161 offset:12032
	ds_read_b128 v[88:91], v161 offset:20224
	ds_read_b128 v[100:103], v161 offset:28416
	ds_read_b64 v[104:105], v82 offset:44800
	ds_read_b128 v[92:95], v161 offset:3840
	ds_read_b128 v[96:99], v161 offset:36608
	v_pk_mul_f32 v[106:107], v[72:73], v[30:31]
	v_pk_mul_f32 v[108:109], v[76:77], v[30:31]
	v_pk_fma_f32 v[106:107], v[74:75], v[32:33], v[106:107]
	v_pk_fma_f32 v[108:109], v[78:79], v[32:33], v[108:109]
	v_add_f32_e32 v110, v106, v107
	v_add_f32_e32 v112, v108, v109
	s_nop 0
	v_add_f32_dpp v110, v110, v110 quad_perm:[1,0,3,2] row_mask:0xf bank_mask:0xf bound_ctrl:1
	v_add_f32_dpp v112, v112, v112 quad_perm:[1,0,3,2] row_mask:0xf bank_mask:0xf bound_ctrl:1
	s_nop 0
	v_add_f32_dpp v110, v110, v110 quad_perm:[2,3,0,1] row_mask:0xf bank_mask:0xf bound_ctrl:1
	v_add_f32_dpp v112, v112, v112 quad_perm:[2,3,0,1] row_mask:0xf bank_mask:0xf bound_ctrl:1
	s_nop 0
	v_add_f32_dpp v110, v110, v110 row_half_mirror row_mask:0xf bank_mask:0xf bound_ctrl:1
	v_add_f32_dpp v112, v112, v112 row_half_mirror row_mask:0xf bank_mask:0xf bound_ctrl:1
	s_nop 0
	v_add_f32_dpp v110, v110, v110 row_ror:8 row_mask:0xf bank_mask:0xf bound_ctrl:1
	v_add_f32_dpp v112, v112, v112 row_ror:8 row_mask:0xf bank_mask:0xf bound_ctrl:1
	v_pk_mul_f32 v[114:115], v[34:35], v[110:111] op_sel_hi:[1,0]
	v_pk_mul_f32 v[116:117], v[34:35], v[112:113] op_sel_hi:[1,0]
	v_pk_mul_f32 v[118:119], v[36:37], v[110:111] op_sel_hi:[1,0]
	v_pk_mul_f32 v[120:121], v[36:37], v[112:113] op_sel_hi:[1,0]
	v_pk_fma_f32 v[114:115], v[46:47], v[80:81], v[114:115] op_sel_hi:[1,0,1]
	v_pk_fma_f32 v[116:117], v[46:47], v[80:81], v[116:117] op_sel:[0,1,0]
	v_pk_fma_f32 v[118:119], v[48:49], v[80:81], v[118:119] op_sel_hi:[1,0,1]
	v_pk_fma_f32 v[120:121], v[48:49], v[80:81], v[120:121] op_sel:[0,1,0]
	v_pk_fma_f32 v[72:73], v[72:73], v[38:39], v[114:115]
	v_pk_fma_f32 v[76:77], v[76:77], v[38:39], v[116:117]
	v_pk_fma_f32 v[74:75], v[74:75], v[40:41], v[118:119]
	v_pk_fma_f32 v[78:79], v[78:79], v[40:41], v[120:121]
	v_pk_mul_f32 v[122:123], v[72:73], v[42:43]
	v_pk_mul_f32 v[124:125], v[76:77], v[42:43]
	v_pk_fma_f32 v[122:123], v[74:75], v[44:45], v[122:123]
	v_pk_fma_f32 v[124:125], v[78:79], v[44:45], v[124:125]
	v_add_f32_e32 v126, v122, v123
	v_add_f32_e32 v127, v124, v125
	ds_write_b64 v187, v[126:127] offset:28672
	s_waitcnt lgkmcnt(1)
	ds_read_b128 v[30:33], v161 offset:12288
	ds_read_b128 v[34:37], v161 offset:20480
	ds_read_b128 v[46:49], v161 offset:28672
	ds_read_b64 v[80:81], v82 offset:45056
	ds_read_b128 v[38:41], v161 offset:4096
	ds_read_b128 v[42:45], v161 offset:36864
	v_pk_mul_f32 v[106:107], v[72:73], v[84:85]
	v_pk_mul_f32 v[108:109], v[76:77], v[84:85]
	v_pk_fma_f32 v[106:107], v[74:75], v[86:87], v[106:107]
	v_pk_fma_f32 v[108:109], v[78:79], v[86:87], v[108:109]
	v_add_f32_e32 v110, v106, v107
	v_add_f32_e32 v112, v108, v109
	s_nop 0
	v_add_f32_dpp v110, v110, v110 quad_perm:[1,0,3,2] row_mask:0xf bank_mask:0xf bound_ctrl:1
	v_add_f32_dpp v112, v112, v112 quad_perm:[1,0,3,2] row_mask:0xf bank_mask:0xf bound_ctrl:1
	s_nop 0
	v_add_f32_dpp v110, v110, v110 quad_perm:[2,3,0,1] row_mask:0xf bank_mask:0xf bound_ctrl:1
	v_add_f32_dpp v112, v112, v112 quad_perm:[2,3,0,1] row_mask:0xf bank_mask:0xf bound_ctrl:1
	s_nop 0
	v_add_f32_dpp v110, v110, v110 row_half_mirror row_mask:0xf bank_mask:0xf bound_ctrl:1
	v_add_f32_dpp v112, v112, v112 row_half_mirror row_mask:0xf bank_mask:0xf bound_ctrl:1
	s_nop 0
	v_add_f32_dpp v110, v110, v110 row_ror:8 row_mask:0xf bank_mask:0xf bound_ctrl:1
	v_add_f32_dpp v112, v112, v112 row_ror:8 row_mask:0xf bank_mask:0xf bound_ctrl:1
	v_pk_mul_f32 v[114:115], v[88:89], v[110:111] op_sel_hi:[1,0]
	v_pk_mul_f32 v[116:117], v[88:89], v[112:113] op_sel_hi:[1,0]
	v_pk_mul_f32 v[118:119], v[90:91], v[110:111] op_sel_hi:[1,0]
	v_pk_mul_f32 v[120:121], v[90:91], v[112:113] op_sel_hi:[1,0]
	v_pk_fma_f32 v[114:115], v[100:101], v[104:105], v[114:115] op_sel_hi:[1,0,1]
	v_pk_fma_f32 v[116:117], v[100:101], v[104:105], v[116:117] op_sel:[0,1,0]
	v_pk_fma_f32 v[118:119], v[102:103], v[104:105], v[118:119] op_sel_hi:[1,0,1]
	v_pk_fma_f32 v[120:121], v[102:103], v[104:105], v[120:121] op_sel:[0,1,0]
	v_pk_fma_f32 v[72:73], v[72:73], v[92:93], v[114:115]
	v_pk_fma_f32 v[76:77], v[76:77], v[92:93], v[116:117]
	v_pk_fma_f32 v[74:75], v[74:75], v[94:95], v[118:119]
	v_pk_fma_f32 v[78:79], v[78:79], v[94:95], v[120:121]
	v_pk_mul_f32 v[122:123], v[72:73], v[96:97]
	v_pk_mul_f32 v[124:125], v[76:77], v[96:97]
	v_pk_fma_f32 v[122:123], v[74:75], v[98:99], v[122:123]
	v_pk_fma_f32 v[124:125], v[78:79], v[98:99], v[124:125]
	v_add_f32_e32 v126, v122, v123
	v_add_f32_e32 v127, v124, v125
	ds_write_b64 v187, v[126:127] offset:30720
	s_waitcnt lgkmcnt(1)
	ds_read_b128 v[84:87], v161 offset:12544
	ds_read_b128 v[88:91], v161 offset:20736
	ds_read_b128 v[100:103], v161 offset:28928
	ds_read_b64 v[104:105], v82 offset:45312
	ds_read_b128 v[92:95], v161 offset:4352
	ds_read_b128 v[96:99], v161 offset:37120
	v_pk_mul_f32 v[106:107], v[72:73], v[30:31]
	v_pk_mul_f32 v[108:109], v[76:77], v[30:31]
	v_pk_fma_f32 v[106:107], v[74:75], v[32:33], v[106:107]
	v_pk_fma_f32 v[108:109], v[78:79], v[32:33], v[108:109]
	v_add_f32_e32 v110, v106, v107
	v_add_f32_e32 v112, v108, v109
	s_nop 0
	v_add_f32_dpp v110, v110, v110 quad_perm:[1,0,3,2] row_mask:0xf bank_mask:0xf bound_ctrl:1
	v_add_f32_dpp v112, v112, v112 quad_perm:[1,0,3,2] row_mask:0xf bank_mask:0xf bound_ctrl:1
	s_nop 0
	v_add_f32_dpp v110, v110, v110 quad_perm:[2,3,0,1] row_mask:0xf bank_mask:0xf bound_ctrl:1
	v_add_f32_dpp v112, v112, v112 quad_perm:[2,3,0,1] row_mask:0xf bank_mask:0xf bound_ctrl:1
	s_nop 0
	v_add_f32_dpp v110, v110, v110 row_half_mirror row_mask:0xf bank_mask:0xf bound_ctrl:1
	v_add_f32_dpp v112, v112, v112 row_half_mirror row_mask:0xf bank_mask:0xf bound_ctrl:1
	s_nop 0
	v_add_f32_dpp v110, v110, v110 row_ror:8 row_mask:0xf bank_mask:0xf bound_ctrl:1
	v_add_f32_dpp v112, v112, v112 row_ror:8 row_mask:0xf bank_mask:0xf bound_ctrl:1
	v_pk_mul_f32 v[114:115], v[34:35], v[110:111] op_sel_hi:[1,0]
	v_pk_mul_f32 v[116:117], v[34:35], v[112:113] op_sel_hi:[1,0]
	v_pk_mul_f32 v[118:119], v[36:37], v[110:111] op_sel_hi:[1,0]
	v_pk_mul_f32 v[120:121], v[36:37], v[112:113] op_sel_hi:[1,0]
	v_pk_fma_f32 v[114:115], v[46:47], v[80:81], v[114:115] op_sel_hi:[1,0,1]
	v_pk_fma_f32 v[116:117], v[46:47], v[80:81], v[116:117] op_sel:[0,1,0]
	v_pk_fma_f32 v[118:119], v[48:49], v[80:81], v[118:119] op_sel_hi:[1,0,1]
	v_pk_fma_f32 v[120:121], v[48:49], v[80:81], v[120:121] op_sel:[0,1,0]
	v_pk_fma_f32 v[72:73], v[72:73], v[38:39], v[114:115]
	v_pk_fma_f32 v[76:77], v[76:77], v[38:39], v[116:117]
	v_pk_fma_f32 v[74:75], v[74:75], v[40:41], v[118:119]
	v_pk_fma_f32 v[78:79], v[78:79], v[40:41], v[120:121]
	v_pk_mul_f32 v[122:123], v[72:73], v[42:43]
	v_pk_mul_f32 v[124:125], v[76:77], v[42:43]
	v_pk_fma_f32 v[122:123], v[74:75], v[44:45], v[122:123]
	v_pk_fma_f32 v[124:125], v[78:79], v[44:45], v[124:125]
	v_add_f32_e32 v126, v122, v123
	v_add_f32_e32 v127, v124, v125
	ds_write_b64 v187, v[126:127] offset:32768
	s_waitcnt lgkmcnt(1)
	ds_read_b128 v[30:33], v161 offset:12800
	ds_read_b128 v[34:37], v161 offset:20992
	ds_read_b128 v[46:49], v161 offset:29184
	ds_read_b64 v[80:81], v82 offset:45568
	ds_read_b128 v[38:41], v161 offset:4608
	ds_read_b128 v[42:45], v161 offset:37376
	v_pk_mul_f32 v[106:107], v[72:73], v[84:85]
	v_pk_mul_f32 v[108:109], v[76:77], v[84:85]
	v_pk_fma_f32 v[106:107], v[74:75], v[86:87], v[106:107]
	v_pk_fma_f32 v[108:109], v[78:79], v[86:87], v[108:109]
	v_add_f32_e32 v110, v106, v107
	v_add_f32_e32 v112, v108, v109
	s_nop 0
	v_add_f32_dpp v110, v110, v110 quad_perm:[1,0,3,2] row_mask:0xf bank_mask:0xf bound_ctrl:1
	v_add_f32_dpp v112, v112, v112 quad_perm:[1,0,3,2] row_mask:0xf bank_mask:0xf bound_ctrl:1
	s_nop 0
	v_add_f32_dpp v110, v110, v110 quad_perm:[2,3,0,1] row_mask:0xf bank_mask:0xf bound_ctrl:1
	v_add_f32_dpp v112, v112, v112 quad_perm:[2,3,0,1] row_mask:0xf bank_mask:0xf bound_ctrl:1
	s_nop 0
	v_add_f32_dpp v110, v110, v110 row_half_mirror row_mask:0xf bank_mask:0xf bound_ctrl:1
	v_add_f32_dpp v112, v112, v112 row_half_mirror row_mask:0xf bank_mask:0xf bound_ctrl:1
	s_nop 0
	v_add_f32_dpp v110, v110, v110 row_ror:8 row_mask:0xf bank_mask:0xf bound_ctrl:1
	v_add_f32_dpp v112, v112, v112 row_ror:8 row_mask:0xf bank_mask:0xf bound_ctrl:1
	v_pk_mul_f32 v[114:115], v[88:89], v[110:111] op_sel_hi:[1,0]
	v_pk_mul_f32 v[116:117], v[88:89], v[112:113] op_sel_hi:[1,0]
	v_pk_mul_f32 v[118:119], v[90:91], v[110:111] op_sel_hi:[1,0]
	v_pk_mul_f32 v[120:121], v[90:91], v[112:113] op_sel_hi:[1,0]
	v_pk_fma_f32 v[114:115], v[100:101], v[104:105], v[114:115] op_sel_hi:[1,0,1]
	v_pk_fma_f32 v[116:117], v[100:101], v[104:105], v[116:117] op_sel:[0,1,0]
	v_pk_fma_f32 v[118:119], v[102:103], v[104:105], v[118:119] op_sel_hi:[1,0,1]
	v_pk_fma_f32 v[120:121], v[102:103], v[104:105], v[120:121] op_sel:[0,1,0]
	v_pk_fma_f32 v[72:73], v[72:73], v[92:93], v[114:115]
	v_pk_fma_f32 v[76:77], v[76:77], v[92:93], v[116:117]
	v_pk_fma_f32 v[74:75], v[74:75], v[94:95], v[118:119]
	v_pk_fma_f32 v[78:79], v[78:79], v[94:95], v[120:121]
	v_pk_mul_f32 v[122:123], v[72:73], v[96:97]
	v_pk_mul_f32 v[124:125], v[76:77], v[96:97]
	v_pk_fma_f32 v[122:123], v[74:75], v[98:99], v[122:123]
	v_pk_fma_f32 v[124:125], v[78:79], v[98:99], v[124:125]
	v_add_f32_e32 v126, v122, v123
	v_add_f32_e32 v127, v124, v125
	ds_write_b64 v187, v[126:127] offset:34816
	s_waitcnt lgkmcnt(1)
	ds_read_b128 v[84:87], v161 offset:13056
	ds_read_b128 v[88:91], v161 offset:21248
	ds_read_b128 v[100:103], v161 offset:29440
	ds_read_b64 v[104:105], v82 offset:45824
	ds_read_b128 v[92:95], v161 offset:4864
	ds_read_b128 v[96:99], v161 offset:37632
	v_pk_mul_f32 v[106:107], v[72:73], v[30:31]
	v_pk_mul_f32 v[108:109], v[76:77], v[30:31]
	v_pk_fma_f32 v[106:107], v[74:75], v[32:33], v[106:107]
	v_pk_fma_f32 v[108:109], v[78:79], v[32:33], v[108:109]
	v_add_f32_e32 v110, v106, v107
	v_add_f32_e32 v112, v108, v109
	s_nop 0
	v_add_f32_dpp v110, v110, v110 quad_perm:[1,0,3,2] row_mask:0xf bank_mask:0xf bound_ctrl:1
	v_add_f32_dpp v112, v112, v112 quad_perm:[1,0,3,2] row_mask:0xf bank_mask:0xf bound_ctrl:1
	s_nop 0
	v_add_f32_dpp v110, v110, v110 quad_perm:[2,3,0,1] row_mask:0xf bank_mask:0xf bound_ctrl:1
	v_add_f32_dpp v112, v112, v112 quad_perm:[2,3,0,1] row_mask:0xf bank_mask:0xf bound_ctrl:1
	s_nop 0
	v_add_f32_dpp v110, v110, v110 row_half_mirror row_mask:0xf bank_mask:0xf bound_ctrl:1
	v_add_f32_dpp v112, v112, v112 row_half_mirror row_mask:0xf bank_mask:0xf bound_ctrl:1
	s_nop 0
	v_add_f32_dpp v110, v110, v110 row_ror:8 row_mask:0xf bank_mask:0xf bound_ctrl:1
	v_add_f32_dpp v112, v112, v112 row_ror:8 row_mask:0xf bank_mask:0xf bound_ctrl:1
	v_pk_mul_f32 v[114:115], v[34:35], v[110:111] op_sel_hi:[1,0]
	v_pk_mul_f32 v[116:117], v[34:35], v[112:113] op_sel_hi:[1,0]
	v_pk_mul_f32 v[118:119], v[36:37], v[110:111] op_sel_hi:[1,0]
	v_pk_mul_f32 v[120:121], v[36:37], v[112:113] op_sel_hi:[1,0]
	v_pk_fma_f32 v[114:115], v[46:47], v[80:81], v[114:115] op_sel_hi:[1,0,1]
	v_pk_fma_f32 v[116:117], v[46:47], v[80:81], v[116:117] op_sel:[0,1,0]
	v_pk_fma_f32 v[118:119], v[48:49], v[80:81], v[118:119] op_sel_hi:[1,0,1]
	v_pk_fma_f32 v[120:121], v[48:49], v[80:81], v[120:121] op_sel:[0,1,0]
	v_pk_fma_f32 v[72:73], v[72:73], v[38:39], v[114:115]
	v_pk_fma_f32 v[76:77], v[76:77], v[38:39], v[116:117]
	v_pk_fma_f32 v[74:75], v[74:75], v[40:41], v[118:119]
	v_pk_fma_f32 v[78:79], v[78:79], v[40:41], v[120:121]
	v_pk_mul_f32 v[122:123], v[72:73], v[42:43]
	v_pk_mul_f32 v[124:125], v[76:77], v[42:43]
	v_pk_fma_f32 v[122:123], v[74:75], v[44:45], v[122:123]
	v_pk_fma_f32 v[124:125], v[78:79], v[44:45], v[124:125]
	v_add_f32_e32 v126, v122, v123
	v_add_f32_e32 v127, v124, v125
	ds_write_b64 v187, v[126:127] offset:36864
	s_waitcnt lgkmcnt(1)
	ds_read_b128 v[30:33], v161 offset:13312
	ds_read_b128 v[34:37], v161 offset:21504
	ds_read_b128 v[46:49], v161 offset:29696
	ds_read_b64 v[80:81], v82 offset:46080
	ds_read_b128 v[38:41], v161 offset:5120
	ds_read_b128 v[42:45], v161 offset:37888
	v_pk_mul_f32 v[106:107], v[72:73], v[84:85]
	v_pk_mul_f32 v[108:109], v[76:77], v[84:85]
	v_pk_fma_f32 v[106:107], v[74:75], v[86:87], v[106:107]
	v_pk_fma_f32 v[108:109], v[78:79], v[86:87], v[108:109]
	v_add_f32_e32 v110, v106, v107
	v_add_f32_e32 v112, v108, v109
	s_nop 0
	v_add_f32_dpp v110, v110, v110 quad_perm:[1,0,3,2] row_mask:0xf bank_mask:0xf bound_ctrl:1
	v_add_f32_dpp v112, v112, v112 quad_perm:[1,0,3,2] row_mask:0xf bank_mask:0xf bound_ctrl:1
	s_nop 0
	v_add_f32_dpp v110, v110, v110 quad_perm:[2,3,0,1] row_mask:0xf bank_mask:0xf bound_ctrl:1
	v_add_f32_dpp v112, v112, v112 quad_perm:[2,3,0,1] row_mask:0xf bank_mask:0xf bound_ctrl:1
	s_nop 0
	v_add_f32_dpp v110, v110, v110 row_half_mirror row_mask:0xf bank_mask:0xf bound_ctrl:1
	v_add_f32_dpp v112, v112, v112 row_half_mirror row_mask:0xf bank_mask:0xf bound_ctrl:1
	s_nop 0
	v_add_f32_dpp v110, v110, v110 row_ror:8 row_mask:0xf bank_mask:0xf bound_ctrl:1
	v_add_f32_dpp v112, v112, v112 row_ror:8 row_mask:0xf bank_mask:0xf bound_ctrl:1
	v_pk_mul_f32 v[114:115], v[88:89], v[110:111] op_sel_hi:[1,0]
	v_pk_mul_f32 v[116:117], v[88:89], v[112:113] op_sel_hi:[1,0]
	v_pk_mul_f32 v[118:119], v[90:91], v[110:111] op_sel_hi:[1,0]
	v_pk_mul_f32 v[120:121], v[90:91], v[112:113] op_sel_hi:[1,0]
	v_pk_fma_f32 v[114:115], v[100:101], v[104:105], v[114:115] op_sel_hi:[1,0,1]
	v_pk_fma_f32 v[116:117], v[100:101], v[104:105], v[116:117] op_sel:[0,1,0]
	v_pk_fma_f32 v[118:119], v[102:103], v[104:105], v[118:119] op_sel_hi:[1,0,1]
	v_pk_fma_f32 v[120:121], v[102:103], v[104:105], v[120:121] op_sel:[0,1,0]
	v_pk_fma_f32 v[72:73], v[72:73], v[92:93], v[114:115]
	v_pk_fma_f32 v[76:77], v[76:77], v[92:93], v[116:117]
	v_pk_fma_f32 v[74:75], v[74:75], v[94:95], v[118:119]
	v_pk_fma_f32 v[78:79], v[78:79], v[94:95], v[120:121]
	v_pk_mul_f32 v[122:123], v[72:73], v[96:97]
	v_pk_mul_f32 v[124:125], v[76:77], v[96:97]
	v_pk_fma_f32 v[122:123], v[74:75], v[98:99], v[122:123]
	v_pk_fma_f32 v[124:125], v[78:79], v[98:99], v[124:125]
	v_add_f32_e32 v126, v122, v123
	v_add_f32_e32 v127, v124, v125
	ds_write_b64 v187, v[126:127] offset:38912
	s_waitcnt lgkmcnt(1)
	ds_read_b128 v[84:87], v161 offset:13568
	ds_read_b128 v[88:91], v161 offset:21760
	ds_read_b128 v[100:103], v161 offset:29952
	ds_read_b64 v[104:105], v82 offset:46336
	ds_read_b128 v[92:95], v161 offset:5376
	ds_read_b128 v[96:99], v161 offset:38144
	v_pk_mul_f32 v[106:107], v[72:73], v[30:31]
	v_pk_mul_f32 v[108:109], v[76:77], v[30:31]
	v_pk_fma_f32 v[106:107], v[74:75], v[32:33], v[106:107]
	v_pk_fma_f32 v[108:109], v[78:79], v[32:33], v[108:109]
	v_add_f32_e32 v110, v106, v107
	v_add_f32_e32 v112, v108, v109
	s_nop 0
	v_add_f32_dpp v110, v110, v110 quad_perm:[1,0,3,2] row_mask:0xf bank_mask:0xf bound_ctrl:1
	v_add_f32_dpp v112, v112, v112 quad_perm:[1,0,3,2] row_mask:0xf bank_mask:0xf bound_ctrl:1
	s_nop 0
	v_add_f32_dpp v110, v110, v110 quad_perm:[2,3,0,1] row_mask:0xf bank_mask:0xf bound_ctrl:1
	v_add_f32_dpp v112, v112, v112 quad_perm:[2,3,0,1] row_mask:0xf bank_mask:0xf bound_ctrl:1
	s_nop 0
	v_add_f32_dpp v110, v110, v110 row_half_mirror row_mask:0xf bank_mask:0xf bound_ctrl:1
	v_add_f32_dpp v112, v112, v112 row_half_mirror row_mask:0xf bank_mask:0xf bound_ctrl:1
	s_nop 0
	v_add_f32_dpp v110, v110, v110 row_ror:8 row_mask:0xf bank_mask:0xf bound_ctrl:1
	v_add_f32_dpp v112, v112, v112 row_ror:8 row_mask:0xf bank_mask:0xf bound_ctrl:1
	v_pk_mul_f32 v[114:115], v[34:35], v[110:111] op_sel_hi:[1,0]
	v_pk_mul_f32 v[116:117], v[34:35], v[112:113] op_sel_hi:[1,0]
	v_pk_mul_f32 v[118:119], v[36:37], v[110:111] op_sel_hi:[1,0]
	v_pk_mul_f32 v[120:121], v[36:37], v[112:113] op_sel_hi:[1,0]
	v_pk_fma_f32 v[114:115], v[46:47], v[80:81], v[114:115] op_sel_hi:[1,0,1]
	v_pk_fma_f32 v[116:117], v[46:47], v[80:81], v[116:117] op_sel:[0,1,0]
	v_pk_fma_f32 v[118:119], v[48:49], v[80:81], v[118:119] op_sel_hi:[1,0,1]
	v_pk_fma_f32 v[120:121], v[48:49], v[80:81], v[120:121] op_sel:[0,1,0]
	v_pk_fma_f32 v[72:73], v[72:73], v[38:39], v[114:115]
	v_pk_fma_f32 v[76:77], v[76:77], v[38:39], v[116:117]
	v_pk_fma_f32 v[74:75], v[74:75], v[40:41], v[118:119]
	v_pk_fma_f32 v[78:79], v[78:79], v[40:41], v[120:121]
	v_pk_mul_f32 v[122:123], v[72:73], v[42:43]
	v_pk_mul_f32 v[124:125], v[76:77], v[42:43]
	v_pk_fma_f32 v[122:123], v[74:75], v[44:45], v[122:123]
	v_pk_fma_f32 v[124:125], v[78:79], v[44:45], v[124:125]
	v_add_f32_e32 v126, v122, v123
	v_add_f32_e32 v127, v124, v125
	ds_write_b64 v187, v[126:127] offset:40960
	s_waitcnt lgkmcnt(1)
	ds_read_b128 v[30:33], v161 offset:13824
	ds_read_b128 v[34:37], v161 offset:22016
	ds_read_b128 v[46:49], v161 offset:30208
	ds_read_b64 v[80:81], v82 offset:46592
	ds_read_b128 v[38:41], v161 offset:5632
	ds_read_b128 v[42:45], v161 offset:38400
	v_pk_mul_f32 v[106:107], v[72:73], v[84:85]
	v_pk_mul_f32 v[108:109], v[76:77], v[84:85]
	v_pk_fma_f32 v[106:107], v[74:75], v[86:87], v[106:107]
	v_pk_fma_f32 v[108:109], v[78:79], v[86:87], v[108:109]
	v_add_f32_e32 v110, v106, v107
	v_add_f32_e32 v112, v108, v109
	s_nop 0
	v_add_f32_dpp v110, v110, v110 quad_perm:[1,0,3,2] row_mask:0xf bank_mask:0xf bound_ctrl:1
	v_add_f32_dpp v112, v112, v112 quad_perm:[1,0,3,2] row_mask:0xf bank_mask:0xf bound_ctrl:1
	s_nop 0
	v_add_f32_dpp v110, v110, v110 quad_perm:[2,3,0,1] row_mask:0xf bank_mask:0xf bound_ctrl:1
	v_add_f32_dpp v112, v112, v112 quad_perm:[2,3,0,1] row_mask:0xf bank_mask:0xf bound_ctrl:1
	s_nop 0
	v_add_f32_dpp v110, v110, v110 row_half_mirror row_mask:0xf bank_mask:0xf bound_ctrl:1
	v_add_f32_dpp v112, v112, v112 row_half_mirror row_mask:0xf bank_mask:0xf bound_ctrl:1
	s_nop 0
	v_add_f32_dpp v110, v110, v110 row_ror:8 row_mask:0xf bank_mask:0xf bound_ctrl:1
	v_add_f32_dpp v112, v112, v112 row_ror:8 row_mask:0xf bank_mask:0xf bound_ctrl:1
	v_pk_mul_f32 v[114:115], v[88:89], v[110:111] op_sel_hi:[1,0]
	v_pk_mul_f32 v[116:117], v[88:89], v[112:113] op_sel_hi:[1,0]
	v_pk_mul_f32 v[118:119], v[90:91], v[110:111] op_sel_hi:[1,0]
	v_pk_mul_f32 v[120:121], v[90:91], v[112:113] op_sel_hi:[1,0]
	v_pk_fma_f32 v[114:115], v[100:101], v[104:105], v[114:115] op_sel_hi:[1,0,1]
	v_pk_fma_f32 v[116:117], v[100:101], v[104:105], v[116:117] op_sel:[0,1,0]
	v_pk_fma_f32 v[118:119], v[102:103], v[104:105], v[118:119] op_sel_hi:[1,0,1]
	v_pk_fma_f32 v[120:121], v[102:103], v[104:105], v[120:121] op_sel:[0,1,0]
	v_pk_fma_f32 v[72:73], v[72:73], v[92:93], v[114:115]
	v_pk_fma_f32 v[76:77], v[76:77], v[92:93], v[116:117]
	v_pk_fma_f32 v[74:75], v[74:75], v[94:95], v[118:119]
	v_pk_fma_f32 v[78:79], v[78:79], v[94:95], v[120:121]
	v_pk_mul_f32 v[122:123], v[72:73], v[96:97]
	v_pk_mul_f32 v[124:125], v[76:77], v[96:97]
	v_pk_fma_f32 v[122:123], v[74:75], v[98:99], v[122:123]
	v_pk_fma_f32 v[124:125], v[78:79], v[98:99], v[124:125]
	v_add_f32_e32 v126, v122, v123
	v_add_f32_e32 v127, v124, v125
	ds_write_b64 v187, v[126:127] offset:43008
	s_waitcnt lgkmcnt(1)
	ds_read_b128 v[84:87], v161 offset:14080
	ds_read_b128 v[88:91], v161 offset:22272
	ds_read_b128 v[100:103], v161 offset:30464
	ds_read_b64 v[104:105], v82 offset:46848
	ds_read_b128 v[92:95], v161 offset:5888
	ds_read_b128 v[96:99], v161 offset:38656
	v_pk_mul_f32 v[106:107], v[72:73], v[30:31]
	v_pk_mul_f32 v[108:109], v[76:77], v[30:31]
	v_pk_fma_f32 v[106:107], v[74:75], v[32:33], v[106:107]
	v_pk_fma_f32 v[108:109], v[78:79], v[32:33], v[108:109]
	v_add_f32_e32 v110, v106, v107
	v_add_f32_e32 v112, v108, v109
	s_nop 0
	v_add_f32_dpp v110, v110, v110 quad_perm:[1,0,3,2] row_mask:0xf bank_mask:0xf bound_ctrl:1
	v_add_f32_dpp v112, v112, v112 quad_perm:[1,0,3,2] row_mask:0xf bank_mask:0xf bound_ctrl:1
	s_nop 0
	v_add_f32_dpp v110, v110, v110 quad_perm:[2,3,0,1] row_mask:0xf bank_mask:0xf bound_ctrl:1
	v_add_f32_dpp v112, v112, v112 quad_perm:[2,3,0,1] row_mask:0xf bank_mask:0xf bound_ctrl:1
	s_nop 0
	v_add_f32_dpp v110, v110, v110 row_half_mirror row_mask:0xf bank_mask:0xf bound_ctrl:1
	v_add_f32_dpp v112, v112, v112 row_half_mirror row_mask:0xf bank_mask:0xf bound_ctrl:1
	s_nop 0
	v_add_f32_dpp v110, v110, v110 row_ror:8 row_mask:0xf bank_mask:0xf bound_ctrl:1
	v_add_f32_dpp v112, v112, v112 row_ror:8 row_mask:0xf bank_mask:0xf bound_ctrl:1
	v_pk_mul_f32 v[114:115], v[34:35], v[110:111] op_sel_hi:[1,0]
	v_pk_mul_f32 v[116:117], v[34:35], v[112:113] op_sel_hi:[1,0]
	v_pk_mul_f32 v[118:119], v[36:37], v[110:111] op_sel_hi:[1,0]
	v_pk_mul_f32 v[120:121], v[36:37], v[112:113] op_sel_hi:[1,0]
	v_pk_fma_f32 v[114:115], v[46:47], v[80:81], v[114:115] op_sel_hi:[1,0,1]
	v_pk_fma_f32 v[116:117], v[46:47], v[80:81], v[116:117] op_sel:[0,1,0]
	v_pk_fma_f32 v[118:119], v[48:49], v[80:81], v[118:119] op_sel_hi:[1,0,1]
	v_pk_fma_f32 v[120:121], v[48:49], v[80:81], v[120:121] op_sel:[0,1,0]
	v_pk_fma_f32 v[72:73], v[72:73], v[38:39], v[114:115]
	v_pk_fma_f32 v[76:77], v[76:77], v[38:39], v[116:117]
	v_pk_fma_f32 v[74:75], v[74:75], v[40:41], v[118:119]
	v_pk_fma_f32 v[78:79], v[78:79], v[40:41], v[120:121]
	v_pk_mul_f32 v[122:123], v[72:73], v[42:43]
	v_pk_mul_f32 v[124:125], v[76:77], v[42:43]
	v_pk_fma_f32 v[122:123], v[74:75], v[44:45], v[122:123]
	v_pk_fma_f32 v[124:125], v[78:79], v[44:45], v[124:125]
	v_add_f32_e32 v126, v122, v123
	v_add_f32_e32 v127, v124, v125
	ds_write_b64 v187, v[126:127] offset:45056
	s_waitcnt lgkmcnt(1)
	ds_read_b128 v[30:33], v161 offset:14336
	ds_read_b128 v[34:37], v161 offset:22528
	ds_read_b128 v[46:49], v161 offset:30720
	ds_read_b64 v[80:81], v82 offset:47104
	ds_read_b128 v[38:41], v161 offset:6144
	ds_read_b128 v[42:45], v161 offset:38912
	v_pk_mul_f32 v[106:107], v[72:73], v[84:85]
	v_pk_mul_f32 v[108:109], v[76:77], v[84:85]
	v_pk_fma_f32 v[106:107], v[74:75], v[86:87], v[106:107]
	v_pk_fma_f32 v[108:109], v[78:79], v[86:87], v[108:109]
	v_add_f32_e32 v110, v106, v107
	v_add_f32_e32 v112, v108, v109
	s_nop 0
	v_add_f32_dpp v110, v110, v110 quad_perm:[1,0,3,2] row_mask:0xf bank_mask:0xf bound_ctrl:1
	v_add_f32_dpp v112, v112, v112 quad_perm:[1,0,3,2] row_mask:0xf bank_mask:0xf bound_ctrl:1
	s_nop 0
	v_add_f32_dpp v110, v110, v110 quad_perm:[2,3,0,1] row_mask:0xf bank_mask:0xf bound_ctrl:1
	v_add_f32_dpp v112, v112, v112 quad_perm:[2,3,0,1] row_mask:0xf bank_mask:0xf bound_ctrl:1
	s_nop 0
	v_add_f32_dpp v110, v110, v110 row_half_mirror row_mask:0xf bank_mask:0xf bound_ctrl:1
	v_add_f32_dpp v112, v112, v112 row_half_mirror row_mask:0xf bank_mask:0xf bound_ctrl:1
	s_nop 0
	v_add_f32_dpp v110, v110, v110 row_ror:8 row_mask:0xf bank_mask:0xf bound_ctrl:1
	v_add_f32_dpp v112, v112, v112 row_ror:8 row_mask:0xf bank_mask:0xf bound_ctrl:1
	v_pk_mul_f32 v[114:115], v[88:89], v[110:111] op_sel_hi:[1,0]
	v_pk_mul_f32 v[116:117], v[88:89], v[112:113] op_sel_hi:[1,0]
	v_pk_mul_f32 v[118:119], v[90:91], v[110:111] op_sel_hi:[1,0]
	v_pk_mul_f32 v[120:121], v[90:91], v[112:113] op_sel_hi:[1,0]
	v_pk_fma_f32 v[114:115], v[100:101], v[104:105], v[114:115] op_sel_hi:[1,0,1]
	v_pk_fma_f32 v[116:117], v[100:101], v[104:105], v[116:117] op_sel:[0,1,0]
	v_pk_fma_f32 v[118:119], v[102:103], v[104:105], v[118:119] op_sel_hi:[1,0,1]
	v_pk_fma_f32 v[120:121], v[102:103], v[104:105], v[120:121] op_sel:[0,1,0]
	v_pk_fma_f32 v[72:73], v[72:73], v[92:93], v[114:115]
	v_pk_fma_f32 v[76:77], v[76:77], v[92:93], v[116:117]
	v_pk_fma_f32 v[74:75], v[74:75], v[94:95], v[118:119]
	v_pk_fma_f32 v[78:79], v[78:79], v[94:95], v[120:121]
	v_pk_mul_f32 v[122:123], v[72:73], v[96:97]
	v_pk_mul_f32 v[124:125], v[76:77], v[96:97]
	v_pk_fma_f32 v[122:123], v[74:75], v[98:99], v[122:123]
	v_pk_fma_f32 v[124:125], v[78:79], v[98:99], v[124:125]
	v_add_f32_e32 v126, v122, v123
	v_add_f32_e32 v127, v124, v125
	ds_write_b64 v187, v[126:127] offset:47104
	s_waitcnt lgkmcnt(1)
	ds_read_b128 v[84:87], v161 offset:14592
	ds_read_b128 v[88:91], v161 offset:22784
	ds_read_b128 v[100:103], v161 offset:30976
	ds_read_b64 v[104:105], v82 offset:47360
	ds_read_b128 v[92:95], v161 offset:6400
	ds_read_b128 v[96:99], v161 offset:39168
	v_pk_mul_f32 v[106:107], v[72:73], v[30:31]
	v_pk_mul_f32 v[108:109], v[76:77], v[30:31]
	v_pk_fma_f32 v[106:107], v[74:75], v[32:33], v[106:107]
	v_pk_fma_f32 v[108:109], v[78:79], v[32:33], v[108:109]
	v_add_f32_e32 v110, v106, v107
	v_add_f32_e32 v112, v108, v109
	s_nop 0
	v_add_f32_dpp v110, v110, v110 quad_perm:[1,0,3,2] row_mask:0xf bank_mask:0xf bound_ctrl:1
	v_add_f32_dpp v112, v112, v112 quad_perm:[1,0,3,2] row_mask:0xf bank_mask:0xf bound_ctrl:1
	s_nop 0
	v_add_f32_dpp v110, v110, v110 quad_perm:[2,3,0,1] row_mask:0xf bank_mask:0xf bound_ctrl:1
	v_add_f32_dpp v112, v112, v112 quad_perm:[2,3,0,1] row_mask:0xf bank_mask:0xf bound_ctrl:1
	s_nop 0
	v_add_f32_dpp v110, v110, v110 row_half_mirror row_mask:0xf bank_mask:0xf bound_ctrl:1
	v_add_f32_dpp v112, v112, v112 row_half_mirror row_mask:0xf bank_mask:0xf bound_ctrl:1
	s_nop 0
	v_add_f32_dpp v110, v110, v110 row_ror:8 row_mask:0xf bank_mask:0xf bound_ctrl:1
	v_add_f32_dpp v112, v112, v112 row_ror:8 row_mask:0xf bank_mask:0xf bound_ctrl:1
	v_pk_mul_f32 v[114:115], v[34:35], v[110:111] op_sel_hi:[1,0]
	v_pk_mul_f32 v[116:117], v[34:35], v[112:113] op_sel_hi:[1,0]
	v_pk_mul_f32 v[118:119], v[36:37], v[110:111] op_sel_hi:[1,0]
	v_pk_mul_f32 v[120:121], v[36:37], v[112:113] op_sel_hi:[1,0]
	v_pk_fma_f32 v[114:115], v[46:47], v[80:81], v[114:115] op_sel_hi:[1,0,1]
	v_pk_fma_f32 v[116:117], v[46:47], v[80:81], v[116:117] op_sel:[0,1,0]
	v_pk_fma_f32 v[118:119], v[48:49], v[80:81], v[118:119] op_sel_hi:[1,0,1]
	v_pk_fma_f32 v[120:121], v[48:49], v[80:81], v[120:121] op_sel:[0,1,0]
	v_pk_fma_f32 v[72:73], v[72:73], v[38:39], v[114:115]
	v_pk_fma_f32 v[76:77], v[76:77], v[38:39], v[116:117]
	v_pk_fma_f32 v[74:75], v[74:75], v[40:41], v[118:119]
	v_pk_fma_f32 v[78:79], v[78:79], v[40:41], v[120:121]
	v_pk_mul_f32 v[122:123], v[72:73], v[42:43]
	v_pk_mul_f32 v[124:125], v[76:77], v[42:43]
	v_pk_fma_f32 v[122:123], v[74:75], v[44:45], v[122:123]
	v_pk_fma_f32 v[124:125], v[78:79], v[44:45], v[124:125]
	v_add_f32_e32 v126, v122, v123
	v_add_f32_e32 v127, v124, v125
	ds_write_b64 v187, v[126:127] offset:49152
	s_waitcnt lgkmcnt(1)
	ds_read_b128 v[30:33], v161 offset:14848
	ds_read_b128 v[34:37], v161 offset:23040
	ds_read_b128 v[46:49], v161 offset:31232
	ds_read_b64 v[80:81], v82 offset:47616
	ds_read_b128 v[38:41], v161 offset:6656
	ds_read_b128 v[42:45], v161 offset:39424
	v_pk_mul_f32 v[106:107], v[72:73], v[84:85]
	v_pk_mul_f32 v[108:109], v[76:77], v[84:85]
	v_pk_fma_f32 v[106:107], v[74:75], v[86:87], v[106:107]
	v_pk_fma_f32 v[108:109], v[78:79], v[86:87], v[108:109]
	v_add_f32_e32 v110, v106, v107
	v_add_f32_e32 v112, v108, v109
	s_nop 0
	v_add_f32_dpp v110, v110, v110 quad_perm:[1,0,3,2] row_mask:0xf bank_mask:0xf bound_ctrl:1
	v_add_f32_dpp v112, v112, v112 quad_perm:[1,0,3,2] row_mask:0xf bank_mask:0xf bound_ctrl:1
	s_nop 0
	v_add_f32_dpp v110, v110, v110 quad_perm:[2,3,0,1] row_mask:0xf bank_mask:0xf bound_ctrl:1
	v_add_f32_dpp v112, v112, v112 quad_perm:[2,3,0,1] row_mask:0xf bank_mask:0xf bound_ctrl:1
	s_nop 0
	v_add_f32_dpp v110, v110, v110 row_half_mirror row_mask:0xf bank_mask:0xf bound_ctrl:1
	v_add_f32_dpp v112, v112, v112 row_half_mirror row_mask:0xf bank_mask:0xf bound_ctrl:1
	s_nop 0
	v_add_f32_dpp v110, v110, v110 row_ror:8 row_mask:0xf bank_mask:0xf bound_ctrl:1
	v_add_f32_dpp v112, v112, v112 row_ror:8 row_mask:0xf bank_mask:0xf bound_ctrl:1
	v_pk_mul_f32 v[114:115], v[88:89], v[110:111] op_sel_hi:[1,0]
	v_pk_mul_f32 v[116:117], v[88:89], v[112:113] op_sel_hi:[1,0]
	v_pk_mul_f32 v[118:119], v[90:91], v[110:111] op_sel_hi:[1,0]
	v_pk_mul_f32 v[120:121], v[90:91], v[112:113] op_sel_hi:[1,0]
	v_pk_fma_f32 v[114:115], v[100:101], v[104:105], v[114:115] op_sel_hi:[1,0,1]
	v_pk_fma_f32 v[116:117], v[100:101], v[104:105], v[116:117] op_sel:[0,1,0]
	v_pk_fma_f32 v[118:119], v[102:103], v[104:105], v[118:119] op_sel_hi:[1,0,1]
	v_pk_fma_f32 v[120:121], v[102:103], v[104:105], v[120:121] op_sel:[0,1,0]
	v_pk_fma_f32 v[72:73], v[72:73], v[92:93], v[114:115]
	v_pk_fma_f32 v[76:77], v[76:77], v[92:93], v[116:117]
	v_pk_fma_f32 v[74:75], v[74:75], v[94:95], v[118:119]
	v_pk_fma_f32 v[78:79], v[78:79], v[94:95], v[120:121]
	v_pk_mul_f32 v[122:123], v[72:73], v[96:97]
	v_pk_mul_f32 v[124:125], v[76:77], v[96:97]
	v_pk_fma_f32 v[122:123], v[74:75], v[98:99], v[122:123]
	v_pk_fma_f32 v[124:125], v[78:79], v[98:99], v[124:125]
	v_add_f32_e32 v126, v122, v123
	v_add_f32_e32 v127, v124, v125
	ds_write_b64 v187, v[126:127] offset:51200
	s_waitcnt lgkmcnt(1)
	ds_read_b128 v[84:87], v161 offset:15104
	ds_read_b128 v[88:91], v161 offset:23296
	ds_read_b128 v[100:103], v161 offset:31488
	ds_read_b64 v[104:105], v82 offset:47872
	ds_read_b128 v[92:95], v161 offset:6912
	ds_read_b128 v[96:99], v161 offset:39680
	v_pk_mul_f32 v[106:107], v[72:73], v[30:31]
	v_pk_mul_f32 v[108:109], v[76:77], v[30:31]
	v_pk_fma_f32 v[106:107], v[74:75], v[32:33], v[106:107]
	v_pk_fma_f32 v[108:109], v[78:79], v[32:33], v[108:109]
	v_add_f32_e32 v110, v106, v107
	v_add_f32_e32 v112, v108, v109
	s_nop 0
	v_add_f32_dpp v110, v110, v110 quad_perm:[1,0,3,2] row_mask:0xf bank_mask:0xf bound_ctrl:1
	v_add_f32_dpp v112, v112, v112 quad_perm:[1,0,3,2] row_mask:0xf bank_mask:0xf bound_ctrl:1
	s_nop 0
	v_add_f32_dpp v110, v110, v110 quad_perm:[2,3,0,1] row_mask:0xf bank_mask:0xf bound_ctrl:1
	v_add_f32_dpp v112, v112, v112 quad_perm:[2,3,0,1] row_mask:0xf bank_mask:0xf bound_ctrl:1
	s_nop 0
	v_add_f32_dpp v110, v110, v110 row_half_mirror row_mask:0xf bank_mask:0xf bound_ctrl:1
	v_add_f32_dpp v112, v112, v112 row_half_mirror row_mask:0xf bank_mask:0xf bound_ctrl:1
	s_nop 0
	v_add_f32_dpp v110, v110, v110 row_ror:8 row_mask:0xf bank_mask:0xf bound_ctrl:1
	v_add_f32_dpp v112, v112, v112 row_ror:8 row_mask:0xf bank_mask:0xf bound_ctrl:1
	v_pk_mul_f32 v[114:115], v[34:35], v[110:111] op_sel_hi:[1,0]
	v_pk_mul_f32 v[116:117], v[34:35], v[112:113] op_sel_hi:[1,0]
	v_pk_mul_f32 v[118:119], v[36:37], v[110:111] op_sel_hi:[1,0]
	v_pk_mul_f32 v[120:121], v[36:37], v[112:113] op_sel_hi:[1,0]
	v_pk_fma_f32 v[114:115], v[46:47], v[80:81], v[114:115] op_sel_hi:[1,0,1]
	v_pk_fma_f32 v[116:117], v[46:47], v[80:81], v[116:117] op_sel:[0,1,0]
	v_pk_fma_f32 v[118:119], v[48:49], v[80:81], v[118:119] op_sel_hi:[1,0,1]
	v_pk_fma_f32 v[120:121], v[48:49], v[80:81], v[120:121] op_sel:[0,1,0]
	v_pk_fma_f32 v[72:73], v[72:73], v[38:39], v[114:115]
	v_pk_fma_f32 v[76:77], v[76:77], v[38:39], v[116:117]
	v_pk_fma_f32 v[74:75], v[74:75], v[40:41], v[118:119]
	v_pk_fma_f32 v[78:79], v[78:79], v[40:41], v[120:121]
	v_pk_mul_f32 v[122:123], v[72:73], v[42:43]
	v_pk_mul_f32 v[124:125], v[76:77], v[42:43]
	v_pk_fma_f32 v[122:123], v[74:75], v[44:45], v[122:123]
	v_pk_fma_f32 v[124:125], v[78:79], v[44:45], v[124:125]
	v_add_f32_e32 v126, v122, v123
	v_add_f32_e32 v127, v124, v125
	ds_write_b64 v187, v[126:127] offset:53248
	s_waitcnt lgkmcnt(1)
	ds_read_b128 v[30:33], v161 offset:15360
	ds_read_b128 v[34:37], v161 offset:23552
	ds_read_b128 v[46:49], v161 offset:31744
	ds_read_b64 v[80:81], v82 offset:48128
	ds_read_b128 v[38:41], v161 offset:7168
	ds_read_b128 v[42:45], v161 offset:39936
	v_pk_mul_f32 v[106:107], v[72:73], v[84:85]
	v_pk_mul_f32 v[108:109], v[76:77], v[84:85]
	v_pk_fma_f32 v[106:107], v[74:75], v[86:87], v[106:107]
	v_pk_fma_f32 v[108:109], v[78:79], v[86:87], v[108:109]
	v_add_f32_e32 v110, v106, v107
	v_add_f32_e32 v112, v108, v109
	s_nop 0
	v_add_f32_dpp v110, v110, v110 quad_perm:[1,0,3,2] row_mask:0xf bank_mask:0xf bound_ctrl:1
	v_add_f32_dpp v112, v112, v112 quad_perm:[1,0,3,2] row_mask:0xf bank_mask:0xf bound_ctrl:1
	s_nop 0
	v_add_f32_dpp v110, v110, v110 quad_perm:[2,3,0,1] row_mask:0xf bank_mask:0xf bound_ctrl:1
	v_add_f32_dpp v112, v112, v112 quad_perm:[2,3,0,1] row_mask:0xf bank_mask:0xf bound_ctrl:1
	s_nop 0
	v_add_f32_dpp v110, v110, v110 row_half_mirror row_mask:0xf bank_mask:0xf bound_ctrl:1
	v_add_f32_dpp v112, v112, v112 row_half_mirror row_mask:0xf bank_mask:0xf bound_ctrl:1
	s_nop 0
	v_add_f32_dpp v110, v110, v110 row_ror:8 row_mask:0xf bank_mask:0xf bound_ctrl:1
	v_add_f32_dpp v112, v112, v112 row_ror:8 row_mask:0xf bank_mask:0xf bound_ctrl:1
	v_pk_mul_f32 v[114:115], v[88:89], v[110:111] op_sel_hi:[1,0]
	v_pk_mul_f32 v[116:117], v[88:89], v[112:113] op_sel_hi:[1,0]
	v_pk_mul_f32 v[118:119], v[90:91], v[110:111] op_sel_hi:[1,0]
	v_pk_mul_f32 v[120:121], v[90:91], v[112:113] op_sel_hi:[1,0]
	v_pk_fma_f32 v[114:115], v[100:101], v[104:105], v[114:115] op_sel_hi:[1,0,1]
	v_pk_fma_f32 v[116:117], v[100:101], v[104:105], v[116:117] op_sel:[0,1,0]
	v_pk_fma_f32 v[118:119], v[102:103], v[104:105], v[118:119] op_sel_hi:[1,0,1]
	v_pk_fma_f32 v[120:121], v[102:103], v[104:105], v[120:121] op_sel:[0,1,0]
	v_pk_fma_f32 v[72:73], v[72:73], v[92:93], v[114:115]
	v_pk_fma_f32 v[76:77], v[76:77], v[92:93], v[116:117]
	v_pk_fma_f32 v[74:75], v[74:75], v[94:95], v[118:119]
	v_pk_fma_f32 v[78:79], v[78:79], v[94:95], v[120:121]
	v_pk_mul_f32 v[122:123], v[72:73], v[96:97]
	v_pk_mul_f32 v[124:125], v[76:77], v[96:97]
	v_pk_fma_f32 v[122:123], v[74:75], v[98:99], v[122:123]
	v_pk_fma_f32 v[124:125], v[78:79], v[98:99], v[124:125]
	v_add_f32_e32 v126, v122, v123
	v_add_f32_e32 v127, v124, v125
	ds_write_b64 v187, v[126:127] offset:55296
	s_waitcnt lgkmcnt(1)
	ds_read_b128 v[84:87], v161 offset:15616
	ds_read_b128 v[88:91], v161 offset:23808
	ds_read_b128 v[100:103], v161 offset:32000
	ds_read_b64 v[104:105], v82 offset:48384
	ds_read_b128 v[92:95], v161 offset:7424
	ds_read_b128 v[96:99], v161 offset:40192
	v_pk_mul_f32 v[106:107], v[72:73], v[30:31]
	v_pk_mul_f32 v[108:109], v[76:77], v[30:31]
	v_pk_fma_f32 v[106:107], v[74:75], v[32:33], v[106:107]
	v_pk_fma_f32 v[108:109], v[78:79], v[32:33], v[108:109]
	v_add_f32_e32 v110, v106, v107
	v_add_f32_e32 v112, v108, v109
	s_nop 0
	v_add_f32_dpp v110, v110, v110 quad_perm:[1,0,3,2] row_mask:0xf bank_mask:0xf bound_ctrl:1
	v_add_f32_dpp v112, v112, v112 quad_perm:[1,0,3,2] row_mask:0xf bank_mask:0xf bound_ctrl:1
	s_nop 0
	v_add_f32_dpp v110, v110, v110 quad_perm:[2,3,0,1] row_mask:0xf bank_mask:0xf bound_ctrl:1
	v_add_f32_dpp v112, v112, v112 quad_perm:[2,3,0,1] row_mask:0xf bank_mask:0xf bound_ctrl:1
	s_nop 0
	v_add_f32_dpp v110, v110, v110 row_half_mirror row_mask:0xf bank_mask:0xf bound_ctrl:1
	v_add_f32_dpp v112, v112, v112 row_half_mirror row_mask:0xf bank_mask:0xf bound_ctrl:1
	s_nop 0
	v_add_f32_dpp v110, v110, v110 row_ror:8 row_mask:0xf bank_mask:0xf bound_ctrl:1
	v_add_f32_dpp v112, v112, v112 row_ror:8 row_mask:0xf bank_mask:0xf bound_ctrl:1
	v_pk_mul_f32 v[114:115], v[34:35], v[110:111] op_sel_hi:[1,0]
	v_pk_mul_f32 v[116:117], v[34:35], v[112:113] op_sel_hi:[1,0]
	v_pk_mul_f32 v[118:119], v[36:37], v[110:111] op_sel_hi:[1,0]
	v_pk_mul_f32 v[120:121], v[36:37], v[112:113] op_sel_hi:[1,0]
	v_pk_fma_f32 v[114:115], v[46:47], v[80:81], v[114:115] op_sel_hi:[1,0,1]
	v_pk_fma_f32 v[116:117], v[46:47], v[80:81], v[116:117] op_sel:[0,1,0]
	v_pk_fma_f32 v[118:119], v[48:49], v[80:81], v[118:119] op_sel_hi:[1,0,1]
	v_pk_fma_f32 v[120:121], v[48:49], v[80:81], v[120:121] op_sel:[0,1,0]
	v_pk_fma_f32 v[72:73], v[72:73], v[38:39], v[114:115]
	v_pk_fma_f32 v[76:77], v[76:77], v[38:39], v[116:117]
	v_pk_fma_f32 v[74:75], v[74:75], v[40:41], v[118:119]
	v_pk_fma_f32 v[78:79], v[78:79], v[40:41], v[120:121]
	v_pk_mul_f32 v[122:123], v[72:73], v[42:43]
	v_pk_mul_f32 v[124:125], v[76:77], v[42:43]
	v_pk_fma_f32 v[122:123], v[74:75], v[44:45], v[122:123]
	v_pk_fma_f32 v[124:125], v[78:79], v[44:45], v[124:125]
	v_add_f32_e32 v126, v122, v123
	v_add_f32_e32 v127, v124, v125
	ds_write_b64 v187, v[126:127] offset:57344
	s_waitcnt lgkmcnt(1)
	ds_read_b128 v[30:33], v161 offset:15872
	ds_read_b128 v[34:37], v161 offset:24064
	ds_read_b128 v[46:49], v161 offset:32256
	ds_read_b64 v[80:81], v82 offset:48640
	ds_read_b128 v[38:41], v161 offset:7680
	ds_read_b128 v[42:45], v161 offset:40448
	v_pk_mul_f32 v[106:107], v[72:73], v[84:85]
	v_pk_mul_f32 v[108:109], v[76:77], v[84:85]
	v_pk_fma_f32 v[106:107], v[74:75], v[86:87], v[106:107]
	v_pk_fma_f32 v[108:109], v[78:79], v[86:87], v[108:109]
	v_add_f32_e32 v110, v106, v107
	v_add_f32_e32 v112, v108, v109
	s_nop 0
	v_add_f32_dpp v110, v110, v110 quad_perm:[1,0,3,2] row_mask:0xf bank_mask:0xf bound_ctrl:1
	v_add_f32_dpp v112, v112, v112 quad_perm:[1,0,3,2] row_mask:0xf bank_mask:0xf bound_ctrl:1
	s_nop 0
	v_add_f32_dpp v110, v110, v110 quad_perm:[2,3,0,1] row_mask:0xf bank_mask:0xf bound_ctrl:1
	v_add_f32_dpp v112, v112, v112 quad_perm:[2,3,0,1] row_mask:0xf bank_mask:0xf bound_ctrl:1
	s_nop 0
	v_add_f32_dpp v110, v110, v110 row_half_mirror row_mask:0xf bank_mask:0xf bound_ctrl:1
	v_add_f32_dpp v112, v112, v112 row_half_mirror row_mask:0xf bank_mask:0xf bound_ctrl:1
	s_nop 0
	v_add_f32_dpp v110, v110, v110 row_ror:8 row_mask:0xf bank_mask:0xf bound_ctrl:1
	v_add_f32_dpp v112, v112, v112 row_ror:8 row_mask:0xf bank_mask:0xf bound_ctrl:1
	v_pk_mul_f32 v[114:115], v[88:89], v[110:111] op_sel_hi:[1,0]
	v_pk_mul_f32 v[116:117], v[88:89], v[112:113] op_sel_hi:[1,0]
	v_pk_mul_f32 v[118:119], v[90:91], v[110:111] op_sel_hi:[1,0]
	v_pk_mul_f32 v[120:121], v[90:91], v[112:113] op_sel_hi:[1,0]
	v_pk_fma_f32 v[114:115], v[100:101], v[104:105], v[114:115] op_sel_hi:[1,0,1]
	v_pk_fma_f32 v[116:117], v[100:101], v[104:105], v[116:117] op_sel:[0,1,0]
	v_pk_fma_f32 v[118:119], v[102:103], v[104:105], v[118:119] op_sel_hi:[1,0,1]
	v_pk_fma_f32 v[120:121], v[102:103], v[104:105], v[120:121] op_sel:[0,1,0]
	v_pk_fma_f32 v[72:73], v[72:73], v[92:93], v[114:115]
	v_pk_fma_f32 v[76:77], v[76:77], v[92:93], v[116:117]
	v_pk_fma_f32 v[74:75], v[74:75], v[94:95], v[118:119]
	v_pk_fma_f32 v[78:79], v[78:79], v[94:95], v[120:121]
	v_pk_mul_f32 v[122:123], v[72:73], v[96:97]
	v_pk_mul_f32 v[124:125], v[76:77], v[96:97]
	v_pk_fma_f32 v[122:123], v[74:75], v[98:99], v[122:123]
	v_pk_fma_f32 v[124:125], v[78:79], v[98:99], v[124:125]
	v_add_f32_e32 v126, v122, v123
	v_add_f32_e32 v127, v124, v125
	ds_write_b64 v187, v[126:127] offset:59392
	s_waitcnt lgkmcnt(1)
	ds_read_b128 v[84:87], v161 offset:16128
	ds_read_b128 v[88:91], v161 offset:24320
	ds_read_b128 v[100:103], v161 offset:32512
	ds_read_b64 v[104:105], v82 offset:48896
	ds_read_b128 v[92:95], v161 offset:7936
	ds_read_b128 v[96:99], v161 offset:40704
	v_pk_mul_f32 v[106:107], v[72:73], v[30:31]
	v_pk_mul_f32 v[108:109], v[76:77], v[30:31]
	v_pk_fma_f32 v[106:107], v[74:75], v[32:33], v[106:107]
	v_pk_fma_f32 v[108:109], v[78:79], v[32:33], v[108:109]
	v_add_f32_e32 v110, v106, v107
	v_add_f32_e32 v112, v108, v109
	s_nop 0
	v_add_f32_dpp v110, v110, v110 quad_perm:[1,0,3,2] row_mask:0xf bank_mask:0xf bound_ctrl:1
	v_add_f32_dpp v112, v112, v112 quad_perm:[1,0,3,2] row_mask:0xf bank_mask:0xf bound_ctrl:1
	s_nop 0
	v_add_f32_dpp v110, v110, v110 quad_perm:[2,3,0,1] row_mask:0xf bank_mask:0xf bound_ctrl:1
	v_add_f32_dpp v112, v112, v112 quad_perm:[2,3,0,1] row_mask:0xf bank_mask:0xf bound_ctrl:1
	s_nop 0
	v_add_f32_dpp v110, v110, v110 row_half_mirror row_mask:0xf bank_mask:0xf bound_ctrl:1
	v_add_f32_dpp v112, v112, v112 row_half_mirror row_mask:0xf bank_mask:0xf bound_ctrl:1
	s_nop 0
	v_add_f32_dpp v110, v110, v110 row_ror:8 row_mask:0xf bank_mask:0xf bound_ctrl:1
	v_add_f32_dpp v112, v112, v112 row_ror:8 row_mask:0xf bank_mask:0xf bound_ctrl:1
	v_pk_mul_f32 v[114:115], v[34:35], v[110:111] op_sel_hi:[1,0]
	v_pk_mul_f32 v[116:117], v[34:35], v[112:113] op_sel_hi:[1,0]
	v_pk_mul_f32 v[118:119], v[36:37], v[110:111] op_sel_hi:[1,0]
	v_pk_mul_f32 v[120:121], v[36:37], v[112:113] op_sel_hi:[1,0]
	v_pk_fma_f32 v[114:115], v[46:47], v[80:81], v[114:115] op_sel_hi:[1,0,1]
	v_pk_fma_f32 v[116:117], v[46:47], v[80:81], v[116:117] op_sel:[0,1,0]
	v_pk_fma_f32 v[118:119], v[48:49], v[80:81], v[118:119] op_sel_hi:[1,0,1]
	v_pk_fma_f32 v[120:121], v[48:49], v[80:81], v[120:121] op_sel:[0,1,0]
	v_pk_fma_f32 v[72:73], v[72:73], v[38:39], v[114:115]
	v_pk_fma_f32 v[76:77], v[76:77], v[38:39], v[116:117]
	v_pk_fma_f32 v[74:75], v[74:75], v[40:41], v[118:119]
	v_pk_fma_f32 v[78:79], v[78:79], v[40:41], v[120:121]
	v_pk_mul_f32 v[122:123], v[72:73], v[42:43]
	v_pk_mul_f32 v[124:125], v[76:77], v[42:43]
	v_pk_fma_f32 v[122:123], v[74:75], v[44:45], v[122:123]
	v_pk_fma_f32 v[124:125], v[78:79], v[44:45], v[124:125]
	v_add_f32_e32 v126, v122, v123
	v_add_f32_e32 v127, v124, v125
	ds_write_b64 v187, v[126:127] offset:61440
	s_waitcnt lgkmcnt(1)
	v_pk_mul_f32 v[106:107], v[72:73], v[84:85]
	v_pk_mul_f32 v[108:109], v[76:77], v[84:85]
	v_pk_fma_f32 v[106:107], v[74:75], v[86:87], v[106:107]
	v_pk_fma_f32 v[108:109], v[78:79], v[86:87], v[108:109]
	v_add_f32_e32 v110, v106, v107
	v_add_f32_e32 v112, v108, v109
	s_nop 0
	v_add_f32_dpp v110, v110, v110 quad_perm:[1,0,3,2] row_mask:0xf bank_mask:0xf bound_ctrl:1
	v_add_f32_dpp v112, v112, v112 quad_perm:[1,0,3,2] row_mask:0xf bank_mask:0xf bound_ctrl:1
	s_nop 0
	v_add_f32_dpp v110, v110, v110 quad_perm:[2,3,0,1] row_mask:0xf bank_mask:0xf bound_ctrl:1
	v_add_f32_dpp v112, v112, v112 quad_perm:[2,3,0,1] row_mask:0xf bank_mask:0xf bound_ctrl:1
	s_nop 0
	v_add_f32_dpp v110, v110, v110 row_half_mirror row_mask:0xf bank_mask:0xf bound_ctrl:1
	v_add_f32_dpp v112, v112, v112 row_half_mirror row_mask:0xf bank_mask:0xf bound_ctrl:1
	s_nop 0
	v_add_f32_dpp v110, v110, v110 row_ror:8 row_mask:0xf bank_mask:0xf bound_ctrl:1
	v_add_f32_dpp v112, v112, v112 row_ror:8 row_mask:0xf bank_mask:0xf bound_ctrl:1
	v_pk_mul_f32 v[114:115], v[88:89], v[110:111] op_sel_hi:[1,0]
	v_pk_mul_f32 v[116:117], v[88:89], v[112:113] op_sel_hi:[1,0]
	v_pk_mul_f32 v[118:119], v[90:91], v[110:111] op_sel_hi:[1,0]
	v_pk_mul_f32 v[120:121], v[90:91], v[112:113] op_sel_hi:[1,0]
	v_pk_fma_f32 v[114:115], v[100:101], v[104:105], v[114:115] op_sel_hi:[1,0,1]
	v_pk_fma_f32 v[116:117], v[100:101], v[104:105], v[116:117] op_sel:[0,1,0]
	v_pk_fma_f32 v[118:119], v[102:103], v[104:105], v[118:119] op_sel_hi:[1,0,1]
	v_pk_fma_f32 v[120:121], v[102:103], v[104:105], v[120:121] op_sel:[0,1,0]
	v_pk_fma_f32 v[72:73], v[72:73], v[92:93], v[114:115]
	v_pk_fma_f32 v[76:77], v[76:77], v[92:93], v[116:117]
	v_pk_fma_f32 v[74:75], v[74:75], v[94:95], v[118:119]
	v_pk_fma_f32 v[78:79], v[78:79], v[94:95], v[120:121]
	v_pk_mul_f32 v[122:123], v[72:73], v[96:97]
	v_pk_mul_f32 v[124:125], v[76:77], v[96:97]
	v_pk_fma_f32 v[122:123], v[74:75], v[98:99], v[122:123]
	v_pk_fma_f32 v[124:125], v[78:79], v[98:99], v[124:125]
	v_add_f32_e32 v126, v122, v123
	v_add_f32_e32 v127, v124, v125
	ds_write_b64 v187, v[126:127] offset:63488

.LBB0_3086:
	s_and_saveexec_b64 s[30:31], s[22:23]
	s_cbranch_execz .LBB0_3089
	ds_read_b128 v[30:33], v161 offset:8192
	ds_read_b128 v[34:37], v161 offset:16384
	ds_read_b128 v[46:49], v161 offset:24576
	ds_read_b64 v[80:81], v82 offset:40960
	ds_read_b128 v[38:41], v161
	ds_read_b128 v[42:45], v161 offset:32768
	s_waitcnt lgkmcnt(0)
	ds_read_b128 v[84:87], v161 offset:8448
	ds_read_b128 v[88:91], v161 offset:16640
	ds_read_b128 v[100:103], v161 offset:24832
	ds_read_b64 v[104:105], v82 offset:41216
	ds_read_b128 v[92:95], v161 offset:256
	ds_read_b128 v[96:99], v161 offset:33024
	v_pk_mul_f32 v[106:107], v[72:73], v[30:31]
	v_pk_mul_f32 v[108:109], v[76:77], v[30:31]
	v_pk_fma_f32 v[106:107], v[74:75], v[32:33], v[106:107]
	v_pk_fma_f32 v[108:109], v[78:79], v[32:33], v[108:109]
	v_add_f32_e32 v110, v106, v107
	v_add_f32_e32 v112, v108, v109
	s_nop 0
	v_add_f32_dpp v110, v110, v110 quad_perm:[1,0,3,2] row_mask:0xf bank_mask:0xf bound_ctrl:1
	v_add_f32_dpp v112, v112, v112 quad_perm:[1,0,3,2] row_mask:0xf bank_mask:0xf bound_ctrl:1
	s_nop 0
	v_add_f32_dpp v110, v110, v110 quad_perm:[2,3,0,1] row_mask:0xf bank_mask:0xf bound_ctrl:1
	v_add_f32_dpp v112, v112, v112 quad_perm:[2,3,0,1] row_mask:0xf bank_mask:0xf bound_ctrl:1
	s_nop 0
	v_add_f32_dpp v110, v110, v110 row_half_mirror row_mask:0xf bank_mask:0xf bound_ctrl:1
	v_add_f32_dpp v112, v112, v112 row_half_mirror row_mask:0xf bank_mask:0xf bound_ctrl:1
	s_nop 0
	v_add_f32_dpp v110, v110, v110 row_ror:8 row_mask:0xf bank_mask:0xf bound_ctrl:1
	v_add_f32_dpp v112, v112, v112 row_ror:8 row_mask:0xf bank_mask:0xf bound_ctrl:1
	v_pk_mul_f32 v[114:115], v[34:35], v[110:111] op_sel_hi:[1,0]
	v_pk_mul_f32 v[116:117], v[34:35], v[112:113] op_sel_hi:[1,0]
	v_pk_mul_f32 v[118:119], v[36:37], v[110:111] op_sel_hi:[1,0]
	v_pk_mul_f32 v[120:121], v[36:37], v[112:113] op_sel_hi:[1,0]
	v_pk_fma_f32 v[114:115], v[46:47], v[80:81], v[114:115] op_sel_hi:[1,0,1]
	v_pk_fma_f32 v[116:117], v[46:47], v[80:81], v[116:117] op_sel:[0,1,0]
	v_pk_fma_f32 v[118:119], v[48:49], v[80:81], v[118:119] op_sel_hi:[1,0,1]
	v_pk_fma_f32 v[120:121], v[48:49], v[80:81], v[120:121] op_sel:[0,1,0]
	v_pk_fma_f32 v[72:73], v[72:73], v[38:39], v[114:115]
	v_pk_fma_f32 v[76:77], v[76:77], v[38:39], v[116:117]
	v_pk_fma_f32 v[74:75], v[74:75], v[40:41], v[118:119]
	v_pk_fma_f32 v[78:79], v[78:79], v[40:41], v[120:121]
	v_pk_mul_f32 v[122:123], v[72:73], v[42:43]
	v_pk_mul_f32 v[124:125], v[76:77], v[42:43]
	v_pk_fma_f32 v[122:123], v[74:75], v[44:45], v[122:123]
	v_pk_fma_f32 v[124:125], v[78:79], v[44:45], v[124:125]
	v_add_f32_e32 v126, v122, v123
	v_add_f32_e32 v127, v124, v125
	ds_write_b64 v187, v[126:127]
	s_waitcnt lgkmcnt(1)
	ds_read_b128 v[30:33], v161 offset:8704
	ds_read_b128 v[34:37], v161 offset:16896
	ds_read_b128 v[46:49], v161 offset:25088
	ds_read_b64 v[80:81], v82 offset:41472
	ds_read_b128 v[38:41], v161 offset:512
	ds_read_b128 v[42:45], v161 offset:33280
	v_pk_mul_f32 v[106:107], v[72:73], v[84:85]
	v_pk_mul_f32 v[108:109], v[76:77], v[84:85]
	v_pk_fma_f32 v[106:107], v[74:75], v[86:87], v[106:107]
	v_pk_fma_f32 v[108:109], v[78:79], v[86:87], v[108:109]
	v_add_f32_e32 v110, v106, v107
	v_add_f32_e32 v112, v108, v109
	s_nop 0
	v_add_f32_dpp v110, v110, v110 quad_perm:[1,0,3,2] row_mask:0xf bank_mask:0xf bound_ctrl:1
	v_add_f32_dpp v112, v112, v112 quad_perm:[1,0,3,2] row_mask:0xf bank_mask:0xf bound_ctrl:1
	s_nop 0
	v_add_f32_dpp v110, v110, v110 quad_perm:[2,3,0,1] row_mask:0xf bank_mask:0xf bound_ctrl:1
	v_add_f32_dpp v112, v112, v112 quad_perm:[2,3,0,1] row_mask:0xf bank_mask:0xf bound_ctrl:1
	s_nop 0
	v_add_f32_dpp v110, v110, v110 row_half_mirror row_mask:0xf bank_mask:0xf bound_ctrl:1
	v_add_f32_dpp v112, v112, v112 row_half_mirror row_mask:0xf bank_mask:0xf bound_ctrl:1
	s_nop 0
	v_add_f32_dpp v110, v110, v110 row_ror:8 row_mask:0xf bank_mask:0xf bound_ctrl:1
	v_add_f32_dpp v112, v112, v112 row_ror:8 row_mask:0xf bank_mask:0xf bound_ctrl:1
	v_pk_mul_f32 v[114:115], v[88:89], v[110:111] op_sel_hi:[1,0]
	v_pk_mul_f32 v[116:117], v[88:89], v[112:113] op_sel_hi:[1,0]
	v_pk_mul_f32 v[118:119], v[90:91], v[110:111] op_sel_hi:[1,0]
	v_pk_mul_f32 v[120:121], v[90:91], v[112:113] op_sel_hi:[1,0]
	v_pk_fma_f32 v[114:115], v[100:101], v[104:105], v[114:115] op_sel_hi:[1,0,1]
	v_pk_fma_f32 v[116:117], v[100:101], v[104:105], v[116:117] op_sel:[0,1,0]
	v_pk_fma_f32 v[118:119], v[102:103], v[104:105], v[118:119] op_sel_hi:[1,0,1]
	v_pk_fma_f32 v[120:121], v[102:103], v[104:105], v[120:121] op_sel:[0,1,0]
	v_pk_fma_f32 v[72:73], v[72:73], v[92:93], v[114:115]
	v_pk_fma_f32 v[76:77], v[76:77], v[92:93], v[116:117]
	v_pk_fma_f32 v[74:75], v[74:75], v[94:95], v[118:119]
	v_pk_fma_f32 v[78:79], v[78:79], v[94:95], v[120:121]
	v_pk_mul_f32 v[122:123], v[72:73], v[96:97]
	v_pk_mul_f32 v[124:125], v[76:77], v[96:97]
	v_pk_fma_f32 v[122:123], v[74:75], v[98:99], v[122:123]
	v_pk_fma_f32 v[124:125], v[78:79], v[98:99], v[124:125]
	v_add_f32_e32 v126, v122, v123
	v_add_f32_e32 v127, v124, v125
	ds_write_b64 v187, v[126:127] offset:2048
	s_waitcnt lgkmcnt(1)
	ds_read_b128 v[84:87], v161 offset:8960
	ds_read_b128 v[88:91], v161 offset:17152
	ds_read_b128 v[100:103], v161 offset:25344
	ds_read_b64 v[104:105], v82 offset:41728
	ds_read_b128 v[92:95], v161 offset:768
	ds_read_b128 v[96:99], v161 offset:33536
	v_pk_mul_f32 v[106:107], v[72:73], v[30:31]
	v_pk_mul_f32 v[108:109], v[76:77], v[30:31]
	v_pk_fma_f32 v[106:107], v[74:75], v[32:33], v[106:107]
	v_pk_fma_f32 v[108:109], v[78:79], v[32:33], v[108:109]
	v_add_f32_e32 v110, v106, v107
	v_add_f32_e32 v112, v108, v109
	s_nop 0
	v_add_f32_dpp v110, v110, v110 quad_perm:[1,0,3,2] row_mask:0xf bank_mask:0xf bound_ctrl:1
	v_add_f32_dpp v112, v112, v112 quad_perm:[1,0,3,2] row_mask:0xf bank_mask:0xf bound_ctrl:1
	s_nop 0
	v_add_f32_dpp v110, v110, v110 quad_perm:[2,3,0,1] row_mask:0xf bank_mask:0xf bound_ctrl:1
	v_add_f32_dpp v112, v112, v112 quad_perm:[2,3,0,1] row_mask:0xf bank_mask:0xf bound_ctrl:1
	s_nop 0
	v_add_f32_dpp v110, v110, v110 row_half_mirror row_mask:0xf bank_mask:0xf bound_ctrl:1
	v_add_f32_dpp v112, v112, v112 row_half_mirror row_mask:0xf bank_mask:0xf bound_ctrl:1
	s_nop 0
	v_add_f32_dpp v110, v110, v110 row_ror:8 row_mask:0xf bank_mask:0xf bound_ctrl:1
	v_add_f32_dpp v112, v112, v112 row_ror:8 row_mask:0xf bank_mask:0xf bound_ctrl:1
	v_pk_mul_f32 v[114:115], v[34:35], v[110:111] op_sel_hi:[1,0]
	v_pk_mul_f32 v[116:117], v[34:35], v[112:113] op_sel_hi:[1,0]
	v_pk_mul_f32 v[118:119], v[36:37], v[110:111] op_sel_hi:[1,0]
	v_pk_mul_f32 v[120:121], v[36:37], v[112:113] op_sel_hi:[1,0]
	v_pk_fma_f32 v[114:115], v[46:47], v[80:81], v[114:115] op_sel_hi:[1,0,1]
	v_pk_fma_f32 v[116:117], v[46:47], v[80:81], v[116:117] op_sel:[0,1,0]
	v_pk_fma_f32 v[118:119], v[48:49], v[80:81], v[118:119] op_sel_hi:[1,0,1]
	v_pk_fma_f32 v[120:121], v[48:49], v[80:81], v[120:121] op_sel:[0,1,0]
	v_pk_fma_f32 v[72:73], v[72:73], v[38:39], v[114:115]
	v_pk_fma_f32 v[76:77], v[76:77], v[38:39], v[116:117]
	v_pk_fma_f32 v[74:75], v[74:75], v[40:41], v[118:119]
	v_pk_fma_f32 v[78:79], v[78:79], v[40:41], v[120:121]
	v_pk_mul_f32 v[122:123], v[72:73], v[42:43]
	v_pk_mul_f32 v[124:125], v[76:77], v[42:43]
	v_pk_fma_f32 v[122:123], v[74:75], v[44:45], v[122:123]
	v_pk_fma_f32 v[124:125], v[78:79], v[44:45], v[124:125]
	v_add_f32_e32 v126, v122, v123
	v_add_f32_e32 v127, v124, v125
	ds_write_b64 v187, v[126:127] offset:4096
	s_waitcnt lgkmcnt(1)
	ds_read_b128 v[30:33], v161 offset:9216
	ds_read_b128 v[34:37], v161 offset:17408
	ds_read_b128 v[46:49], v161 offset:25600
	ds_read_b64 v[80:81], v82 offset:41984
	ds_read_b128 v[38:41], v161 offset:1024
	ds_read_b128 v[42:45], v161 offset:33792
	v_pk_mul_f32 v[106:107], v[72:73], v[84:85]
	v_pk_mul_f32 v[108:109], v[76:77], v[84:85]
	v_pk_fma_f32 v[106:107], v[74:75], v[86:87], v[106:107]
	v_pk_fma_f32 v[108:109], v[78:79], v[86:87], v[108:109]
	v_add_f32_e32 v110, v106, v107
	v_add_f32_e32 v112, v108, v109
	s_nop 0
	v_add_f32_dpp v110, v110, v110 quad_perm:[1,0,3,2] row_mask:0xf bank_mask:0xf bound_ctrl:1
	v_add_f32_dpp v112, v112, v112 quad_perm:[1,0,3,2] row_mask:0xf bank_mask:0xf bound_ctrl:1
	s_nop 0
	v_add_f32_dpp v110, v110, v110 quad_perm:[2,3,0,1] row_mask:0xf bank_mask:0xf bound_ctrl:1
	v_add_f32_dpp v112, v112, v112 quad_perm:[2,3,0,1] row_mask:0xf bank_mask:0xf bound_ctrl:1
	s_nop 0
	v_add_f32_dpp v110, v110, v110 row_half_mirror row_mask:0xf bank_mask:0xf bound_ctrl:1
	v_add_f32_dpp v112, v112, v112 row_half_mirror row_mask:0xf bank_mask:0xf bound_ctrl:1
	s_nop 0
	v_add_f32_dpp v110, v110, v110 row_ror:8 row_mask:0xf bank_mask:0xf bound_ctrl:1
	v_add_f32_dpp v112, v112, v112 row_ror:8 row_mask:0xf bank_mask:0xf bound_ctrl:1
	v_pk_mul_f32 v[114:115], v[88:89], v[110:111] op_sel_hi:[1,0]
	v_pk_mul_f32 v[116:117], v[88:89], v[112:113] op_sel_hi:[1,0]
	v_pk_mul_f32 v[118:119], v[90:91], v[110:111] op_sel_hi:[1,0]
	v_pk_mul_f32 v[120:121], v[90:91], v[112:113] op_sel_hi:[1,0]
	v_pk_fma_f32 v[114:115], v[100:101], v[104:105], v[114:115] op_sel_hi:[1,0,1]
	v_pk_fma_f32 v[116:117], v[100:101], v[104:105], v[116:117] op_sel:[0,1,0]
	v_pk_fma_f32 v[118:119], v[102:103], v[104:105], v[118:119] op_sel_hi:[1,0,1]
	v_pk_fma_f32 v[120:121], v[102:103], v[104:105], v[120:121] op_sel:[0,1,0]
	v_pk_fma_f32 v[72:73], v[72:73], v[92:93], v[114:115]
	v_pk_fma_f32 v[76:77], v[76:77], v[92:93], v[116:117]
	v_pk_fma_f32 v[74:75], v[74:75], v[94:95], v[118:119]
	v_pk_fma_f32 v[78:79], v[78:79], v[94:95], v[120:121]
	v_pk_mul_f32 v[122:123], v[72:73], v[96:97]
	v_pk_mul_f32 v[124:125], v[76:77], v[96:97]
	v_pk_fma_f32 v[122:123], v[74:75], v[98:99], v[122:123]
	v_pk_fma_f32 v[124:125], v[78:79], v[98:99], v[124:125]
	v_add_f32_e32 v126, v122, v123
	v_add_f32_e32 v127, v124, v125
	ds_write_b64 v187, v[126:127] offset:6144
	s_waitcnt lgkmcnt(1)
	ds_read_b128 v[84:87], v161 offset:9472
	ds_read_b128 v[88:91], v161 offset:17664
	ds_read_b128 v[100:103], v161 offset:25856
	ds_read_b64 v[104:105], v82 offset:42240
	ds_read_b128 v[92:95], v161 offset:1280
	ds_read_b128 v[96:99], v161 offset:34048
	v_pk_mul_f32 v[106:107], v[72:73], v[30:31]
	v_pk_mul_f32 v[108:109], v[76:77], v[30:31]
	v_pk_fma_f32 v[106:107], v[74:75], v[32:33], v[106:107]
	v_pk_fma_f32 v[108:109], v[78:79], v[32:33], v[108:109]
	v_add_f32_e32 v110, v106, v107
	v_add_f32_e32 v112, v108, v109
	s_nop 0
	v_add_f32_dpp v110, v110, v110 quad_perm:[1,0,3,2] row_mask:0xf bank_mask:0xf bound_ctrl:1
	v_add_f32_dpp v112, v112, v112 quad_perm:[1,0,3,2] row_mask:0xf bank_mask:0xf bound_ctrl:1
	s_nop 0
	v_add_f32_dpp v110, v110, v110 quad_perm:[2,3,0,1] row_mask:0xf bank_mask:0xf bound_ctrl:1
	v_add_f32_dpp v112, v112, v112 quad_perm:[2,3,0,1] row_mask:0xf bank_mask:0xf bound_ctrl:1
	s_nop 0
	v_add_f32_dpp v110, v110, v110 row_half_mirror row_mask:0xf bank_mask:0xf bound_ctrl:1
	v_add_f32_dpp v112, v112, v112 row_half_mirror row_mask:0xf bank_mask:0xf bound_ctrl:1
	s_nop 0
	v_add_f32_dpp v110, v110, v110 row_ror:8 row_mask:0xf bank_mask:0xf bound_ctrl:1
	v_add_f32_dpp v112, v112, v112 row_ror:8 row_mask:0xf bank_mask:0xf bound_ctrl:1
	v_pk_mul_f32 v[114:115], v[34:35], v[110:111] op_sel_hi:[1,0]
	v_pk_mul_f32 v[116:117], v[34:35], v[112:113] op_sel_hi:[1,0]
	v_pk_mul_f32 v[118:119], v[36:37], v[110:111] op_sel_hi:[1,0]
	v_pk_mul_f32 v[120:121], v[36:37], v[112:113] op_sel_hi:[1,0]
	v_pk_fma_f32 v[114:115], v[46:47], v[80:81], v[114:115] op_sel_hi:[1,0,1]
	v_pk_fma_f32 v[116:117], v[46:47], v[80:81], v[116:117] op_sel:[0,1,0]
	v_pk_fma_f32 v[118:119], v[48:49], v[80:81], v[118:119] op_sel_hi:[1,0,1]
	v_pk_fma_f32 v[120:121], v[48:49], v[80:81], v[120:121] op_sel:[0,1,0]
	v_pk_fma_f32 v[72:73], v[72:73], v[38:39], v[114:115]
	v_pk_fma_f32 v[76:77], v[76:77], v[38:39], v[116:117]
	v_pk_fma_f32 v[74:75], v[74:75], v[40:41], v[118:119]
	v_pk_fma_f32 v[78:79], v[78:79], v[40:41], v[120:121]
	v_pk_mul_f32 v[122:123], v[72:73], v[42:43]
	v_pk_mul_f32 v[124:125], v[76:77], v[42:43]
	v_pk_fma_f32 v[122:123], v[74:75], v[44:45], v[122:123]
	v_pk_fma_f32 v[124:125], v[78:79], v[44:45], v[124:125]
	v_add_f32_e32 v126, v122, v123
	v_add_f32_e32 v127, v124, v125
	ds_write_b64 v187, v[126:127] offset:8192
	s_waitcnt lgkmcnt(1)
	ds_read_b128 v[30:33], v161 offset:9728
	ds_read_b128 v[34:37], v161 offset:17920
	ds_read_b128 v[46:49], v161 offset:26112
	ds_read_b64 v[80:81], v82 offset:42496
	ds_read_b128 v[38:41], v161 offset:1536
	ds_read_b128 v[42:45], v161 offset:34304
	v_pk_mul_f32 v[106:107], v[72:73], v[84:85]
	v_pk_mul_f32 v[108:109], v[76:77], v[84:85]
	v_pk_fma_f32 v[106:107], v[74:75], v[86:87], v[106:107]
	v_pk_fma_f32 v[108:109], v[78:79], v[86:87], v[108:109]
	v_add_f32_e32 v110, v106, v107
	v_add_f32_e32 v112, v108, v109
	s_nop 0
	v_add_f32_dpp v110, v110, v110 quad_perm:[1,0,3,2] row_mask:0xf bank_mask:0xf bound_ctrl:1
	v_add_f32_dpp v112, v112, v112 quad_perm:[1,0,3,2] row_mask:0xf bank_mask:0xf bound_ctrl:1
	s_nop 0
	v_add_f32_dpp v110, v110, v110 quad_perm:[2,3,0,1] row_mask:0xf bank_mask:0xf bound_ctrl:1
	v_add_f32_dpp v112, v112, v112 quad_perm:[2,3,0,1] row_mask:0xf bank_mask:0xf bound_ctrl:1
	s_nop 0
	v_add_f32_dpp v110, v110, v110 row_half_mirror row_mask:0xf bank_mask:0xf bound_ctrl:1
	v_add_f32_dpp v112, v112, v112 row_half_mirror row_mask:0xf bank_mask:0xf bound_ctrl:1
	s_nop 0
	v_add_f32_dpp v110, v110, v110 row_ror:8 row_mask:0xf bank_mask:0xf bound_ctrl:1
	v_add_f32_dpp v112, v112, v112 row_ror:8 row_mask:0xf bank_mask:0xf bound_ctrl:1
	v_pk_mul_f32 v[114:115], v[88:89], v[110:111] op_sel_hi:[1,0]
	v_pk_mul_f32 v[116:117], v[88:89], v[112:113] op_sel_hi:[1,0]
	v_pk_mul_f32 v[118:119], v[90:91], v[110:111] op_sel_hi:[1,0]
	v_pk_mul_f32 v[120:121], v[90:91], v[112:113] op_sel_hi:[1,0]
	v_pk_fma_f32 v[114:115], v[100:101], v[104:105], v[114:115] op_sel_hi:[1,0,1]
	v_pk_fma_f32 v[116:117], v[100:101], v[104:105], v[116:117] op_sel:[0,1,0]
	v_pk_fma_f32 v[118:119], v[102:103], v[104:105], v[118:119] op_sel_hi:[1,0,1]
	v_pk_fma_f32 v[120:121], v[102:103], v[104:105], v[120:121] op_sel:[0,1,0]
	v_pk_fma_f32 v[72:73], v[72:73], v[92:93], v[114:115]
	v_pk_fma_f32 v[76:77], v[76:77], v[92:93], v[116:117]
	v_pk_fma_f32 v[74:75], v[74:75], v[94:95], v[118:119]
	v_pk_fma_f32 v[78:79], v[78:79], v[94:95], v[120:121]
	v_pk_mul_f32 v[122:123], v[72:73], v[96:97]
	v_pk_mul_f32 v[124:125], v[76:77], v[96:97]
	v_pk_fma_f32 v[122:123], v[74:75], v[98:99], v[122:123]
	v_pk_fma_f32 v[124:125], v[78:79], v[98:99], v[124:125]
	v_add_f32_e32 v126, v122, v123
	v_add_f32_e32 v127, v124, v125
	ds_write_b64 v187, v[126:127] offset:10240
	s_waitcnt lgkmcnt(1)
	ds_read_b128 v[84:87], v161 offset:9984
	ds_read_b128 v[88:91], v161 offset:18176
	ds_read_b128 v[100:103], v161 offset:26368
	ds_read_b64 v[104:105], v82 offset:42752
	ds_read_b128 v[92:95], v161 offset:1792
	ds_read_b128 v[96:99], v161 offset:34560
	v_pk_mul_f32 v[106:107], v[72:73], v[30:31]
	v_pk_mul_f32 v[108:109], v[76:77], v[30:31]
	v_pk_fma_f32 v[106:107], v[74:75], v[32:33], v[106:107]
	v_pk_fma_f32 v[108:109], v[78:79], v[32:33], v[108:109]
	v_add_f32_e32 v110, v106, v107
	v_add_f32_e32 v112, v108, v109
	s_nop 0
	v_add_f32_dpp v110, v110, v110 quad_perm:[1,0,3,2] row_mask:0xf bank_mask:0xf bound_ctrl:1
	v_add_f32_dpp v112, v112, v112 quad_perm:[1,0,3,2] row_mask:0xf bank_mask:0xf bound_ctrl:1
	s_nop 0
	v_add_f32_dpp v110, v110, v110 quad_perm:[2,3,0,1] row_mask:0xf bank_mask:0xf bound_ctrl:1
	v_add_f32_dpp v112, v112, v112 quad_perm:[2,3,0,1] row_mask:0xf bank_mask:0xf bound_ctrl:1
	s_nop 0
	v_add_f32_dpp v110, v110, v110 row_half_mirror row_mask:0xf bank_mask:0xf bound_ctrl:1
	v_add_f32_dpp v112, v112, v112 row_half_mirror row_mask:0xf bank_mask:0xf bound_ctrl:1
	s_nop 0
	v_add_f32_dpp v110, v110, v110 row_ror:8 row_mask:0xf bank_mask:0xf bound_ctrl:1
	v_add_f32_dpp v112, v112, v112 row_ror:8 row_mask:0xf bank_mask:0xf bound_ctrl:1
	v_pk_mul_f32 v[114:115], v[34:35], v[110:111] op_sel_hi:[1,0]
	v_pk_mul_f32 v[116:117], v[34:35], v[112:113] op_sel_hi:[1,0]
	v_pk_mul_f32 v[118:119], v[36:37], v[110:111] op_sel_hi:[1,0]
	v_pk_mul_f32 v[120:121], v[36:37], v[112:113] op_sel_hi:[1,0]
	v_pk_fma_f32 v[114:115], v[46:47], v[80:81], v[114:115] op_sel_hi:[1,0,1]
	v_pk_fma_f32 v[116:117], v[46:47], v[80:81], v[116:117] op_sel:[0,1,0]
	v_pk_fma_f32 v[118:119], v[48:49], v[80:81], v[118:119] op_sel_hi:[1,0,1]
	v_pk_fma_f32 v[120:121], v[48:49], v[80:81], v[120:121] op_sel:[0,1,0]
	v_pk_fma_f32 v[72:73], v[72:73], v[38:39], v[114:115]
	v_pk_fma_f32 v[76:77], v[76:77], v[38:39], v[116:117]
	v_pk_fma_f32 v[74:75], v[74:75], v[40:41], v[118:119]
	v_pk_fma_f32 v[78:79], v[78:79], v[40:41], v[120:121]
	v_pk_mul_f32 v[122:123], v[72:73], v[42:43]
	v_pk_mul_f32 v[124:125], v[76:77], v[42:43]
	v_pk_fma_f32 v[122:123], v[74:75], v[44:45], v[122:123]
	v_pk_fma_f32 v[124:125], v[78:79], v[44:45], v[124:125]
	v_add_f32_e32 v126, v122, v123
	v_add_f32_e32 v127, v124, v125
	ds_write_b64 v187, v[126:127] offset:12288
	s_waitcnt lgkmcnt(1)
	ds_read_b128 v[30:33], v161 offset:10240
	ds_read_b128 v[34:37], v161 offset:18432
	ds_read_b128 v[46:49], v161 offset:26624
	ds_read_b64 v[80:81], v82 offset:43008
	ds_read_b128 v[38:41], v161 offset:2048
	ds_read_b128 v[42:45], v161 offset:34816
	v_pk_mul_f32 v[106:107], v[72:73], v[84:85]
	v_pk_mul_f32 v[108:109], v[76:77], v[84:85]
	v_pk_fma_f32 v[106:107], v[74:75], v[86:87], v[106:107]
	v_pk_fma_f32 v[108:109], v[78:79], v[86:87], v[108:109]
	v_add_f32_e32 v110, v106, v107
	v_add_f32_e32 v112, v108, v109
	s_nop 0
	v_add_f32_dpp v110, v110, v110 quad_perm:[1,0,3,2] row_mask:0xf bank_mask:0xf bound_ctrl:1
	v_add_f32_dpp v112, v112, v112 quad_perm:[1,0,3,2] row_mask:0xf bank_mask:0xf bound_ctrl:1
	s_nop 0
	v_add_f32_dpp v110, v110, v110 quad_perm:[2,3,0,1] row_mask:0xf bank_mask:0xf bound_ctrl:1
	v_add_f32_dpp v112, v112, v112 quad_perm:[2,3,0,1] row_mask:0xf bank_mask:0xf bound_ctrl:1
	s_nop 0
	v_add_f32_dpp v110, v110, v110 row_half_mirror row_mask:0xf bank_mask:0xf bound_ctrl:1
	v_add_f32_dpp v112, v112, v112 row_half_mirror row_mask:0xf bank_mask:0xf bound_ctrl:1
	s_nop 0
	v_add_f32_dpp v110, v110, v110 row_ror:8 row_mask:0xf bank_mask:0xf bound_ctrl:1
	v_add_f32_dpp v112, v112, v112 row_ror:8 row_mask:0xf bank_mask:0xf bound_ctrl:1
	v_pk_mul_f32 v[114:115], v[88:89], v[110:111] op_sel_hi:[1,0]
	v_pk_mul_f32 v[116:117], v[88:89], v[112:113] op_sel_hi:[1,0]
	v_pk_mul_f32 v[118:119], v[90:91], v[110:111] op_sel_hi:[1,0]
	v_pk_mul_f32 v[120:121], v[90:91], v[112:113] op_sel_hi:[1,0]
	v_pk_fma_f32 v[114:115], v[100:101], v[104:105], v[114:115] op_sel_hi:[1,0,1]
	v_pk_fma_f32 v[116:117], v[100:101], v[104:105], v[116:117] op_sel:[0,1,0]
	v_pk_fma_f32 v[118:119], v[102:103], v[104:105], v[118:119] op_sel_hi:[1,0,1]
	v_pk_fma_f32 v[120:121], v[102:103], v[104:105], v[120:121] op_sel:[0,1,0]
	v_pk_fma_f32 v[72:73], v[72:73], v[92:93], v[114:115]
	v_pk_fma_f32 v[76:77], v[76:77], v[92:93], v[116:117]
	v_pk_fma_f32 v[74:75], v[74:75], v[94:95], v[118:119]
	v_pk_fma_f32 v[78:79], v[78:79], v[94:95], v[120:121]
	v_pk_mul_f32 v[122:123], v[72:73], v[96:97]
	v_pk_mul_f32 v[124:125], v[76:77], v[96:97]
	v_pk_fma_f32 v[122:123], v[74:75], v[98:99], v[122:123]
	v_pk_fma_f32 v[124:125], v[78:79], v[98:99], v[124:125]
	v_add_f32_e32 v126, v122, v123
	v_add_f32_e32 v127, v124, v125
	ds_write_b64 v187, v[126:127] offset:14336
	s_waitcnt lgkmcnt(1)
	ds_read_b128 v[84:87], v161 offset:10496
	ds_read_b128 v[88:91], v161 offset:18688
	ds_read_b128 v[100:103], v161 offset:26880
	ds_read_b64 v[104:105], v82 offset:43264
	ds_read_b128 v[92:95], v161 offset:2304
	ds_read_b128 v[96:99], v161 offset:35072
	v_pk_mul_f32 v[106:107], v[72:73], v[30:31]
	v_pk_mul_f32 v[108:109], v[76:77], v[30:31]
	v_pk_fma_f32 v[106:107], v[74:75], v[32:33], v[106:107]
	v_pk_fma_f32 v[108:109], v[78:79], v[32:33], v[108:109]
	v_add_f32_e32 v110, v106, v107
	v_add_f32_e32 v112, v108, v109
	s_nop 0
	v_add_f32_dpp v110, v110, v110 quad_perm:[1,0,3,2] row_mask:0xf bank_mask:0xf bound_ctrl:1
	v_add_f32_dpp v112, v112, v112 quad_perm:[1,0,3,2] row_mask:0xf bank_mask:0xf bound_ctrl:1
	s_nop 0
	v_add_f32_dpp v110, v110, v110 quad_perm:[2,3,0,1] row_mask:0xf bank_mask:0xf bound_ctrl:1
	v_add_f32_dpp v112, v112, v112 quad_perm:[2,3,0,1] row_mask:0xf bank_mask:0xf bound_ctrl:1
	s_nop 0
	v_add_f32_dpp v110, v110, v110 row_half_mirror row_mask:0xf bank_mask:0xf bound_ctrl:1
	v_add_f32_dpp v112, v112, v112 row_half_mirror row_mask:0xf bank_mask:0xf bound_ctrl:1
	s_nop 0
	v_add_f32_dpp v110, v110, v110 row_ror:8 row_mask:0xf bank_mask:0xf bound_ctrl:1
	v_add_f32_dpp v112, v112, v112 row_ror:8 row_mask:0xf bank_mask:0xf bound_ctrl:1
	v_pk_mul_f32 v[114:115], v[34:35], v[110:111] op_sel_hi:[1,0]
	v_pk_mul_f32 v[116:117], v[34:35], v[112:113] op_sel_hi:[1,0]
	v_pk_mul_f32 v[118:119], v[36:37], v[110:111] op_sel_hi:[1,0]
	v_pk_mul_f32 v[120:121], v[36:37], v[112:113] op_sel_hi:[1,0]
	v_pk_fma_f32 v[114:115], v[46:47], v[80:81], v[114:115] op_sel_hi:[1,0,1]
	v_pk_fma_f32 v[116:117], v[46:47], v[80:81], v[116:117] op_sel:[0,1,0]
	v_pk_fma_f32 v[118:119], v[48:49], v[80:81], v[118:119] op_sel_hi:[1,0,1]
	v_pk_fma_f32 v[120:121], v[48:49], v[80:81], v[120:121] op_sel:[0,1,0]
	v_pk_fma_f32 v[72:73], v[72:73], v[38:39], v[114:115]
	v_pk_fma_f32 v[76:77], v[76:77], v[38:39], v[116:117]
	v_pk_fma_f32 v[74:75], v[74:75], v[40:41], v[118:119]
	v_pk_fma_f32 v[78:79], v[78:79], v[40:41], v[120:121]
	v_pk_mul_f32 v[122:123], v[72:73], v[42:43]
	v_pk_mul_f32 v[124:125], v[76:77], v[42:43]
	v_pk_fma_f32 v[122:123], v[74:75], v[44:45], v[122:123]
	v_pk_fma_f32 v[124:125], v[78:79], v[44:45], v[124:125]
	v_add_f32_e32 v126, v122, v123
	v_add_f32_e32 v127, v124, v125
	ds_write_b64 v187, v[126:127] offset:16384
	s_waitcnt lgkmcnt(1)
	ds_read_b128 v[30:33], v161 offset:10752
	ds_read_b128 v[34:37], v161 offset:18944
	ds_read_b128 v[46:49], v161 offset:27136
	ds_read_b64 v[80:81], v82 offset:43520
	ds_read_b128 v[38:41], v161 offset:2560
	ds_read_b128 v[42:45], v161 offset:35328
	v_pk_mul_f32 v[106:107], v[72:73], v[84:85]
	v_pk_mul_f32 v[108:109], v[76:77], v[84:85]
	v_pk_fma_f32 v[106:107], v[74:75], v[86:87], v[106:107]
	v_pk_fma_f32 v[108:109], v[78:79], v[86:87], v[108:109]
	v_add_f32_e32 v110, v106, v107
	v_add_f32_e32 v112, v108, v109
	s_nop 0
	v_add_f32_dpp v110, v110, v110 quad_perm:[1,0,3,2] row_mask:0xf bank_mask:0xf bound_ctrl:1
	v_add_f32_dpp v112, v112, v112 quad_perm:[1,0,3,2] row_mask:0xf bank_mask:0xf bound_ctrl:1
	s_nop 0
	v_add_f32_dpp v110, v110, v110 quad_perm:[2,3,0,1] row_mask:0xf bank_mask:0xf bound_ctrl:1
	v_add_f32_dpp v112, v112, v112 quad_perm:[2,3,0,1] row_mask:0xf bank_mask:0xf bound_ctrl:1
	s_nop 0
	v_add_f32_dpp v110, v110, v110 row_half_mirror row_mask:0xf bank_mask:0xf bound_ctrl:1
	v_add_f32_dpp v112, v112, v112 row_half_mirror row_mask:0xf bank_mask:0xf bound_ctrl:1
	s_nop 0
	v_add_f32_dpp v110, v110, v110 row_ror:8 row_mask:0xf bank_mask:0xf bound_ctrl:1
	v_add_f32_dpp v112, v112, v112 row_ror:8 row_mask:0xf bank_mask:0xf bound_ctrl:1
	v_pk_mul_f32 v[114:115], v[88:89], v[110:111] op_sel_hi:[1,0]
	v_pk_mul_f32 v[116:117], v[88:89], v[112:113] op_sel_hi:[1,0]
	v_pk_mul_f32 v[118:119], v[90:91], v[110:111] op_sel_hi:[1,0]
	v_pk_mul_f32 v[120:121], v[90:91], v[112:113] op_sel_hi:[1,0]
	v_pk_fma_f32 v[114:115], v[100:101], v[104:105], v[114:115] op_sel_hi:[1,0,1]
	v_pk_fma_f32 v[116:117], v[100:101], v[104:105], v[116:117] op_sel:[0,1,0]
	v_pk_fma_f32 v[118:119], v[102:103], v[104:105], v[118:119] op_sel_hi:[1,0,1]
	v_pk_fma_f32 v[120:121], v[102:103], v[104:105], v[120:121] op_sel:[0,1,0]
	v_pk_fma_f32 v[72:73], v[72:73], v[92:93], v[114:115]
	v_pk_fma_f32 v[76:77], v[76:77], v[92:93], v[116:117]
	v_pk_fma_f32 v[74:75], v[74:75], v[94:95], v[118:119]
	v_pk_fma_f32 v[78:79], v[78:79], v[94:95], v[120:121]
	v_pk_mul_f32 v[122:123], v[72:73], v[96:97]
	v_pk_mul_f32 v[124:125], v[76:77], v[96:97]
	v_pk_fma_f32 v[122:123], v[74:75], v[98:99], v[122:123]
	v_pk_fma_f32 v[124:125], v[78:79], v[98:99], v[124:125]
	v_add_f32_e32 v126, v122, v123
	v_add_f32_e32 v127, v124, v125
	ds_write_b64 v187, v[126:127] offset:18432
	s_waitcnt lgkmcnt(1)
	ds_read_b128 v[84:87], v161 offset:11008
	ds_read_b128 v[88:91], v161 offset:19200
	ds_read_b128 v[100:103], v161 offset:27392
	ds_read_b64 v[104:105], v82 offset:43776
	ds_read_b128 v[92:95], v161 offset:2816
	ds_read_b128 v[96:99], v161 offset:35584
	v_pk_mul_f32 v[106:107], v[72:73], v[30:31]
	v_pk_mul_f32 v[108:109], v[76:77], v[30:31]
	v_pk_fma_f32 v[106:107], v[74:75], v[32:33], v[106:107]
	v_pk_fma_f32 v[108:109], v[78:79], v[32:33], v[108:109]
	v_add_f32_e32 v110, v106, v107
	v_add_f32_e32 v112, v108, v109
	s_nop 0
	v_add_f32_dpp v110, v110, v110 quad_perm:[1,0,3,2] row_mask:0xf bank_mask:0xf bound_ctrl:1
	v_add_f32_dpp v112, v112, v112 quad_perm:[1,0,3,2] row_mask:0xf bank_mask:0xf bound_ctrl:1
	s_nop 0
	v_add_f32_dpp v110, v110, v110 quad_perm:[2,3,0,1] row_mask:0xf bank_mask:0xf bound_ctrl:1
	v_add_f32_dpp v112, v112, v112 quad_perm:[2,3,0,1] row_mask:0xf bank_mask:0xf bound_ctrl:1
	s_nop 0
	v_add_f32_dpp v110, v110, v110 row_half_mirror row_mask:0xf bank_mask:0xf bound_ctrl:1
	v_add_f32_dpp v112, v112, v112 row_half_mirror row_mask:0xf bank_mask:0xf bound_ctrl:1
	s_nop 0
	v_add_f32_dpp v110, v110, v110 row_ror:8 row_mask:0xf bank_mask:0xf bound_ctrl:1
	v_add_f32_dpp v112, v112, v112 row_ror:8 row_mask:0xf bank_mask:0xf bound_ctrl:1
	v_pk_mul_f32 v[114:115], v[34:35], v[110:111] op_sel_hi:[1,0]
	v_pk_mul_f32 v[116:117], v[34:35], v[112:113] op_sel_hi:[1,0]
	v_pk_mul_f32 v[118:119], v[36:37], v[110:111] op_sel_hi:[1,0]
	v_pk_mul_f32 v[120:121], v[36:37], v[112:113] op_sel_hi:[1,0]
	v_pk_fma_f32 v[114:115], v[46:47], v[80:81], v[114:115] op_sel_hi:[1,0,1]
	v_pk_fma_f32 v[116:117], v[46:47], v[80:81], v[116:117] op_sel:[0,1,0]
	v_pk_fma_f32 v[118:119], v[48:49], v[80:81], v[118:119] op_sel_hi:[1,0,1]
	v_pk_fma_f32 v[120:121], v[48:49], v[80:81], v[120:121] op_sel:[0,1,0]
	v_pk_fma_f32 v[72:73], v[72:73], v[38:39], v[114:115]
	v_pk_fma_f32 v[76:77], v[76:77], v[38:39], v[116:117]
	v_pk_fma_f32 v[74:75], v[74:75], v[40:41], v[118:119]
	v_pk_fma_f32 v[78:79], v[78:79], v[40:41], v[120:121]
	v_pk_mul_f32 v[122:123], v[72:73], v[42:43]
	v_pk_mul_f32 v[124:125], v[76:77], v[42:43]
	v_pk_fma_f32 v[122:123], v[74:75], v[44:45], v[122:123]
	v_pk_fma_f32 v[124:125], v[78:79], v[44:45], v[124:125]
	v_add_f32_e32 v126, v122, v123
	v_add_f32_e32 v127, v124, v125
	ds_write_b64 v187, v[126:127] offset:20480
	s_waitcnt lgkmcnt(1)
	ds_read_b128 v[30:33], v161 offset:11264
	ds_read_b128 v[34:37], v161 offset:19456
	ds_read_b128 v[46:49], v161 offset:27648
	ds_read_b64 v[80:81], v82 offset:44032
	ds_read_b128 v[38:41], v161 offset:3072
	ds_read_b128 v[42:45], v161 offset:35840
	v_pk_mul_f32 v[106:107], v[72:73], v[84:85]
	v_pk_mul_f32 v[108:109], v[76:77], v[84:85]
	v_pk_fma_f32 v[106:107], v[74:75], v[86:87], v[106:107]
	v_pk_fma_f32 v[108:109], v[78:79], v[86:87], v[108:109]
	v_add_f32_e32 v110, v106, v107
	v_add_f32_e32 v112, v108, v109
	s_nop 0
	v_add_f32_dpp v110, v110, v110 quad_perm:[1,0,3,2] row_mask:0xf bank_mask:0xf bound_ctrl:1
	v_add_f32_dpp v112, v112, v112 quad_perm:[1,0,3,2] row_mask:0xf bank_mask:0xf bound_ctrl:1
	s_nop 0
	v_add_f32_dpp v110, v110, v110 quad_perm:[2,3,0,1] row_mask:0xf bank_mask:0xf bound_ctrl:1
	v_add_f32_dpp v112, v112, v112 quad_perm:[2,3,0,1] row_mask:0xf bank_mask:0xf bound_ctrl:1
	s_nop 0
	v_add_f32_dpp v110, v110, v110 row_half_mirror row_mask:0xf bank_mask:0xf bound_ctrl:1
	v_add_f32_dpp v112, v112, v112 row_half_mirror row_mask:0xf bank_mask:0xf bound_ctrl:1
	s_nop 0
	v_add_f32_dpp v110, v110, v110 row_ror:8 row_mask:0xf bank_mask:0xf bound_ctrl:1
	v_add_f32_dpp v112, v112, v112 row_ror:8 row_mask:0xf bank_mask:0xf bound_ctrl:1
	v_pk_mul_f32 v[114:115], v[88:89], v[110:111] op_sel_hi:[1,0]
	v_pk_mul_f32 v[116:117], v[88:89], v[112:113] op_sel_hi:[1,0]
	v_pk_mul_f32 v[118:119], v[90:91], v[110:111] op_sel_hi:[1,0]
	v_pk_mul_f32 v[120:121], v[90:91], v[112:113] op_sel_hi:[1,0]
	v_pk_fma_f32 v[114:115], v[100:101], v[104:105], v[114:115] op_sel_hi:[1,0,1]
	v_pk_fma_f32 v[116:117], v[100:101], v[104:105], v[116:117] op_sel:[0,1,0]
	v_pk_fma_f32 v[118:119], v[102:103], v[104:105], v[118:119] op_sel_hi:[1,0,1]
	v_pk_fma_f32 v[120:121], v[102:103], v[104:105], v[120:121] op_sel:[0,1,0]
	v_pk_fma_f32 v[72:73], v[72:73], v[92:93], v[114:115]
	v_pk_fma_f32 v[76:77], v[76:77], v[92:93], v[116:117]
	v_pk_fma_f32 v[74:75], v[74:75], v[94:95], v[118:119]
	v_pk_fma_f32 v[78:79], v[78:79], v[94:95], v[120:121]
	v_pk_mul_f32 v[122:123], v[72:73], v[96:97]
	v_pk_mul_f32 v[124:125], v[76:77], v[96:97]
	v_pk_fma_f32 v[122:123], v[74:75], v[98:99], v[122:123]
	v_pk_fma_f32 v[124:125], v[78:79], v[98:99], v[124:125]
	v_add_f32_e32 v126, v122, v123
	v_add_f32_e32 v127, v124, v125
	ds_write_b64 v187, v[126:127] offset:22528
	s_waitcnt lgkmcnt(1)
	ds_read_b128 v[84:87], v161 offset:11520
	ds_read_b128 v[88:91], v161 offset:19712
	ds_read_b128 v[100:103], v161 offset:27904
	ds_read_b64 v[104:105], v82 offset:44288
	ds_read_b128 v[92:95], v161 offset:3328
	ds_read_b128 v[96:99], v161 offset:36096
	v_pk_mul_f32 v[106:107], v[72:73], v[30:31]
	v_pk_mul_f32 v[108:109], v[76:77], v[30:31]
	v_pk_fma_f32 v[106:107], v[74:75], v[32:33], v[106:107]
	v_pk_fma_f32 v[108:109], v[78:79], v[32:33], v[108:109]
	v_add_f32_e32 v110, v106, v107
	v_add_f32_e32 v112, v108, v109
	s_nop 0
	v_add_f32_dpp v110, v110, v110 quad_perm:[1,0,3,2] row_mask:0xf bank_mask:0xf bound_ctrl:1
	v_add_f32_dpp v112, v112, v112 quad_perm:[1,0,3,2] row_mask:0xf bank_mask:0xf bound_ctrl:1
	s_nop 0
	v_add_f32_dpp v110, v110, v110 quad_perm:[2,3,0,1] row_mask:0xf bank_mask:0xf bound_ctrl:1
	v_add_f32_dpp v112, v112, v112 quad_perm:[2,3,0,1] row_mask:0xf bank_mask:0xf bound_ctrl:1
	s_nop 0
	v_add_f32_dpp v110, v110, v110 row_half_mirror row_mask:0xf bank_mask:0xf bound_ctrl:1
	v_add_f32_dpp v112, v112, v112 row_half_mirror row_mask:0xf bank_mask:0xf bound_ctrl:1
	s_nop 0
	v_add_f32_dpp v110, v110, v110 row_ror:8 row_mask:0xf bank_mask:0xf bound_ctrl:1
	v_add_f32_dpp v112, v112, v112 row_ror:8 row_mask:0xf bank_mask:0xf bound_ctrl:1
	v_pk_mul_f32 v[114:115], v[34:35], v[110:111] op_sel_hi:[1,0]
	v_pk_mul_f32 v[116:117], v[34:35], v[112:113] op_sel_hi:[1,0]
	v_pk_mul_f32 v[118:119], v[36:37], v[110:111] op_sel_hi:[1,0]
	v_pk_mul_f32 v[120:121], v[36:37], v[112:113] op_sel_hi:[1,0]
	v_pk_fma_f32 v[114:115], v[46:47], v[80:81], v[114:115] op_sel_hi:[1,0,1]
	v_pk_fma_f32 v[116:117], v[46:47], v[80:81], v[116:117] op_sel:[0,1,0]
	v_pk_fma_f32 v[118:119], v[48:49], v[80:81], v[118:119] op_sel_hi:[1,0,1]
	v_pk_fma_f32 v[120:121], v[48:49], v[80:81], v[120:121] op_sel:[0,1,0]
	v_pk_fma_f32 v[72:73], v[72:73], v[38:39], v[114:115]
	v_pk_fma_f32 v[76:77], v[76:77], v[38:39], v[116:117]
	v_pk_fma_f32 v[74:75], v[74:75], v[40:41], v[118:119]
	v_pk_fma_f32 v[78:79], v[78:79], v[40:41], v[120:121]
	v_pk_mul_f32 v[122:123], v[72:73], v[42:43]
	v_pk_mul_f32 v[124:125], v[76:77], v[42:43]
	v_pk_fma_f32 v[122:123], v[74:75], v[44:45], v[122:123]
	v_pk_fma_f32 v[124:125], v[78:79], v[44:45], v[124:125]
	v_add_f32_e32 v126, v122, v123
	v_add_f32_e32 v127, v124, v125
	ds_write_b64 v187, v[126:127] offset:24576
	s_waitcnt lgkmcnt(1)
	ds_read_b128 v[30:33], v161 offset:11776
	ds_read_b128 v[34:37], v161 offset:19968
	ds_read_b128 v[46:49], v161 offset:28160
	ds_read_b64 v[80:81], v82 offset:44544
	ds_read_b128 v[38:41], v161 offset:3584
	ds_read_b128 v[42:45], v161 offset:36352
	v_pk_mul_f32 v[106:107], v[72:73], v[84:85]
	v_pk_mul_f32 v[108:109], v[76:77], v[84:85]
	v_pk_fma_f32 v[106:107], v[74:75], v[86:87], v[106:107]
	v_pk_fma_f32 v[108:109], v[78:79], v[86:87], v[108:109]
	v_add_f32_e32 v110, v106, v107
	v_add_f32_e32 v112, v108, v109
	s_nop 0
	v_add_f32_dpp v110, v110, v110 quad_perm:[1,0,3,2] row_mask:0xf bank_mask:0xf bound_ctrl:1
	v_add_f32_dpp v112, v112, v112 quad_perm:[1,0,3,2] row_mask:0xf bank_mask:0xf bound_ctrl:1
	s_nop 0
	v_add_f32_dpp v110, v110, v110 quad_perm:[2,3,0,1] row_mask:0xf bank_mask:0xf bound_ctrl:1
	v_add_f32_dpp v112, v112, v112 quad_perm:[2,3,0,1] row_mask:0xf bank_mask:0xf bound_ctrl:1
	s_nop 0
	v_add_f32_dpp v110, v110, v110 row_half_mirror row_mask:0xf bank_mask:0xf bound_ctrl:1
	v_add_f32_dpp v112, v112, v112 row_half_mirror row_mask:0xf bank_mask:0xf bound_ctrl:1
	s_nop 0
	v_add_f32_dpp v110, v110, v110 row_ror:8 row_mask:0xf bank_mask:0xf bound_ctrl:1
	v_add_f32_dpp v112, v112, v112 row_ror:8 row_mask:0xf bank_mask:0xf bound_ctrl:1
	v_pk_mul_f32 v[114:115], v[88:89], v[110:111] op_sel_hi:[1,0]
	v_pk_mul_f32 v[116:117], v[88:89], v[112:113] op_sel_hi:[1,0]
	v_pk_mul_f32 v[118:119], v[90:91], v[110:111] op_sel_hi:[1,0]
	v_pk_mul_f32 v[120:121], v[90:91], v[112:113] op_sel_hi:[1,0]
	v_pk_fma_f32 v[114:115], v[100:101], v[104:105], v[114:115] op_sel_hi:[1,0,1]
	v_pk_fma_f32 v[116:117], v[100:101], v[104:105], v[116:117] op_sel:[0,1,0]
	v_pk_fma_f32 v[118:119], v[102:103], v[104:105], v[118:119] op_sel_hi:[1,0,1]
	v_pk_fma_f32 v[120:121], v[102:103], v[104:105], v[120:121] op_sel:[0,1,0]
	v_pk_fma_f32 v[72:73], v[72:73], v[92:93], v[114:115]
	v_pk_fma_f32 v[76:77], v[76:77], v[92:93], v[116:117]
	v_pk_fma_f32 v[74:75], v[74:75], v[94:95], v[118:119]
	v_pk_fma_f32 v[78:79], v[78:79], v[94:95], v[120:121]
	v_pk_mul_f32 v[122:123], v[72:73], v[96:97]
	v_pk_mul_f32 v[124:125], v[76:77], v[96:97]
	v_pk_fma_f32 v[122:123], v[74:75], v[98:99], v[122:123]
	v_pk_fma_f32 v[124:125], v[78:79], v[98:99], v[124:125]
	v_add_f32_e32 v126, v122, v123
	v_add_f32_e32 v127, v124, v125
	ds_write_b64 v187, v[126:127] offset:26624
	s_waitcnt lgkmcnt(1)
	ds_read_b128 v[84:87], v161 offset:12032
	ds_read_b128 v[88:91], v161 offset:20224
	ds_read_b128 v[100:103], v161 offset:28416
	ds_read_b64 v[104:105], v82 offset:44800
	ds_read_b128 v[92:95], v161 offset:3840
	ds_read_b128 v[96:99], v161 offset:36608
	v_pk_mul_f32 v[106:107], v[72:73], v[30:31]
	v_pk_mul_f32 v[108:109], v[76:77], v[30:31]
	v_pk_fma_f32 v[106:107], v[74:75], v[32:33], v[106:107]
	v_pk_fma_f32 v[108:109], v[78:79], v[32:33], v[108:109]
	v_add_f32_e32 v110, v106, v107
	v_add_f32_e32 v112, v108, v109
	s_nop 0
	v_add_f32_dpp v110, v110, v110 quad_perm:[1,0,3,2] row_mask:0xf bank_mask:0xf bound_ctrl:1
	v_add_f32_dpp v112, v112, v112 quad_perm:[1,0,3,2] row_mask:0xf bank_mask:0xf bound_ctrl:1
	s_nop 0
	v_add_f32_dpp v110, v110, v110 quad_perm:[2,3,0,1] row_mask:0xf bank_mask:0xf bound_ctrl:1
	v_add_f32_dpp v112, v112, v112 quad_perm:[2,3,0,1] row_mask:0xf bank_mask:0xf bound_ctrl:1
	s_nop 0
	v_add_f32_dpp v110, v110, v110 row_half_mirror row_mask:0xf bank_mask:0xf bound_ctrl:1
	v_add_f32_dpp v112, v112, v112 row_half_mirror row_mask:0xf bank_mask:0xf bound_ctrl:1
	s_nop 0
	v_add_f32_dpp v110, v110, v110 row_ror:8 row_mask:0xf bank_mask:0xf bound_ctrl:1
	v_add_f32_dpp v112, v112, v112 row_ror:8 row_mask:0xf bank_mask:0xf bound_ctrl:1
	v_pk_mul_f32 v[114:115], v[34:35], v[110:111] op_sel_hi:[1,0]
	v_pk_mul_f32 v[116:117], v[34:35], v[112:113] op_sel_hi:[1,0]
	v_pk_mul_f32 v[118:119], v[36:37], v[110:111] op_sel_hi:[1,0]
	v_pk_mul_f32 v[120:121], v[36:37], v[112:113] op_sel_hi:[1,0]
	v_pk_fma_f32 v[114:115], v[46:47], v[80:81], v[114:115] op_sel_hi:[1,0,1]
	v_pk_fma_f32 v[116:117], v[46:47], v[80:81], v[116:117] op_sel:[0,1,0]
	v_pk_fma_f32 v[118:119], v[48:49], v[80:81], v[118:119] op_sel_hi:[1,0,1]
	v_pk_fma_f32 v[120:121], v[48:49], v[80:81], v[120:121] op_sel:[0,1,0]
	v_pk_fma_f32 v[72:73], v[72:73], v[38:39], v[114:115]
	v_pk_fma_f32 v[76:77], v[76:77], v[38:39], v[116:117]
	v_pk_fma_f32 v[74:75], v[74:75], v[40:41], v[118:119]
	v_pk_fma_f32 v[78:79], v[78:79], v[40:41], v[120:121]
	v_pk_mul_f32 v[122:123], v[72:73], v[42:43]
	v_pk_mul_f32 v[124:125], v[76:77], v[42:43]
	v_pk_fma_f32 v[122:123], v[74:75], v[44:45], v[122:123]
	v_pk_fma_f32 v[124:125], v[78:79], v[44:45], v[124:125]
	v_add_f32_e32 v126, v122, v123
	v_add_f32_e32 v127, v124, v125
	ds_write_b64 v187, v[126:127] offset:28672
	s_waitcnt lgkmcnt(1)
	ds_read_b128 v[30:33], v161 offset:12288
	ds_read_b128 v[34:37], v161 offset:20480
	ds_read_b128 v[46:49], v161 offset:28672
	ds_read_b64 v[80:81], v82 offset:45056
	ds_read_b128 v[38:41], v161 offset:4096
	ds_read_b128 v[42:45], v161 offset:36864
	v_pk_mul_f32 v[106:107], v[72:73], v[84:85]
	v_pk_mul_f32 v[108:109], v[76:77], v[84:85]
	v_pk_fma_f32 v[106:107], v[74:75], v[86:87], v[106:107]
	v_pk_fma_f32 v[108:109], v[78:79], v[86:87], v[108:109]
	v_add_f32_e32 v110, v106, v107
	v_add_f32_e32 v112, v108, v109
	s_nop 0
	v_add_f32_dpp v110, v110, v110 quad_perm:[1,0,3,2] row_mask:0xf bank_mask:0xf bound_ctrl:1
	v_add_f32_dpp v112, v112, v112 quad_perm:[1,0,3,2] row_mask:0xf bank_mask:0xf bound_ctrl:1
	s_nop 0
	v_add_f32_dpp v110, v110, v110 quad_perm:[2,3,0,1] row_mask:0xf bank_mask:0xf bound_ctrl:1
	v_add_f32_dpp v112, v112, v112 quad_perm:[2,3,0,1] row_mask:0xf bank_mask:0xf bound_ctrl:1
	s_nop 0
	v_add_f32_dpp v110, v110, v110 row_half_mirror row_mask:0xf bank_mask:0xf bound_ctrl:1
	v_add_f32_dpp v112, v112, v112 row_half_mirror row_mask:0xf bank_mask:0xf bound_ctrl:1
	s_nop 0
	v_add_f32_dpp v110, v110, v110 row_ror:8 row_mask:0xf bank_mask:0xf bound_ctrl:1
	v_add_f32_dpp v112, v112, v112 row_ror:8 row_mask:0xf bank_mask:0xf bound_ctrl:1
	v_pk_mul_f32 v[114:115], v[88:89], v[110:111] op_sel_hi:[1,0]
	v_pk_mul_f32 v[116:117], v[88:89], v[112:113] op_sel_hi:[1,0]
	v_pk_mul_f32 v[118:119], v[90:91], v[110:111] op_sel_hi:[1,0]
	v_pk_mul_f32 v[120:121], v[90:91], v[112:113] op_sel_hi:[1,0]
	v_pk_fma_f32 v[114:115], v[100:101], v[104:105], v[114:115] op_sel_hi:[1,0,1]
	v_pk_fma_f32 v[116:117], v[100:101], v[104:105], v[116:117] op_sel:[0,1,0]
	v_pk_fma_f32 v[118:119], v[102:103], v[104:105], v[118:119] op_sel_hi:[1,0,1]
	v_pk_fma_f32 v[120:121], v[102:103], v[104:105], v[120:121] op_sel:[0,1,0]
	v_pk_fma_f32 v[72:73], v[72:73], v[92:93], v[114:115]
	v_pk_fma_f32 v[76:77], v[76:77], v[92:93], v[116:117]
	v_pk_fma_f32 v[74:75], v[74:75], v[94:95], v[118:119]
	v_pk_fma_f32 v[78:79], v[78:79], v[94:95], v[120:121]
	v_pk_mul_f32 v[122:123], v[72:73], v[96:97]
	v_pk_mul_f32 v[124:125], v[76:77], v[96:97]
	v_pk_fma_f32 v[122:123], v[74:75], v[98:99], v[122:123]
	v_pk_fma_f32 v[124:125], v[78:79], v[98:99], v[124:125]
	v_add_f32_e32 v126, v122, v123
	v_add_f32_e32 v127, v124, v125
	ds_write_b64 v187, v[126:127] offset:30720
	s_waitcnt lgkmcnt(1)
	ds_read_b128 v[84:87], v161 offset:12544
	ds_read_b128 v[88:91], v161 offset:20736
	ds_read_b128 v[100:103], v161 offset:28928
	ds_read_b64 v[104:105], v82 offset:45312
	ds_read_b128 v[92:95], v161 offset:4352
	ds_read_b128 v[96:99], v161 offset:37120
	v_pk_mul_f32 v[106:107], v[72:73], v[30:31]
	v_pk_mul_f32 v[108:109], v[76:77], v[30:31]
	v_pk_fma_f32 v[106:107], v[74:75], v[32:33], v[106:107]
	v_pk_fma_f32 v[108:109], v[78:79], v[32:33], v[108:109]
	v_add_f32_e32 v110, v106, v107
	v_add_f32_e32 v112, v108, v109
	s_nop 0
	v_add_f32_dpp v110, v110, v110 quad_perm:[1,0,3,2] row_mask:0xf bank_mask:0xf bound_ctrl:1
	v_add_f32_dpp v112, v112, v112 quad_perm:[1,0,3,2] row_mask:0xf bank_mask:0xf bound_ctrl:1
	s_nop 0
	v_add_f32_dpp v110, v110, v110 quad_perm:[2,3,0,1] row_mask:0xf bank_mask:0xf bound_ctrl:1
	v_add_f32_dpp v112, v112, v112 quad_perm:[2,3,0,1] row_mask:0xf bank_mask:0xf bound_ctrl:1
	s_nop 0
	v_add_f32_dpp v110, v110, v110 row_half_mirror row_mask:0xf bank_mask:0xf bound_ctrl:1
	v_add_f32_dpp v112, v112, v112 row_half_mirror row_mask:0xf bank_mask:0xf bound_ctrl:1
	s_nop 0
	v_add_f32_dpp v110, v110, v110 row_ror:8 row_mask:0xf bank_mask:0xf bound_ctrl:1
	v_add_f32_dpp v112, v112, v112 row_ror:8 row_mask:0xf bank_mask:0xf bound_ctrl:1
	v_pk_mul_f32 v[114:115], v[34:35], v[110:111] op_sel_hi:[1,0]
	v_pk_mul_f32 v[116:117], v[34:35], v[112:113] op_sel_hi:[1,0]
	v_pk_mul_f32 v[118:119], v[36:37], v[110:111] op_sel_hi:[1,0]
	v_pk_mul_f32 v[120:121], v[36:37], v[112:113] op_sel_hi:[1,0]
	v_pk_fma_f32 v[114:115], v[46:47], v[80:81], v[114:115] op_sel_hi:[1,0,1]
	v_pk_fma_f32 v[116:117], v[46:47], v[80:81], v[116:117] op_sel:[0,1,0]
	v_pk_fma_f32 v[118:119], v[48:49], v[80:81], v[118:119] op_sel_hi:[1,0,1]
	v_pk_fma_f32 v[120:121], v[48:49], v[80:81], v[120:121] op_sel:[0,1,0]
	v_pk_fma_f32 v[72:73], v[72:73], v[38:39], v[114:115]
	v_pk_fma_f32 v[76:77], v[76:77], v[38:39], v[116:117]
	v_pk_fma_f32 v[74:75], v[74:75], v[40:41], v[118:119]
	v_pk_fma_f32 v[78:79], v[78:79], v[40:41], v[120:121]
	v_pk_mul_f32 v[122:123], v[72:73], v[42:43]
	v_pk_mul_f32 v[124:125], v[76:77], v[42:43]
	v_pk_fma_f32 v[122:123], v[74:75], v[44:45], v[122:123]
	v_pk_fma_f32 v[124:125], v[78:79], v[44:45], v[124:125]
	v_add_f32_e32 v126, v122, v123
	v_add_f32_e32 v127, v124, v125
	ds_write_b64 v187, v[126:127] offset:32768
	s_waitcnt lgkmcnt(1)
	ds_read_b128 v[30:33], v161 offset:12800
	ds_read_b128 v[34:37], v161 offset:20992
	ds_read_b128 v[46:49], v161 offset:29184
	ds_read_b64 v[80:81], v82 offset:45568
	ds_read_b128 v[38:41], v161 offset:4608
	ds_read_b128 v[42:45], v161 offset:37376
	v_pk_mul_f32 v[106:107], v[72:73], v[84:85]
	v_pk_mul_f32 v[108:109], v[76:77], v[84:85]
	v_pk_fma_f32 v[106:107], v[74:75], v[86:87], v[106:107]
	v_pk_fma_f32 v[108:109], v[78:79], v[86:87], v[108:109]
	v_add_f32_e32 v110, v106, v107
	v_add_f32_e32 v112, v108, v109
	s_nop 0
	v_add_f32_dpp v110, v110, v110 quad_perm:[1,0,3,2] row_mask:0xf bank_mask:0xf bound_ctrl:1
	v_add_f32_dpp v112, v112, v112 quad_perm:[1,0,3,2] row_mask:0xf bank_mask:0xf bound_ctrl:1
	s_nop 0
	v_add_f32_dpp v110, v110, v110 quad_perm:[2,3,0,1] row_mask:0xf bank_mask:0xf bound_ctrl:1
	v_add_f32_dpp v112, v112, v112 quad_perm:[2,3,0,1] row_mask:0xf bank_mask:0xf bound_ctrl:1
	s_nop 0
	v_add_f32_dpp v110, v110, v110 row_half_mirror row_mask:0xf bank_mask:0xf bound_ctrl:1
	v_add_f32_dpp v112, v112, v112 row_half_mirror row_mask:0xf bank_mask:0xf bound_ctrl:1
	s_nop 0
	v_add_f32_dpp v110, v110, v110 row_ror:8 row_mask:0xf bank_mask:0xf bound_ctrl:1
	v_add_f32_dpp v112, v112, v112 row_ror:8 row_mask:0xf bank_mask:0xf bound_ctrl:1
	v_pk_mul_f32 v[114:115], v[88:89], v[110:111] op_sel_hi:[1,0]
	v_pk_mul_f32 v[116:117], v[88:89], v[112:113] op_sel_hi:[1,0]
	v_pk_mul_f32 v[118:119], v[90:91], v[110:111] op_sel_hi:[1,0]
	v_pk_mul_f32 v[120:121], v[90:91], v[112:113] op_sel_hi:[1,0]
	v_pk_fma_f32 v[114:115], v[100:101], v[104:105], v[114:115] op_sel_hi:[1,0,1]
	v_pk_fma_f32 v[116:117], v[100:101], v[104:105], v[116:117] op_sel:[0,1,0]
	v_pk_fma_f32 v[118:119], v[102:103], v[104:105], v[118:119] op_sel_hi:[1,0,1]
	v_pk_fma_f32 v[120:121], v[102:103], v[104:105], v[120:121] op_sel:[0,1,0]
	v_pk_fma_f32 v[72:73], v[72:73], v[92:93], v[114:115]
	v_pk_fma_f32 v[76:77], v[76:77], v[92:93], v[116:117]
	v_pk_fma_f32 v[74:75], v[74:75], v[94:95], v[118:119]
	v_pk_fma_f32 v[78:79], v[78:79], v[94:95], v[120:121]
	v_pk_mul_f32 v[122:123], v[72:73], v[96:97]
	v_pk_mul_f32 v[124:125], v[76:77], v[96:97]
	v_pk_fma_f32 v[122:123], v[74:75], v[98:99], v[122:123]
	v_pk_fma_f32 v[124:125], v[78:79], v[98:99], v[124:125]
	v_add_f32_e32 v126, v122, v123
	v_add_f32_e32 v127, v124, v125
	ds_write_b64 v187, v[126:127] offset:34816
	s_waitcnt lgkmcnt(1)
	ds_read_b128 v[84:87], v161 offset:13056
	ds_read_b128 v[88:91], v161 offset:21248
	ds_read_b128 v[100:103], v161 offset:29440
	ds_read_b64 v[104:105], v82 offset:45824
	ds_read_b128 v[92:95], v161 offset:4864
	ds_read_b128 v[96:99], v161 offset:37632
	v_pk_mul_f32 v[106:107], v[72:73], v[30:31]
	v_pk_mul_f32 v[108:109], v[76:77], v[30:31]
	v_pk_fma_f32 v[106:107], v[74:75], v[32:33], v[106:107]
	v_pk_fma_f32 v[108:109], v[78:79], v[32:33], v[108:109]
	v_add_f32_e32 v110, v106, v107
	v_add_f32_e32 v112, v108, v109
	s_nop 0
	v_add_f32_dpp v110, v110, v110 quad_perm:[1,0,3,2] row_mask:0xf bank_mask:0xf bound_ctrl:1
	v_add_f32_dpp v112, v112, v112 quad_perm:[1,0,3,2] row_mask:0xf bank_mask:0xf bound_ctrl:1
	s_nop 0
	v_add_f32_dpp v110, v110, v110 quad_perm:[2,3,0,1] row_mask:0xf bank_mask:0xf bound_ctrl:1
	v_add_f32_dpp v112, v112, v112 quad_perm:[2,3,0,1] row_mask:0xf bank_mask:0xf bound_ctrl:1
	s_nop 0
	v_add_f32_dpp v110, v110, v110 row_half_mirror row_mask:0xf bank_mask:0xf bound_ctrl:1
	v_add_f32_dpp v112, v112, v112 row_half_mirror row_mask:0xf bank_mask:0xf bound_ctrl:1
	s_nop 0
	v_add_f32_dpp v110, v110, v110 row_ror:8 row_mask:0xf bank_mask:0xf bound_ctrl:1
	v_add_f32_dpp v112, v112, v112 row_ror:8 row_mask:0xf bank_mask:0xf bound_ctrl:1
	v_pk_mul_f32 v[114:115], v[34:35], v[110:111] op_sel_hi:[1,0]
	v_pk_mul_f32 v[116:117], v[34:35], v[112:113] op_sel_hi:[1,0]
	v_pk_mul_f32 v[118:119], v[36:37], v[110:111] op_sel_hi:[1,0]
	v_pk_mul_f32 v[120:121], v[36:37], v[112:113] op_sel_hi:[1,0]
	v_pk_fma_f32 v[114:115], v[46:47], v[80:81], v[114:115] op_sel_hi:[1,0,1]
	v_pk_fma_f32 v[116:117], v[46:47], v[80:81], v[116:117] op_sel:[0,1,0]
	v_pk_fma_f32 v[118:119], v[48:49], v[80:81], v[118:119] op_sel_hi:[1,0,1]
	v_pk_fma_f32 v[120:121], v[48:49], v[80:81], v[120:121] op_sel:[0,1,0]
	v_pk_fma_f32 v[72:73], v[72:73], v[38:39], v[114:115]
	v_pk_fma_f32 v[76:77], v[76:77], v[38:39], v[116:117]
	v_pk_fma_f32 v[74:75], v[74:75], v[40:41], v[118:119]
	v_pk_fma_f32 v[78:79], v[78:79], v[40:41], v[120:121]
	v_pk_mul_f32 v[122:123], v[72:73], v[42:43]
	v_pk_mul_f32 v[124:125], v[76:77], v[42:43]
	v_pk_fma_f32 v[122:123], v[74:75], v[44:45], v[122:123]
	v_pk_fma_f32 v[124:125], v[78:79], v[44:45], v[124:125]
	v_add_f32_e32 v126, v122, v123
	v_add_f32_e32 v127, v124, v125
	ds_write_b64 v187, v[126:127] offset:36864
	s_waitcnt lgkmcnt(1)
	ds_read_b128 v[30:33], v161 offset:13312
	ds_read_b128 v[34:37], v161 offset:21504
	ds_read_b128 v[46:49], v161 offset:29696
	ds_read_b64 v[80:81], v82 offset:46080
	ds_read_b128 v[38:41], v161 offset:5120
	ds_read_b128 v[42:45], v161 offset:37888
	v_pk_mul_f32 v[106:107], v[72:73], v[84:85]
	v_pk_mul_f32 v[108:109], v[76:77], v[84:85]
	v_pk_fma_f32 v[106:107], v[74:75], v[86:87], v[106:107]
	v_pk_fma_f32 v[108:109], v[78:79], v[86:87], v[108:109]
	v_add_f32_e32 v110, v106, v107
	v_add_f32_e32 v112, v108, v109
	s_nop 0
	v_add_f32_dpp v110, v110, v110 quad_perm:[1,0,3,2] row_mask:0xf bank_mask:0xf bound_ctrl:1
	v_add_f32_dpp v112, v112, v112 quad_perm:[1,0,3,2] row_mask:0xf bank_mask:0xf bound_ctrl:1
	s_nop 0
	v_add_f32_dpp v110, v110, v110 quad_perm:[2,3,0,1] row_mask:0xf bank_mask:0xf bound_ctrl:1
	v_add_f32_dpp v112, v112, v112 quad_perm:[2,3,0,1] row_mask:0xf bank_mask:0xf bound_ctrl:1
	s_nop 0
	v_add_f32_dpp v110, v110, v110 row_half_mirror row_mask:0xf bank_mask:0xf bound_ctrl:1
	v_add_f32_dpp v112, v112, v112 row_half_mirror row_mask:0xf bank_mask:0xf bound_ctrl:1
	s_nop 0
	v_add_f32_dpp v110, v110, v110 row_ror:8 row_mask:0xf bank_mask:0xf bound_ctrl:1
	v_add_f32_dpp v112, v112, v112 row_ror:8 row_mask:0xf bank_mask:0xf bound_ctrl:1
	v_pk_mul_f32 v[114:115], v[88:89], v[110:111] op_sel_hi:[1,0]
	v_pk_mul_f32 v[116:117], v[88:89], v[112:113] op_sel_hi:[1,0]
	v_pk_mul_f32 v[118:119], v[90:91], v[110:111] op_sel_hi:[1,0]
	v_pk_mul_f32 v[120:121], v[90:91], v[112:113] op_sel_hi:[1,0]
	v_pk_fma_f32 v[114:115], v[100:101], v[104:105], v[114:115] op_sel_hi:[1,0,1]
	v_pk_fma_f32 v[116:117], v[100:101], v[104:105], v[116:117] op_sel:[0,1,0]
	v_pk_fma_f32 v[118:119], v[102:103], v[104:105], v[118:119] op_sel_hi:[1,0,1]
	v_pk_fma_f32 v[120:121], v[102:103], v[104:105], v[120:121] op_sel:[0,1,0]
	v_pk_fma_f32 v[72:73], v[72:73], v[92:93], v[114:115]
	v_pk_fma_f32 v[76:77], v[76:77], v[92:93], v[116:117]
	v_pk_fma_f32 v[74:75], v[74:75], v[94:95], v[118:119]
	v_pk_fma_f32 v[78:79], v[78:79], v[94:95], v[120:121]
	v_pk_mul_f32 v[122:123], v[72:73], v[96:97]
	v_pk_mul_f32 v[124:125], v[76:77], v[96:97]
	v_pk_fma_f32 v[122:123], v[74:75], v[98:99], v[122:123]
	v_pk_fma_f32 v[124:125], v[78:79], v[98:99], v[124:125]
	v_add_f32_e32 v126, v122, v123
	v_add_f32_e32 v127, v124, v125
	ds_write_b64 v187, v[126:127] offset:38912
	s_waitcnt lgkmcnt(1)
	ds_read_b128 v[84:87], v161 offset:13568
	ds_read_b128 v[88:91], v161 offset:21760
	ds_read_b128 v[100:103], v161 offset:29952
	ds_read_b64 v[104:105], v82 offset:46336
	ds_read_b128 v[92:95], v161 offset:5376
	ds_read_b128 v[96:99], v161 offset:38144
	v_pk_mul_f32 v[106:107], v[72:73], v[30:31]
	v_pk_mul_f32 v[108:109], v[76:77], v[30:31]
	v_pk_fma_f32 v[106:107], v[74:75], v[32:33], v[106:107]
	v_pk_fma_f32 v[108:109], v[78:79], v[32:33], v[108:109]
	v_add_f32_e32 v110, v106, v107
	v_add_f32_e32 v112, v108, v109
	s_nop 0
	v_add_f32_dpp v110, v110, v110 quad_perm:[1,0,3,2] row_mask:0xf bank_mask:0xf bound_ctrl:1
	v_add_f32_dpp v112, v112, v112 quad_perm:[1,0,3,2] row_mask:0xf bank_mask:0xf bound_ctrl:1
	s_nop 0
	v_add_f32_dpp v110, v110, v110 quad_perm:[2,3,0,1] row_mask:0xf bank_mask:0xf bound_ctrl:1
	v_add_f32_dpp v112, v112, v112 quad_perm:[2,3,0,1] row_mask:0xf bank_mask:0xf bound_ctrl:1
	s_nop 0
	v_add_f32_dpp v110, v110, v110 row_half_mirror row_mask:0xf bank_mask:0xf bound_ctrl:1
	v_add_f32_dpp v112, v112, v112 row_half_mirror row_mask:0xf bank_mask:0xf bound_ctrl:1
	s_nop 0
	v_add_f32_dpp v110, v110, v110 row_ror:8 row_mask:0xf bank_mask:0xf bound_ctrl:1
	v_add_f32_dpp v112, v112, v112 row_ror:8 row_mask:0xf bank_mask:0xf bound_ctrl:1
	v_pk_mul_f32 v[114:115], v[34:35], v[110:111] op_sel_hi:[1,0]
	v_pk_mul_f32 v[116:117], v[34:35], v[112:113] op_sel_hi:[1,0]
	v_pk_mul_f32 v[118:119], v[36:37], v[110:111] op_sel_hi:[1,0]
	v_pk_mul_f32 v[120:121], v[36:37], v[112:113] op_sel_hi:[1,0]
	v_pk_fma_f32 v[114:115], v[46:47], v[80:81], v[114:115] op_sel_hi:[1,0,1]
	v_pk_fma_f32 v[116:117], v[46:47], v[80:81], v[116:117] op_sel:[0,1,0]
	v_pk_fma_f32 v[118:119], v[48:49], v[80:81], v[118:119] op_sel_hi:[1,0,1]
	v_pk_fma_f32 v[120:121], v[48:49], v[80:81], v[120:121] op_sel:[0,1,0]
	v_pk_fma_f32 v[72:73], v[72:73], v[38:39], v[114:115]
	v_pk_fma_f32 v[76:77], v[76:77], v[38:39], v[116:117]
	v_pk_fma_f32 v[74:75], v[74:75], v[40:41], v[118:119]
	v_pk_fma_f32 v[78:79], v[78:79], v[40:41], v[120:121]
	v_pk_mul_f32 v[122:123], v[72:73], v[42:43]
	v_pk_mul_f32 v[124:125], v[76:77], v[42:43]
	v_pk_fma_f32 v[122:123], v[74:75], v[44:45], v[122:123]
	v_pk_fma_f32 v[124:125], v[78:79], v[44:45], v[124:125]
	v_add_f32_e32 v126, v122, v123
	v_add_f32_e32 v127, v124, v125
	ds_write_b64 v187, v[126:127] offset:40960
	s_waitcnt lgkmcnt(1)
	ds_read_b128 v[30:33], v161 offset:13824
	ds_read_b128 v[34:37], v161 offset:22016
	ds_read_b128 v[46:49], v161 offset:30208
	ds_read_b64 v[80:81], v82 offset:46592
	ds_read_b128 v[38:41], v161 offset:5632
	ds_read_b128 v[42:45], v161 offset:38400
	v_pk_mul_f32 v[106:107], v[72:73], v[84:85]
	v_pk_mul_f32 v[108:109], v[76:77], v[84:85]
	v_pk_fma_f32 v[106:107], v[74:75], v[86:87], v[106:107]
	v_pk_fma_f32 v[108:109], v[78:79], v[86:87], v[108:109]
	v_add_f32_e32 v110, v106, v107
	v_add_f32_e32 v112, v108, v109
	s_nop 0
	v_add_f32_dpp v110, v110, v110 quad_perm:[1,0,3,2] row_mask:0xf bank_mask:0xf bound_ctrl:1
	v_add_f32_dpp v112, v112, v112 quad_perm:[1,0,3,2] row_mask:0xf bank_mask:0xf bound_ctrl:1
	s_nop 0
	v_add_f32_dpp v110, v110, v110 quad_perm:[2,3,0,1] row_mask:0xf bank_mask:0xf bound_ctrl:1
	v_add_f32_dpp v112, v112, v112 quad_perm:[2,3,0,1] row_mask:0xf bank_mask:0xf bound_ctrl:1
	s_nop 0
	v_add_f32_dpp v110, v110, v110 row_half_mirror row_mask:0xf bank_mask:0xf bound_ctrl:1
	v_add_f32_dpp v112, v112, v112 row_half_mirror row_mask:0xf bank_mask:0xf bound_ctrl:1
	s_nop 0
	v_add_f32_dpp v110, v110, v110 row_ror:8 row_mask:0xf bank_mask:0xf bound_ctrl:1
	v_add_f32_dpp v112, v112, v112 row_ror:8 row_mask:0xf bank_mask:0xf bound_ctrl:1
	v_pk_mul_f32 v[114:115], v[88:89], v[110:111] op_sel_hi:[1,0]
	v_pk_mul_f32 v[116:117], v[88:89], v[112:113] op_sel_hi:[1,0]
	v_pk_mul_f32 v[118:119], v[90:91], v[110:111] op_sel_hi:[1,0]
	v_pk_mul_f32 v[120:121], v[90:91], v[112:113] op_sel_hi:[1,0]
	v_pk_fma_f32 v[114:115], v[100:101], v[104:105], v[114:115] op_sel_hi:[1,0,1]
	v_pk_fma_f32 v[116:117], v[100:101], v[104:105], v[116:117] op_sel:[0,1,0]
	v_pk_fma_f32 v[118:119], v[102:103], v[104:105], v[118:119] op_sel_hi:[1,0,1]
	v_pk_fma_f32 v[120:121], v[102:103], v[104:105], v[120:121] op_sel:[0,1,0]
	v_pk_fma_f32 v[72:73], v[72:73], v[92:93], v[114:115]
	v_pk_fma_f32 v[76:77], v[76:77], v[92:93], v[116:117]
	v_pk_fma_f32 v[74:75], v[74:75], v[94:95], v[118:119]
	v_pk_fma_f32 v[78:79], v[78:79], v[94:95], v[120:121]
	v_pk_mul_f32 v[122:123], v[72:73], v[96:97]
	v_pk_mul_f32 v[124:125], v[76:77], v[96:97]
	v_pk_fma_f32 v[122:123], v[74:75], v[98:99], v[122:123]
	v_pk_fma_f32 v[124:125], v[78:79], v[98:99], v[124:125]
	v_add_f32_e32 v126, v122, v123
	v_add_f32_e32 v127, v124, v125
	ds_write_b64 v187, v[126:127] offset:43008
	s_waitcnt lgkmcnt(1)
	ds_read_b128 v[84:87], v161 offset:14080
	ds_read_b128 v[88:91], v161 offset:22272
	ds_read_b128 v[100:103], v161 offset:30464
	ds_read_b64 v[104:105], v82 offset:46848
	ds_read_b128 v[92:95], v161 offset:5888
	ds_read_b128 v[96:99], v161 offset:38656
	v_pk_mul_f32 v[106:107], v[72:73], v[30:31]
	v_pk_mul_f32 v[108:109], v[76:77], v[30:31]
	v_pk_fma_f32 v[106:107], v[74:75], v[32:33], v[106:107]
	v_pk_fma_f32 v[108:109], v[78:79], v[32:33], v[108:109]
	v_add_f32_e32 v110, v106, v107
	v_add_f32_e32 v112, v108, v109
	s_nop 0
	v_add_f32_dpp v110, v110, v110 quad_perm:[1,0,3,2] row_mask:0xf bank_mask:0xf bound_ctrl:1
	v_add_f32_dpp v112, v112, v112 quad_perm:[1,0,3,2] row_mask:0xf bank_mask:0xf bound_ctrl:1
	s_nop 0
	v_add_f32_dpp v110, v110, v110 quad_perm:[2,3,0,1] row_mask:0xf bank_mask:0xf bound_ctrl:1
	v_add_f32_dpp v112, v112, v112 quad_perm:[2,3,0,1] row_mask:0xf bank_mask:0xf bound_ctrl:1
	s_nop 0
	v_add_f32_dpp v110, v110, v110 row_half_mirror row_mask:0xf bank_mask:0xf bound_ctrl:1
	v_add_f32_dpp v112, v112, v112 row_half_mirror row_mask:0xf bank_mask:0xf bound_ctrl:1
	s_nop 0
	v_add_f32_dpp v110, v110, v110 row_ror:8 row_mask:0xf bank_mask:0xf bound_ctrl:1
	v_add_f32_dpp v112, v112, v112 row_ror:8 row_mask:0xf bank_mask:0xf bound_ctrl:1
	v_pk_mul_f32 v[114:115], v[34:35], v[110:111] op_sel_hi:[1,0]
	v_pk_mul_f32 v[116:117], v[34:35], v[112:113] op_sel_hi:[1,0]
	v_pk_mul_f32 v[118:119], v[36:37], v[110:111] op_sel_hi:[1,0]
	v_pk_mul_f32 v[120:121], v[36:37], v[112:113] op_sel_hi:[1,0]
	v_pk_fma_f32 v[114:115], v[46:47], v[80:81], v[114:115] op_sel_hi:[1,0,1]
	v_pk_fma_f32 v[116:117], v[46:47], v[80:81], v[116:117] op_sel:[0,1,0]
	v_pk_fma_f32 v[118:119], v[48:49], v[80:81], v[118:119] op_sel_hi:[1,0,1]
	v_pk_fma_f32 v[120:121], v[48:49], v[80:81], v[120:121] op_sel:[0,1,0]
	v_pk_fma_f32 v[72:73], v[72:73], v[38:39], v[114:115]
	v_pk_fma_f32 v[76:77], v[76:77], v[38:39], v[116:117]
	v_pk_fma_f32 v[74:75], v[74:75], v[40:41], v[118:119]
	v_pk_fma_f32 v[78:79], v[78:79], v[40:41], v[120:121]
	v_pk_mul_f32 v[122:123], v[72:73], v[42:43]
	v_pk_mul_f32 v[124:125], v[76:77], v[42:43]
	v_pk_fma_f32 v[122:123], v[74:75], v[44:45], v[122:123]
	v_pk_fma_f32 v[124:125], v[78:79], v[44:45], v[124:125]
	v_add_f32_e32 v126, v122, v123
	v_add_f32_e32 v127, v124, v125
	ds_write_b64 v187, v[126:127] offset:45056
	s_waitcnt lgkmcnt(1)
	ds_read_b128 v[30:33], v161 offset:14336
	ds_read_b128 v[34:37], v161 offset:22528
	ds_read_b128 v[46:49], v161 offset:30720
	ds_read_b64 v[80:81], v82 offset:47104
	ds_read_b128 v[38:41], v161 offset:6144
	ds_read_b128 v[42:45], v161 offset:38912
	v_pk_mul_f32 v[106:107], v[72:73], v[84:85]
	v_pk_mul_f32 v[108:109], v[76:77], v[84:85]
	v_pk_fma_f32 v[106:107], v[74:75], v[86:87], v[106:107]
	v_pk_fma_f32 v[108:109], v[78:79], v[86:87], v[108:109]
	v_add_f32_e32 v110, v106, v107
	v_add_f32_e32 v112, v108, v109
	s_nop 0
	v_add_f32_dpp v110, v110, v110 quad_perm:[1,0,3,2] row_mask:0xf bank_mask:0xf bound_ctrl:1
	v_add_f32_dpp v112, v112, v112 quad_perm:[1,0,3,2] row_mask:0xf bank_mask:0xf bound_ctrl:1
	s_nop 0
	v_add_f32_dpp v110, v110, v110 quad_perm:[2,3,0,1] row_mask:0xf bank_mask:0xf bound_ctrl:1
	v_add_f32_dpp v112, v112, v112 quad_perm:[2,3,0,1] row_mask:0xf bank_mask:0xf bound_ctrl:1
	s_nop 0
	v_add_f32_dpp v110, v110, v110 row_half_mirror row_mask:0xf bank_mask:0xf bound_ctrl:1
	v_add_f32_dpp v112, v112, v112 row_half_mirror row_mask:0xf bank_mask:0xf bound_ctrl:1
	s_nop 0
	v_add_f32_dpp v110, v110, v110 row_ror:8 row_mask:0xf bank_mask:0xf bound_ctrl:1
	v_add_f32_dpp v112, v112, v112 row_ror:8 row_mask:0xf bank_mask:0xf bound_ctrl:1
	v_pk_mul_f32 v[114:115], v[88:89], v[110:111] op_sel_hi:[1,0]
	v_pk_mul_f32 v[116:117], v[88:89], v[112:113] op_sel_hi:[1,0]
	v_pk_mul_f32 v[118:119], v[90:91], v[110:111] op_sel_hi:[1,0]
	v_pk_mul_f32 v[120:121], v[90:91], v[112:113] op_sel_hi:[1,0]
	v_pk_fma_f32 v[114:115], v[100:101], v[104:105], v[114:115] op_sel_hi:[1,0,1]
	v_pk_fma_f32 v[116:117], v[100:101], v[104:105], v[116:117] op_sel:[0,1,0]
	v_pk_fma_f32 v[118:119], v[102:103], v[104:105], v[118:119] op_sel_hi:[1,0,1]
	v_pk_fma_f32 v[120:121], v[102:103], v[104:105], v[120:121] op_sel:[0,1,0]
	v_pk_fma_f32 v[72:73], v[72:73], v[92:93], v[114:115]
	v_pk_fma_f32 v[76:77], v[76:77], v[92:93], v[116:117]
	v_pk_fma_f32 v[74:75], v[74:75], v[94:95], v[118:119]
	v_pk_fma_f32 v[78:79], v[78:79], v[94:95], v[120:121]
	v_pk_mul_f32 v[122:123], v[72:73], v[96:97]
	v_pk_mul_f32 v[124:125], v[76:77], v[96:97]
	v_pk_fma_f32 v[122:123], v[74:75], v[98:99], v[122:123]
	v_pk_fma_f32 v[124:125], v[78:79], v[98:99], v[124:125]
	v_add_f32_e32 v126, v122, v123
	v_add_f32_e32 v127, v124, v125
	ds_write_b64 v187, v[126:127] offset:47104
	s_waitcnt lgkmcnt(1)
	ds_read_b128 v[84:87], v161 offset:14592
	ds_read_b128 v[88:91], v161 offset:22784
	ds_read_b128 v[100:103], v161 offset:30976
	ds_read_b64 v[104:105], v82 offset:47360
	ds_read_b128 v[92:95], v161 offset:6400
	ds_read_b128 v[96:99], v161 offset:39168
	v_pk_mul_f32 v[106:107], v[72:73], v[30:31]
	v_pk_mul_f32 v[108:109], v[76:77], v[30:31]
	v_pk_fma_f32 v[106:107], v[74:75], v[32:33], v[106:107]
	v_pk_fma_f32 v[108:109], v[78:79], v[32:33], v[108:109]
	v_add_f32_e32 v110, v106, v107
	v_add_f32_e32 v112, v108, v109
	s_nop 0
	v_add_f32_dpp v110, v110, v110 quad_perm:[1,0,3,2] row_mask:0xf bank_mask:0xf bound_ctrl:1
	v_add_f32_dpp v112, v112, v112 quad_perm:[1,0,3,2] row_mask:0xf bank_mask:0xf bound_ctrl:1
	s_nop 0
	v_add_f32_dpp v110, v110, v110 quad_perm:[2,3,0,1] row_mask:0xf bank_mask:0xf bound_ctrl:1
	v_add_f32_dpp v112, v112, v112 quad_perm:[2,3,0,1] row_mask:0xf bank_mask:0xf bound_ctrl:1
	s_nop 0
	v_add_f32_dpp v110, v110, v110 row_half_mirror row_mask:0xf bank_mask:0xf bound_ctrl:1
	v_add_f32_dpp v112, v112, v112 row_half_mirror row_mask:0xf bank_mask:0xf bound_ctrl:1
	s_nop 0
	v_add_f32_dpp v110, v110, v110 row_ror:8 row_mask:0xf bank_mask:0xf bound_ctrl:1
	v_add_f32_dpp v112, v112, v112 row_ror:8 row_mask:0xf bank_mask:0xf bound_ctrl:1
	v_pk_mul_f32 v[114:115], v[34:35], v[110:111] op_sel_hi:[1,0]
	v_pk_mul_f32 v[116:117], v[34:35], v[112:113] op_sel_hi:[1,0]
	v_pk_mul_f32 v[118:119], v[36:37], v[110:111] op_sel_hi:[1,0]
	v_pk_mul_f32 v[120:121], v[36:37], v[112:113] op_sel_hi:[1,0]
	v_pk_fma_f32 v[114:115], v[46:47], v[80:81], v[114:115] op_sel_hi:[1,0,1]
	v_pk_fma_f32 v[116:117], v[46:47], v[80:81], v[116:117] op_sel:[0,1,0]
	v_pk_fma_f32 v[118:119], v[48:49], v[80:81], v[118:119] op_sel_hi:[1,0,1]
	v_pk_fma_f32 v[120:121], v[48:49], v[80:81], v[120:121] op_sel:[0,1,0]
	v_pk_fma_f32 v[72:73], v[72:73], v[38:39], v[114:115]
	v_pk_fma_f32 v[76:77], v[76:77], v[38:39], v[116:117]
	v_pk_fma_f32 v[74:75], v[74:75], v[40:41], v[118:119]
	v_pk_fma_f32 v[78:79], v[78:79], v[40:41], v[120:121]
	v_pk_mul_f32 v[122:123], v[72:73], v[42:43]
	v_pk_mul_f32 v[124:125], v[76:77], v[42:43]
	v_pk_fma_f32 v[122:123], v[74:75], v[44:45], v[122:123]
	v_pk_fma_f32 v[124:125], v[78:79], v[44:45], v[124:125]
	v_add_f32_e32 v126, v122, v123
	v_add_f32_e32 v127, v124, v125
	ds_write_b64 v187, v[126:127] offset:49152
	s_waitcnt lgkmcnt(1)
	ds_read_b128 v[30:33], v161 offset:14848
	ds_read_b128 v[34:37], v161 offset:23040
	ds_read_b128 v[46:49], v161 offset:31232
	ds_read_b64 v[80:81], v82 offset:47616
	ds_read_b128 v[38:41], v161 offset:6656
	ds_read_b128 v[42:45], v161 offset:39424
	v_pk_mul_f32 v[106:107], v[72:73], v[84:85]
	v_pk_mul_f32 v[108:109], v[76:77], v[84:85]
	v_pk_fma_f32 v[106:107], v[74:75], v[86:87], v[106:107]
	v_pk_fma_f32 v[108:109], v[78:79], v[86:87], v[108:109]
	v_add_f32_e32 v110, v106, v107
	v_add_f32_e32 v112, v108, v109
	s_nop 0
	v_add_f32_dpp v110, v110, v110 quad_perm:[1,0,3,2] row_mask:0xf bank_mask:0xf bound_ctrl:1
	v_add_f32_dpp v112, v112, v112 quad_perm:[1,0,3,2] row_mask:0xf bank_mask:0xf bound_ctrl:1
	s_nop 0
	v_add_f32_dpp v110, v110, v110 quad_perm:[2,3,0,1] row_mask:0xf bank_mask:0xf bound_ctrl:1
	v_add_f32_dpp v112, v112, v112 quad_perm:[2,3,0,1] row_mask:0xf bank_mask:0xf bound_ctrl:1
	s_nop 0
	v_add_f32_dpp v110, v110, v110 row_half_mirror row_mask:0xf bank_mask:0xf bound_ctrl:1
	v_add_f32_dpp v112, v112, v112 row_half_mirror row_mask:0xf bank_mask:0xf bound_ctrl:1
	s_nop 0
	v_add_f32_dpp v110, v110, v110 row_ror:8 row_mask:0xf bank_mask:0xf bound_ctrl:1
	v_add_f32_dpp v112, v112, v112 row_ror:8 row_mask:0xf bank_mask:0xf bound_ctrl:1
	v_pk_mul_f32 v[114:115], v[88:89], v[110:111] op_sel_hi:[1,0]
	v_pk_mul_f32 v[116:117], v[88:89], v[112:113] op_sel_hi:[1,0]
	v_pk_mul_f32 v[118:119], v[90:91], v[110:111] op_sel_hi:[1,0]
	v_pk_mul_f32 v[120:121], v[90:91], v[112:113] op_sel_hi:[1,0]
	v_pk_fma_f32 v[114:115], v[100:101], v[104:105], v[114:115] op_sel_hi:[1,0,1]
	v_pk_fma_f32 v[116:117], v[100:101], v[104:105], v[116:117] op_sel:[0,1,0]
	v_pk_fma_f32 v[118:119], v[102:103], v[104:105], v[118:119] op_sel_hi:[1,0,1]
	v_pk_fma_f32 v[120:121], v[102:103], v[104:105], v[120:121] op_sel:[0,1,0]
	v_pk_fma_f32 v[72:73], v[72:73], v[92:93], v[114:115]
	v_pk_fma_f32 v[76:77], v[76:77], v[92:93], v[116:117]
	v_pk_fma_f32 v[74:75], v[74:75], v[94:95], v[118:119]
	v_pk_fma_f32 v[78:79], v[78:79], v[94:95], v[120:121]
	v_pk_mul_f32 v[122:123], v[72:73], v[96:97]
	v_pk_mul_f32 v[124:125], v[76:77], v[96:97]
	v_pk_fma_f32 v[122:123], v[74:75], v[98:99], v[122:123]
	v_pk_fma_f32 v[124:125], v[78:79], v[98:99], v[124:125]
	v_add_f32_e32 v126, v122, v123
	v_add_f32_e32 v127, v124, v125
	ds_write_b64 v187, v[126:127] offset:51200
	s_waitcnt lgkmcnt(1)
	ds_read_b128 v[84:87], v161 offset:15104
	ds_read_b128 v[88:91], v161 offset:23296
	ds_read_b128 v[100:103], v161 offset:31488
	ds_read_b64 v[104:105], v82 offset:47872
	ds_read_b128 v[92:95], v161 offset:6912
	ds_read_b128 v[96:99], v161 offset:39680
	v_pk_mul_f32 v[106:107], v[72:73], v[30:31]
	v_pk_mul_f32 v[108:109], v[76:77], v[30:31]
	v_pk_fma_f32 v[106:107], v[74:75], v[32:33], v[106:107]
	v_pk_fma_f32 v[108:109], v[78:79], v[32:33], v[108:109]
	v_add_f32_e32 v110, v106, v107
	v_add_f32_e32 v112, v108, v109
	s_nop 0
	v_add_f32_dpp v110, v110, v110 quad_perm:[1,0,3,2] row_mask:0xf bank_mask:0xf bound_ctrl:1
	v_add_f32_dpp v112, v112, v112 quad_perm:[1,0,3,2] row_mask:0xf bank_mask:0xf bound_ctrl:1
	s_nop 0
	v_add_f32_dpp v110, v110, v110 quad_perm:[2,3,0,1] row_mask:0xf bank_mask:0xf bound_ctrl:1
	v_add_f32_dpp v112, v112, v112 quad_perm:[2,3,0,1] row_mask:0xf bank_mask:0xf bound_ctrl:1
	s_nop 0
	v_add_f32_dpp v110, v110, v110 row_half_mirror row_mask:0xf bank_mask:0xf bound_ctrl:1
	v_add_f32_dpp v112, v112, v112 row_half_mirror row_mask:0xf bank_mask:0xf bound_ctrl:1
	s_nop 0
	v_add_f32_dpp v110, v110, v110 row_ror:8 row_mask:0xf bank_mask:0xf bound_ctrl:1
	v_add_f32_dpp v112, v112, v112 row_ror:8 row_mask:0xf bank_mask:0xf bound_ctrl:1
	v_pk_mul_f32 v[114:115], v[34:35], v[110:111] op_sel_hi:[1,0]
	v_pk_mul_f32 v[116:117], v[34:35], v[112:113] op_sel_hi:[1,0]
	v_pk_mul_f32 v[118:119], v[36:37], v[110:111] op_sel_hi:[1,0]
	v_pk_mul_f32 v[120:121], v[36:37], v[112:113] op_sel_hi:[1,0]
	v_pk_fma_f32 v[114:115], v[46:47], v[80:81], v[114:115] op_sel_hi:[1,0,1]
	v_pk_fma_f32 v[116:117], v[46:47], v[80:81], v[116:117] op_sel:[0,1,0]
	v_pk_fma_f32 v[118:119], v[48:49], v[80:81], v[118:119] op_sel_hi:[1,0,1]
	v_pk_fma_f32 v[120:121], v[48:49], v[80:81], v[120:121] op_sel:[0,1,0]
	v_pk_fma_f32 v[72:73], v[72:73], v[38:39], v[114:115]
	v_pk_fma_f32 v[76:77], v[76:77], v[38:39], v[116:117]
	v_pk_fma_f32 v[74:75], v[74:75], v[40:41], v[118:119]
	v_pk_fma_f32 v[78:79], v[78:79], v[40:41], v[120:121]
	v_pk_mul_f32 v[122:123], v[72:73], v[42:43]
	v_pk_mul_f32 v[124:125], v[76:77], v[42:43]
	v_pk_fma_f32 v[122:123], v[74:75], v[44:45], v[122:123]
	v_pk_fma_f32 v[124:125], v[78:79], v[44:45], v[124:125]
	v_add_f32_e32 v126, v122, v123
	v_add_f32_e32 v127, v124, v125
	ds_write_b64 v187, v[126:127] offset:53248
	s_waitcnt lgkmcnt(1)
	ds_read_b128 v[30:33], v161 offset:15360
	ds_read_b128 v[34:37], v161 offset:23552
	ds_read_b128 v[46:49], v161 offset:31744
	ds_read_b64 v[80:81], v82 offset:48128
	ds_read_b128 v[38:41], v161 offset:7168
	ds_read_b128 v[42:45], v161 offset:39936
	v_pk_mul_f32 v[106:107], v[72:73], v[84:85]
	v_pk_mul_f32 v[108:109], v[76:77], v[84:85]
	v_pk_fma_f32 v[106:107], v[74:75], v[86:87], v[106:107]
	v_pk_fma_f32 v[108:109], v[78:79], v[86:87], v[108:109]
	v_add_f32_e32 v110, v106, v107
	v_add_f32_e32 v112, v108, v109
	s_nop 0
	v_add_f32_dpp v110, v110, v110 quad_perm:[1,0,3,2] row_mask:0xf bank_mask:0xf bound_ctrl:1
	v_add_f32_dpp v112, v112, v112 quad_perm:[1,0,3,2] row_mask:0xf bank_mask:0xf bound_ctrl:1
	s_nop 0
	v_add_f32_dpp v110, v110, v110 quad_perm:[2,3,0,1] row_mask:0xf bank_mask:0xf bound_ctrl:1
	v_add_f32_dpp v112, v112, v112 quad_perm:[2,3,0,1] row_mask:0xf bank_mask:0xf bound_ctrl:1
	s_nop 0
	v_add_f32_dpp v110, v110, v110 row_half_mirror row_mask:0xf bank_mask:0xf bound_ctrl:1
	v_add_f32_dpp v112, v112, v112 row_half_mirror row_mask:0xf bank_mask:0xf bound_ctrl:1
	s_nop 0
	v_add_f32_dpp v110, v110, v110 row_ror:8 row_mask:0xf bank_mask:0xf bound_ctrl:1
	v_add_f32_dpp v112, v112, v112 row_ror:8 row_mask:0xf bank_mask:0xf bound_ctrl:1
	v_pk_mul_f32 v[114:115], v[88:89], v[110:111] op_sel_hi:[1,0]
	v_pk_mul_f32 v[116:117], v[88:89], v[112:113] op_sel_hi:[1,0]
	v_pk_mul_f32 v[118:119], v[90:91], v[110:111] op_sel_hi:[1,0]
	v_pk_mul_f32 v[120:121], v[90:91], v[112:113] op_sel_hi:[1,0]
	v_pk_fma_f32 v[114:115], v[100:101], v[104:105], v[114:115] op_sel_hi:[1,0,1]
	v_pk_fma_f32 v[116:117], v[100:101], v[104:105], v[116:117] op_sel:[0,1,0]
	v_pk_fma_f32 v[118:119], v[102:103], v[104:105], v[118:119] op_sel_hi:[1,0,1]
	v_pk_fma_f32 v[120:121], v[102:103], v[104:105], v[120:121] op_sel:[0,1,0]
	v_pk_fma_f32 v[72:73], v[72:73], v[92:93], v[114:115]
	v_pk_fma_f32 v[76:77], v[76:77], v[92:93], v[116:117]
	v_pk_fma_f32 v[74:75], v[74:75], v[94:95], v[118:119]
	v_pk_fma_f32 v[78:79], v[78:79], v[94:95], v[120:121]
	v_pk_mul_f32 v[122:123], v[72:73], v[96:97]
	v_pk_mul_f32 v[124:125], v[76:77], v[96:97]
	v_pk_fma_f32 v[122:123], v[74:75], v[98:99], v[122:123]
	v_pk_fma_f32 v[124:125], v[78:79], v[98:99], v[124:125]
	v_add_f32_e32 v126, v122, v123
	v_add_f32_e32 v127, v124, v125
	ds_write_b64 v187, v[126:127] offset:55296
	s_waitcnt lgkmcnt(1)
	ds_read_b128 v[84:87], v161 offset:15616
	ds_read_b128 v[88:91], v161 offset:23808
	ds_read_b128 v[100:103], v161 offset:32000
	ds_read_b64 v[104:105], v82 offset:48384
	ds_read_b128 v[92:95], v161 offset:7424
	ds_read_b128 v[96:99], v161 offset:40192
	v_pk_mul_f32 v[106:107], v[72:73], v[30:31]
	v_pk_mul_f32 v[108:109], v[76:77], v[30:31]
	v_pk_fma_f32 v[106:107], v[74:75], v[32:33], v[106:107]
	v_pk_fma_f32 v[108:109], v[78:79], v[32:33], v[108:109]
	v_add_f32_e32 v110, v106, v107
	v_add_f32_e32 v112, v108, v109
	s_nop 0
	v_add_f32_dpp v110, v110, v110 quad_perm:[1,0,3,2] row_mask:0xf bank_mask:0xf bound_ctrl:1
	v_add_f32_dpp v112, v112, v112 quad_perm:[1,0,3,2] row_mask:0xf bank_mask:0xf bound_ctrl:1
	s_nop 0
	v_add_f32_dpp v110, v110, v110 quad_perm:[2,3,0,1] row_mask:0xf bank_mask:0xf bound_ctrl:1
	v_add_f32_dpp v112, v112, v112 quad_perm:[2,3,0,1] row_mask:0xf bank_mask:0xf bound_ctrl:1
	s_nop 0
	v_add_f32_dpp v110, v110, v110 row_half_mirror row_mask:0xf bank_mask:0xf bound_ctrl:1
	v_add_f32_dpp v112, v112, v112 row_half_mirror row_mask:0xf bank_mask:0xf bound_ctrl:1
	s_nop 0
	v_add_f32_dpp v110, v110, v110 row_ror:8 row_mask:0xf bank_mask:0xf bound_ctrl:1
	v_add_f32_dpp v112, v112, v112 row_ror:8 row_mask:0xf bank_mask:0xf bound_ctrl:1
	v_pk_mul_f32 v[114:115], v[34:35], v[110:111] op_sel_hi:[1,0]
	v_pk_mul_f32 v[116:117], v[34:35], v[112:113] op_sel_hi:[1,0]
	v_pk_mul_f32 v[118:119], v[36:37], v[110:111] op_sel_hi:[1,0]
	v_pk_mul_f32 v[120:121], v[36:37], v[112:113] op_sel_hi:[1,0]
	v_pk_fma_f32 v[114:115], v[46:47], v[80:81], v[114:115] op_sel_hi:[1,0,1]
	v_pk_fma_f32 v[116:117], v[46:47], v[80:81], v[116:117] op_sel:[0,1,0]
	v_pk_fma_f32 v[118:119], v[48:49], v[80:81], v[118:119] op_sel_hi:[1,0,1]
	v_pk_fma_f32 v[120:121], v[48:49], v[80:81], v[120:121] op_sel:[0,1,0]
	v_pk_fma_f32 v[72:73], v[72:73], v[38:39], v[114:115]
	v_pk_fma_f32 v[76:77], v[76:77], v[38:39], v[116:117]
	v_pk_fma_f32 v[74:75], v[74:75], v[40:41], v[118:119]
	v_pk_fma_f32 v[78:79], v[78:79], v[40:41], v[120:121]
	v_pk_mul_f32 v[122:123], v[72:73], v[42:43]
	v_pk_mul_f32 v[124:125], v[76:77], v[42:43]
	v_pk_fma_f32 v[122:123], v[74:75], v[44:45], v[122:123]
	v_pk_fma_f32 v[124:125], v[78:79], v[44:45], v[124:125]
	v_add_f32_e32 v126, v122, v123
	v_add_f32_e32 v127, v124, v125
	ds_write_b64 v187, v[126:127] offset:57344
	s_waitcnt lgkmcnt(1)
	ds_read_b128 v[30:33], v161 offset:15872
	ds_read_b128 v[34:37], v161 offset:24064
	ds_read_b128 v[46:49], v161 offset:32256
	ds_read_b64 v[80:81], v82 offset:48640
	ds_read_b128 v[38:41], v161 offset:7680
	ds_read_b128 v[42:45], v161 offset:40448
	v_pk_mul_f32 v[106:107], v[72:73], v[84:85]
	v_pk_mul_f32 v[108:109], v[76:77], v[84:85]
	v_pk_fma_f32 v[106:107], v[74:75], v[86:87], v[106:107]
	v_pk_fma_f32 v[108:109], v[78:79], v[86:87], v[108:109]
	v_add_f32_e32 v110, v106, v107
	v_add_f32_e32 v112, v108, v109
	s_nop 0
	v_add_f32_dpp v110, v110, v110 quad_perm:[1,0,3,2] row_mask:0xf bank_mask:0xf bound_ctrl:1
	v_add_f32_dpp v112, v112, v112 quad_perm:[1,0,3,2] row_mask:0xf bank_mask:0xf bound_ctrl:1
	s_nop 0
	v_add_f32_dpp v110, v110, v110 quad_perm:[2,3,0,1] row_mask:0xf bank_mask:0xf bound_ctrl:1
	v_add_f32_dpp v112, v112, v112 quad_perm:[2,3,0,1] row_mask:0xf bank_mask:0xf bound_ctrl:1
	s_nop 0
	v_add_f32_dpp v110, v110, v110 row_half_mirror row_mask:0xf bank_mask:0xf bound_ctrl:1
	v_add_f32_dpp v112, v112, v112 row_half_mirror row_mask:0xf bank_mask:0xf bound_ctrl:1
	s_nop 0
	v_add_f32_dpp v110, v110, v110 row_ror:8 row_mask:0xf bank_mask:0xf bound_ctrl:1
	v_add_f32_dpp v112, v112, v112 row_ror:8 row_mask:0xf bank_mask:0xf bound_ctrl:1
	v_pk_mul_f32 v[114:115], v[88:89], v[110:111] op_sel_hi:[1,0]
	v_pk_mul_f32 v[116:117], v[88:89], v[112:113] op_sel_hi:[1,0]
	v_pk_mul_f32 v[118:119], v[90:91], v[110:111] op_sel_hi:[1,0]
	v_pk_mul_f32 v[120:121], v[90:91], v[112:113] op_sel_hi:[1,0]
	v_pk_fma_f32 v[114:115], v[100:101], v[104:105], v[114:115] op_sel_hi:[1,0,1]
	v_pk_fma_f32 v[116:117], v[100:101], v[104:105], v[116:117] op_sel:[0,1,0]
	v_pk_fma_f32 v[118:119], v[102:103], v[104:105], v[118:119] op_sel_hi:[1,0,1]
	v_pk_fma_f32 v[120:121], v[102:103], v[104:105], v[120:121] op_sel:[0,1,0]
	v_pk_fma_f32 v[72:73], v[72:73], v[92:93], v[114:115]
	v_pk_fma_f32 v[76:77], v[76:77], v[92:93], v[116:117]
	v_pk_fma_f32 v[74:75], v[74:75], v[94:95], v[118:119]
	v_pk_fma_f32 v[78:79], v[78:79], v[94:95], v[120:121]
	v_pk_mul_f32 v[122:123], v[72:73], v[96:97]
	v_pk_mul_f32 v[124:125], v[76:77], v[96:97]
	v_pk_fma_f32 v[122:123], v[74:75], v[98:99], v[122:123]
	v_pk_fma_f32 v[124:125], v[78:79], v[98:99], v[124:125]
	v_add_f32_e32 v126, v122, v123
	v_add_f32_e32 v127, v124, v125
	ds_write_b64 v187, v[126:127] offset:59392
	s_waitcnt lgkmcnt(1)
	ds_read_b128 v[84:87], v161 offset:16128
	ds_read_b128 v[88:91], v161 offset:24320
	ds_read_b128 v[100:103], v161 offset:32512
	ds_read_b64 v[104:105], v82 offset:48896
	ds_read_b128 v[92:95], v161 offset:7936
	ds_read_b128 v[96:99], v161 offset:40704
	v_pk_mul_f32 v[106:107], v[72:73], v[30:31]
	v_pk_mul_f32 v[108:109], v[76:77], v[30:31]
	v_pk_fma_f32 v[106:107], v[74:75], v[32:33], v[106:107]
	v_pk_fma_f32 v[108:109], v[78:79], v[32:33], v[108:109]
	v_add_f32_e32 v110, v106, v107
	v_add_f32_e32 v112, v108, v109
	s_nop 0
	v_add_f32_dpp v110, v110, v110 quad_perm:[1,0,3,2] row_mask:0xf bank_mask:0xf bound_ctrl:1
	v_add_f32_dpp v112, v112, v112 quad_perm:[1,0,3,2] row_mask:0xf bank_mask:0xf bound_ctrl:1
	s_nop 0
	v_add_f32_dpp v110, v110, v110 quad_perm:[2,3,0,1] row_mask:0xf bank_mask:0xf bound_ctrl:1
	v_add_f32_dpp v112, v112, v112 quad_perm:[2,3,0,1] row_mask:0xf bank_mask:0xf bound_ctrl:1
	s_nop 0
	v_add_f32_dpp v110, v110, v110 row_half_mirror row_mask:0xf bank_mask:0xf bound_ctrl:1
	v_add_f32_dpp v112, v112, v112 row_half_mirror row_mask:0xf bank_mask:0xf bound_ctrl:1
	s_nop 0
	v_add_f32_dpp v110, v110, v110 row_ror:8 row_mask:0xf bank_mask:0xf bound_ctrl:1
	v_add_f32_dpp v112, v112, v112 row_ror:8 row_mask:0xf bank_mask:0xf bound_ctrl:1
	v_pk_mul_f32 v[114:115], v[34:35], v[110:111] op_sel_hi:[1,0]
	v_pk_mul_f32 v[116:117], v[34:35], v[112:113] op_sel_hi:[1,0]
	v_pk_mul_f32 v[118:119], v[36:37], v[110:111] op_sel_hi:[1,0]
	v_pk_mul_f32 v[120:121], v[36:37], v[112:113] op_sel_hi:[1,0]
	v_pk_fma_f32 v[114:115], v[46:47], v[80:81], v[114:115] op_sel_hi:[1,0,1]
	v_pk_fma_f32 v[116:117], v[46:47], v[80:81], v[116:117] op_sel:[0,1,0]
	v_pk_fma_f32 v[118:119], v[48:49], v[80:81], v[118:119] op_sel_hi:[1,0,1]
	v_pk_fma_f32 v[120:121], v[48:49], v[80:81], v[120:121] op_sel:[0,1,0]
	v_pk_fma_f32 v[72:73], v[72:73], v[38:39], v[114:115]
	v_pk_fma_f32 v[76:77], v[76:77], v[38:39], v[116:117]
	v_pk_fma_f32 v[74:75], v[74:75], v[40:41], v[118:119]
	v_pk_fma_f32 v[78:79], v[78:79], v[40:41], v[120:121]
	v_pk_mul_f32 v[122:123], v[72:73], v[42:43]
	v_pk_mul_f32 v[124:125], v[76:77], v[42:43]
	v_pk_fma_f32 v[122:123], v[74:75], v[44:45], v[122:123]
	v_pk_fma_f32 v[124:125], v[78:79], v[44:45], v[124:125]
	v_add_f32_e32 v126, v122, v123
	v_add_f32_e32 v127, v124, v125
	ds_write_b64 v187, v[126:127] offset:61440
	s_waitcnt lgkmcnt(1)
	v_pk_mul_f32 v[106:107], v[72:73], v[84:85]
	v_pk_mul_f32 v[108:109], v[76:77], v[84:85]
	v_pk_fma_f32 v[106:107], v[74:75], v[86:87], v[106:107]
	v_pk_fma_f32 v[108:109], v[78:79], v[86:87], v[108:109]
	v_add_f32_e32 v110, v106, v107
	v_add_f32_e32 v112, v108, v109
	s_nop 0
	v_add_f32_dpp v110, v110, v110 quad_perm:[1,0,3,2] row_mask:0xf bank_mask:0xf bound_ctrl:1
	v_add_f32_dpp v112, v112, v112 quad_perm:[1,0,3,2] row_mask:0xf bank_mask:0xf bound_ctrl:1
	s_nop 0
	v_add_f32_dpp v110, v110, v110 quad_perm:[2,3,0,1] row_mask:0xf bank_mask:0xf bound_ctrl:1
	v_add_f32_dpp v112, v112, v112 quad_perm:[2,3,0,1] row_mask:0xf bank_mask:0xf bound_ctrl:1
	s_nop 0
	v_add_f32_dpp v110, v110, v110 row_half_mirror row_mask:0xf bank_mask:0xf bound_ctrl:1
	v_add_f32_dpp v112, v112, v112 row_half_mirror row_mask:0xf bank_mask:0xf bound_ctrl:1
	s_nop 0
	v_add_f32_dpp v110, v110, v110 row_ror:8 row_mask:0xf bank_mask:0xf bound_ctrl:1
	v_add_f32_dpp v112, v112, v112 row_ror:8 row_mask:0xf bank_mask:0xf bound_ctrl:1
	v_pk_mul_f32 v[114:115], v[88:89], v[110:111] op_sel_hi:[1,0]
	v_pk_mul_f32 v[116:117], v[88:89], v[112:113] op_sel_hi:[1,0]
	v_pk_mul_f32 v[118:119], v[90:91], v[110:111] op_sel_hi:[1,0]
	v_pk_mul_f32 v[120:121], v[90:91], v[112:113] op_sel_hi:[1,0]
	v_pk_fma_f32 v[114:115], v[100:101], v[104:105], v[114:115] op_sel_hi:[1,0,1]
	v_pk_fma_f32 v[116:117], v[100:101], v[104:105], v[116:117] op_sel:[0,1,0]
	v_pk_fma_f32 v[118:119], v[102:103], v[104:105], v[118:119] op_sel_hi:[1,0,1]
	v_pk_fma_f32 v[120:121], v[102:103], v[104:105], v[120:121] op_sel:[0,1,0]
	v_pk_fma_f32 v[72:73], v[72:73], v[92:93], v[114:115]
	v_pk_fma_f32 v[76:77], v[76:77], v[92:93], v[116:117]
	v_pk_fma_f32 v[74:75], v[74:75], v[94:95], v[118:119]
	v_pk_fma_f32 v[78:79], v[78:79], v[94:95], v[120:121]
	v_pk_mul_f32 v[122:123], v[72:73], v[96:97]
	v_pk_mul_f32 v[124:125], v[76:77], v[96:97]
	v_pk_fma_f32 v[122:123], v[74:75], v[98:99], v[122:123]
	v_pk_fma_f32 v[124:125], v[78:79], v[98:99], v[124:125]
	v_add_f32_e32 v126, v122, v123
	v_add_f32_e32 v127, v124, v125
	ds_write_b64 v187, v[126:127] offset:63488
